# GEMM loops: reorder m0 write before the address add so the s_nop before each second LDS-DMA load goes away (88 sites), on top of v9
# speedup vs baseline: 1.0191x; 1.0083x over previous
; #define PG8_STAGE(bufoff, gbase, voff) do { _Pragma("unroll") for (int _i = 0; _i < 2; ++_i) \
;         __builtin_amdgcn_global_load_lds((const unsigned*)((const char*)(gbase) + (voff)[_i]), (PG8_LAS unsigned*)(lds + (bufoff) + ldsw + _i * 8192), 16, 0, 0); } while (0)
; #define PG8_LDA(dst, b, h) do { _Pragma("unroll") for (int m = 0; m < 4; ++m) _Pragma("unroll") for (int k = 0; k < 2; ++k) dst[m][k] = *(const PG8_LAS bf16x8*)(lds + PG8_SA(b, h) + aoff + m * 2048 + k * 1024); } while (0)
; #define PG8_LDB(dst, b, h) do { _Pragma("unroll") for (int n = 0; n < 2; ++n) _Pragma("unroll") for (int k = 0; k < 2; ++k) dst[n][k] = *(const PG8_LAS bf16x8*)(lds + PG8_SB(b, h) + boff + n * 2048 + k * 1024); } while (0)
; #define PG8_MMA(ai, bj, At, Bt) do { __builtin_amdgcn_s_setprio(1); _Pragma("unroll") for (int m = 0; m < 4; ++m) _Pragma("unroll") for (int n = 0; n < 2; ++n) _Pragma("unroll") for (int k = 0; k < 2; ++k) \
;         acc[ai][bj][m][n] = __builtin_amdgcn_mfma_f32_16x16x32_bf16(Bt[n][k], At[m][k], acc[ai][bj][m][n], 0, 0, 0); __builtin_amdgcn_s_setprio(0); } while (0)
; #define PG8_WAIT_L(n) asm volatile("s_waitcnt lgkmcnt(" #n ")" ::: "memory")
; #define PG8_BAR __builtin_amdgcn_s_barrier()
; #define PG8_SCHED __builtin_amdgcn_sched_barrier(0)
; template <class Epi, class Sched>
; __device__ __forceinline__ void gemm_phase(PG8_LAS unsigned char* lds, const Gemm g, const Sched& S, const Epi& E) {
;     ...
;             const bool last = (t == cnk - 2);
;             const char* a1 = cA + (size_t)(t + 1) * kstep;
;             const char* a2 = last ? nA : cA + (size_t)(t + 2) * kstep; const char* b2 = last ? nB : cB + (size_t)(t + 2) * kstep;
;             const char* a3 = a2 + kstep; const char* b3 = b2 + kstep;
;             if (last && has_next) S.a_ready(nxt);
;             if (last) E.prefetch(pre, cur, wr, fr);
;             PG8_LDB(B0, 0, 0); PG8_SCHED; PG8_LDA(At, 0, 0); PG8_STAGE(PG8_SA(1, 1), a1 + hstep, voffA);
;             PG8_WAIT_L(8); PG8_BAR; PG8_WAIT_L(0); PG8_MMA(0, 0, At, B0); PG8_BAR; PG8_SCHED;
;             PG8_LDB(B1, 0, 1); PG8_STAGE(PG8_SB(0, 0), b2, voffB);
;             PG8_BAR; PG8_WAIT_L(0); PG8_MMA(0, 1, At, B1); PG8_BAR;
;             PG8_LDA(At, 0, 1); PG8_STAGE(PG8_SA(0, 0), a2, voffA);
;             PG8_BAR; PG8_WAIT_L(0); PG8_MMA(1, 0, At, B0); PG8_BAR; PG8_SCHED;
.LBB0_194:
	v_add_u32_e32 v14, s6, v155
	ds_read_b128 v[24:27], v14
	ds_read_b128 v[32:35], v14 offset:1024
	ds_read_b128 v[36:39], v14 offset:2048
	ds_read_b128 v[144:147], v14 offset:3072
	s_add_u32 s22, s0, 0xfffc0080
	s_addc_u32 s23, s1, -1
	s_and_b64 s[20:21], s[20:21], exec
	s_cselect_b32 s23, s11, s23
	s_cselect_b32 s22, s15, s22
	s_cselect_b32 s21, s13, s2
	s_cselect_b32 s20, vcc_lo, vcc_hi
	v_lshl_add_u64 v[14:15], s[0:1], 0, v[176:177]
	s_add_i32 m0, s25, 0xc000
	ds_read_b128 v[148:151], v163
	ds_read_b128 v[192:195], v163 offset:1024
	ds_read_b128 v[196:199], v163 offset:2048
	ds_read_b128 v[200:203], v163 offset:3072
	ds_read_b128 v[210:213], v163 offset:4096
	ds_read_b128 v[214:217], v163 offset:5120
	ds_read_b128 v[218:221], v163 offset:6144
	ds_read_b128 v[222:225], v163 offset:7168
	global_load_lds_dwordx4 v[14:15], off
	s_add_i32 m0, s25, 0xe000
	v_lshl_add_u64 v[14:15], s[0:1], 0, v[178:179]
	global_load_lds_dwordx4 v[14:15], off
	s_waitcnt lgkmcnt(8)
	s_barrier
	s_waitcnt lgkmcnt(0)
	s_setprio 1
	v_mfma_f32_16x16x32_bf16 v[140:143], v[24:27], v[148:151], v[140:143]
	v_mfma_f32_16x16x32_bf16 v[136:139], v[36:39], v[148:151], v[136:139]
	v_mfma_f32_16x16x32_bf16 v[124:127], v[24:27], v[196:199], v[124:127]
	v_mfma_f32_16x16x32_bf16 v[120:123], v[36:39], v[196:199], v[120:123]
	v_mfma_f32_16x16x32_bf16 v[108:111], v[24:27], v[210:213], v[108:111]
	v_mfma_f32_16x16x32_bf16 v[104:107], v[36:39], v[210:213], v[104:107]
	v_mfma_f32_16x16x32_bf16 v[92:95], v[24:27], v[218:221], v[92:95]
	v_mfma_f32_16x16x32_bf16 v[88:91], v[36:39], v[218:221], v[88:91]
	v_mfma_f32_16x16x32_bf16 v[140:143], v[32:35], v[192:195], v[140:143]
	v_mfma_f32_16x16x32_bf16 v[136:139], v[144:147], v[192:195], v[136:139]
	v_mfma_f32_16x16x32_bf16 v[124:127], v[32:35], v[200:203], v[124:127]
	v_mfma_f32_16x16x32_bf16 v[120:123], v[144:147], v[200:203], v[120:123]
	v_mfma_f32_16x16x32_bf16 v[108:111], v[32:35], v[214:217], v[108:111]
	v_mfma_f32_16x16x32_bf16 v[104:107], v[144:147], v[214:217], v[104:107]
	v_mfma_f32_16x16x32_bf16 v[92:95], v[32:35], v[222:225], v[92:95]
	v_mfma_f32_16x16x32_bf16 v[88:91], v[144:147], v[222:225], v[88:91]
	s_setprio 0
	s_barrier
	s_add_i32 s96, s6, s9
	v_add_u32_e32 v14, s8, v155
	v_lshl_add_u64 v[204:205], s[20:21], 0, v[166:167]
	s_mov_b32 m0, s96
	ds_read_b128 v[226:229], v14
	ds_read_b128 v[230:233], v14 offset:1024
	ds_read_b128 v[234:237], v14 offset:2048
	ds_read_b128 v[238:241], v14 offset:3072
	global_load_lds_dwordx4 v[204:205], off
	s_add_i32 m0, s96, 0x2000
	v_lshl_add_u64 v[242:243], s[20:21], 0, v[170:171]
	global_load_lds_dwordx4 v[242:243], off
	s_barrier
	s_waitcnt lgkmcnt(0)
	s_setprio 1
	v_mfma_f32_16x16x32_bf16 v[132:135], v[226:229], v[148:151], v[132:135]
	v_mfma_f32_16x16x32_bf16 v[128:131], v[234:237], v[148:151], v[128:131]
	v_mfma_f32_16x16x32_bf16 v[116:119], v[226:229], v[196:199], v[116:119]
	v_mfma_f32_16x16x32_bf16 v[112:115], v[234:237], v[196:199], v[112:115]
	v_mfma_f32_16x16x32_bf16 v[100:103], v[226:229], v[210:213], v[100:103]
	v_mfma_f32_16x16x32_bf16 v[96:99], v[234:237], v[210:213], v[96:99]
	v_mfma_f32_16x16x32_bf16 v[84:87], v[226:229], v[218:221], v[84:87]
	v_mfma_f32_16x16x32_bf16 v[80:83], v[234:237], v[218:221], v[80:83]
	v_mfma_f32_16x16x32_bf16 v[132:135], v[230:233], v[192:195], v[132:135]
	v_mfma_f32_16x16x32_bf16 v[128:131], v[238:241], v[192:195], v[128:131]
	v_mfma_f32_16x16x32_bf16 v[116:119], v[230:233], v[200:203], v[116:119]
	v_mfma_f32_16x16x32_bf16 v[112:115], v[238:241], v[200:203], v[112:115]
	v_mfma_f32_16x16x32_bf16 v[100:103], v[230:233], v[214:217], v[100:103]
	v_mfma_f32_16x16x32_bf16 v[96:99], v[238:241], v[214:217], v[96:99]
	v_mfma_f32_16x16x32_bf16 v[84:87], v[230:233], v[222:225], v[84:87]
	v_mfma_f32_16x16x32_bf16 v[80:83], v[238:241], v[222:225], v[80:83]
	s_setprio 0
	s_mov_b32 m0, s25
	v_lshl_add_u64 v[244:245], s[22:23], 0, v[164:165]
	s_barrier
	ds_read_b128 v[148:151], v163 offset:16384
	ds_read_b128 v[192:195], v163 offset:17408
	ds_read_b128 v[196:199], v163 offset:18432
	ds_read_b128 v[200:203], v163 offset:19456
	ds_read_b128 v[210:213], v163 offset:20480
	ds_read_b128 v[214:217], v163 offset:21504
	ds_read_b128 v[218:221], v163 offset:22528
	ds_read_b128 v[222:225], v163 offset:23552
	global_load_lds_dwordx4 v[244:245], off
	s_mov_b32 m0, s26
	v_lshl_add_u64 v[246:247], s[22:23], 0, v[168:169]
	global_load_lds_dwordx4 v[246:247], off
	s_barrier
	s_waitcnt lgkmcnt(0)
	s_setprio 1
	v_mfma_f32_16x16x32_bf16 v[76:79], v[24:27], v[148:151], v[76:79]
	v_mfma_f32_16x16x32_bf16 v[72:75], v[36:39], v[148:151], v[72:75]
	v_mfma_f32_16x16x32_bf16 v[60:63], v[24:27], v[196:199], v[60:63]
	v_mfma_f32_16x16x32_bf16 v[56:59], v[36:39], v[196:199], v[56:59]
	v_mfma_f32_16x16x32_bf16 v[44:47], v[24:27], v[210:213], v[44:47]
	v_mfma_f32_16x16x32_bf16 v[40:43], v[36:39], v[210:213], v[40:43]
	v_mfma_f32_16x16x32_bf16 v[14:17], v[24:27], v[218:221], v[16:19]
	v_mfma_f32_16x16x32_bf16 v[8:11], v[36:39], v[218:221], v[8:11]
	v_mfma_f32_16x16x32_bf16 v[76:79], v[32:35], v[192:195], v[76:79]
	v_mfma_f32_16x16x32_bf16 v[72:75], v[144:147], v[192:195], v[72:75]
	v_mfma_f32_16x16x32_bf16 v[60:63], v[32:35], v[200:203], v[60:63]
	v_mfma_f32_16x16x32_bf16 v[56:59], v[144:147], v[200:203], v[56:59]
	v_mfma_f32_16x16x32_bf16 v[44:47], v[32:35], v[214:217], v[44:47]
	v_mfma_f32_16x16x32_bf16 v[40:43], v[144:147], v[214:217], v[40:43]
	v_mfma_f32_16x16x32_bf16 v[14:17], v[32:35], v[222:225], v[14:17]
	v_mfma_f32_16x16x32_bf16 v[8:11], v[144:147], v[222:225], v[8:11]
	s_setprio 0
	s_barrier
; #define PG8_STAGE(bufoff, gbase, voff) do { _Pragma("unroll") for (int _i = 0; _i < 2; ++_i) \
;         __builtin_amdgcn_global_load_lds((const unsigned*)((const char*)(gbase) + (voff)[_i]), (PG8_LAS unsigned*)(lds + (bufoff) + ldsw + _i * 8192), 16, 0, 0); } while (0)
; #define PG8_LDA(dst, b, h) do { _Pragma("unroll") for (int m = 0; m < 4; ++m) _Pragma("unroll") for (int k = 0; k < 2; ++k) dst[m][k] = *(const PG8_LAS bf16x8*)(lds + PG8_SA(b, h) + aoff + m * 2048 + k * 1024); } while (0)
; #define PG8_LDB(dst, b, h) do { _Pragma("unroll") for (int n = 0; n < 2; ++n) _Pragma("unroll") for (int k = 0; k < 2; ++k) dst[n][k] = *(const PG8_LAS bf16x8*)(lds + PG8_SB(b, h) + boff + n * 2048 + k * 1024); } while (0)
; #define PG8_MMA(ai, bj, At, Bt) do { __builtin_amdgcn_s_setprio(1); _Pragma("unroll") for (int m = 0; m < 4; ++m) _Pragma("unroll") for (int n = 0; n < 2; ++n) _Pragma("unroll") for (int k = 0; k < 2; ++k) \
;         acc[ai][bj][m][n] = __builtin_amdgcn_mfma_f32_16x16x32_bf16(Bt[n][k], At[m][k], acc[ai][bj][m][n], 0, 0, 0); __builtin_amdgcn_s_setprio(0); } while (0)
; #define PG8_WAIT_V(n) asm volatile("s_waitcnt vmcnt(" #n ")" ::: "memory")
; #define PG8_WAIT_L(n) asm volatile("s_waitcnt lgkmcnt(" #n ")" ::: "memory")
; #define PG8_BAR __builtin_amdgcn_s_barrier()
; #define PG8_SCHED __builtin_amdgcn_sched_barrier(0)
; template <class Epi, class Sched>
; __device__ __forceinline__ void gemm_phase(PG8_LAS unsigned char* lds, const Gemm g, const Sched& S, const Epi& E) {
;     ...
;             PG8_STAGE(PG8_SB(0, 1), b2 + hstep, voffB);
;             PG8_WAIT_V(6); PG8_BAR; PG8_MMA(1, 1, At, B1); PG8_BAR;
;             PG8_LDB(B0, 1, 0); PG8_SCHED; PG8_LDA(At, 1, 0); PG8_STAGE(PG8_SA(0, 1), a2 + hstep, voffA);
;             PG8_WAIT_L(8); PG8_BAR; PG8_WAIT_L(0); PG8_MMA(0, 0, At, B0); PG8_BAR; PG8_SCHED;
;             PG8_LDB(B1, 1, 1); PG8_STAGE(PG8_SB(1, 0), b3, voffB);
;             PG8_BAR; PG8_WAIT_L(0); PG8_MMA(0, 1, At, B1); PG8_BAR;
;             PG8_LDA(At, 1, 1); PG8_STAGE(PG8_SA(1, 0), a3, voffA);
	s_add_u32 s96, s20, 0x40000
	s_addc_u32 s97, s21, 0
	s_add_i32 s30, s8, s9
	s_mov_b32 m0, s30
	v_lshl_add_u64 v[18:19], s[96:97], 0, v[166:167]
	global_load_lds_dwordx4 v[18:19], off
	s_add_i32 m0, s30, 0x2000
	v_lshl_add_u64 v[18:19], s[96:97], 0, v[170:171]
	global_load_lds_dwordx4 v[18:19], off
	s_waitcnt vmcnt(6)
	s_barrier
	s_setprio 1
	v_mfma_f32_16x16x32_bf16 v[48:51], v[234:237], v[196:199], v[48:51]
	v_mfma_f32_16x16x32_bf16 v[28:31], v[226:229], v[210:213], v[28:31]
	v_mfma_f32_16x16x32_bf16 v[18:21], v[234:237], v[210:213], v[20:23]
	v_mfma_f32_16x16x32_bf16 v[4:7], v[226:229], v[218:221], v[4:7]
	v_mfma_f32_16x16x32_bf16 v[0:3], v[234:237], v[218:221], v[0:3]
	v_mfma_f32_16x16x32_bf16 v[24:27], v[226:229], v[148:151], v[68:71]
	v_mfma_f32_16x16x32_bf16 v[32:35], v[234:237], v[148:151], v[64:67]
	v_mfma_f32_16x16x32_bf16 v[36:39], v[226:229], v[196:199], v[52:55]
	v_mfma_f32_16x16x32_bf16 v[48:51], v[238:241], v[200:203], v[48:51]
	v_mfma_f32_16x16x32_bf16 v[28:31], v[230:233], v[214:217], v[28:31]
	v_mfma_f32_16x16x32_bf16 v[20:23], v[238:241], v[214:217], v[18:21]
	v_mfma_f32_16x16x32_bf16 v[4:7], v[230:233], v[222:225], v[4:7]
	v_mfma_f32_16x16x32_bf16 v[0:3], v[238:241], v[222:225], v[0:3]
	v_mfma_f32_16x16x32_bf16 v[24:27], v[230:233], v[192:195], v[24:27]
	v_mfma_f32_16x16x32_bf16 v[32:35], v[238:241], v[192:195], v[32:35]
	v_mfma_f32_16x16x32_bf16 v[36:39], v[230:233], v[200:203], v[36:39]
	s_setprio 0
	s_add_i32 s30, 0, 0x18000
	v_add_u32_e32 v18, s30, v155
	s_barrier
	ds_read_b128 v[52:55], v18
	ds_read_b128 v[64:67], v18 offset:1024
	ds_read_b128 v[68:71], v18 offset:2048
	ds_read_b128 v[144:147], v18 offset:3072
	s_add_u32 s22, s22, 0x40000
	s_addc_u32 s23, s23, 0
	s_mov_b32 m0, s27
	v_lshl_add_u64 v[18:19], s[22:23], 0, v[164:165]
	ds_read_b128 v[148:151], v163 offset:32768
	ds_read_b128 v[192:195], v163 offset:33792
	ds_read_b128 v[196:199], v163 offset:34816
	ds_read_b128 v[200:203], v163 offset:35840
	ds_read_b128 v[210:213], v163 offset:36864
	ds_read_b128 v[214:217], v163 offset:37888
	ds_read_b128 v[218:221], v163 offset:38912
	ds_read_b128 v[222:225], v163 offset:39936
	global_load_lds_dwordx4 v[18:19], off
	s_mov_b32 m0, s31
	v_lshl_add_u64 v[18:19], s[22:23], 0, v[168:169]
	global_load_lds_dwordx4 v[18:19], off
	s_waitcnt lgkmcnt(8)
	s_barrier
	s_waitcnt lgkmcnt(0)
	s_setprio 1
	v_mfma_f32_16x16x32_bf16 v[140:143], v[52:55], v[148:151], v[140:143]
	v_mfma_f32_16x16x32_bf16 v[136:139], v[68:71], v[148:151], v[136:139]
	v_mfma_f32_16x16x32_bf16 v[124:127], v[52:55], v[196:199], v[124:127]
	v_mfma_f32_16x16x32_bf16 v[120:123], v[68:71], v[196:199], v[120:123]
	v_mfma_f32_16x16x32_bf16 v[108:111], v[52:55], v[210:213], v[108:111]
	v_mfma_f32_16x16x32_bf16 v[104:107], v[68:71], v[210:213], v[104:107]
	v_mfma_f32_16x16x32_bf16 v[92:95], v[52:55], v[218:221], v[92:95]
	v_mfma_f32_16x16x32_bf16 v[88:91], v[68:71], v[218:221], v[88:91]
	v_mfma_f32_16x16x32_bf16 v[140:143], v[64:67], v[192:195], v[140:143]
	v_mfma_f32_16x16x32_bf16 v[136:139], v[144:147], v[192:195], v[136:139]
	v_mfma_f32_16x16x32_bf16 v[124:127], v[64:67], v[200:203], v[124:127]
	v_mfma_f32_16x16x32_bf16 v[120:123], v[144:147], v[200:203], v[120:123]
	v_mfma_f32_16x16x32_bf16 v[108:111], v[64:67], v[214:217], v[108:111]
	v_mfma_f32_16x16x32_bf16 v[104:107], v[144:147], v[214:217], v[104:107]
	v_mfma_f32_16x16x32_bf16 v[92:95], v[64:67], v[222:225], v[92:95]
	v_mfma_f32_16x16x32_bf16 v[88:91], v[144:147], v[222:225], v[88:91]
	s_setprio 0
	s_barrier
	s_add_i32 s22, 0, 0x1c000
	v_add_u32_e32 v18, s22, v155
	s_add_i32 s23, s30, s9
	ds_read_b128 v[226:229], v18
	ds_read_b128 v[230:233], v18 offset:1024
	ds_read_b128 v[234:237], v18 offset:2048
	ds_read_b128 v[238:241], v18 offset:3072
	s_mov_b32 m0, s23
	v_lshl_add_u64 v[18:19], v[204:205], 0, s[4:5]
	global_load_lds_dwordx4 v[18:19], off
	s_add_i32 m0, s23, 0x2000
	v_lshl_add_u64 v[18:19], v[242:243], 0, s[4:5]
	global_load_lds_dwordx4 v[18:19], off
	s_barrier
; #define PG8_STAGE(bufoff, gbase, voff) do { _Pragma("unroll") for (int _i = 0; _i < 2; ++_i) \
;         __builtin_amdgcn_global_load_lds((const unsigned*)((const char*)(gbase) + (voff)[_i]), (PG8_LAS unsigned*)(lds + (bufoff) + ldsw + _i * 8192), 16, 0, 0); } while (0)
; #define PG8_LDA(dst, b, h) do { _Pragma("unroll") for (int m = 0; m < 4; ++m) _Pragma("unroll") for (int k = 0; k < 2; ++k) dst[m][k] = *(const PG8_LAS bf16x8*)(lds + PG8_SA(b, h) + aoff + m * 2048 + k * 1024); } while (0)
; #define PG8_MMA(ai, bj, At, Bt) do { __builtin_amdgcn_s_setprio(1); _Pragma("unroll") for (int m = 0; m < 4; ++m) _Pragma("unroll") for (int n = 0; n < 2; ++n) _Pragma("unroll") for (int k = 0; k < 2; ++k) \
;         acc[ai][bj][m][n] = __builtin_amdgcn_mfma_f32_16x16x32_bf16(Bt[n][k], At[m][k], acc[ai][bj][m][n], 0, 0, 0); __builtin_amdgcn_s_setprio(0); } while (0)
; #define PG8_WAIT_V(n) asm volatile("s_waitcnt vmcnt(" #n ")" ::: "memory")
; #define PG8_WAIT_L(n) asm volatile("s_waitcnt lgkmcnt(" #n ")" ::: "memory")
; #define PG8_BAR __builtin_amdgcn_s_barrier()
; #define PG8_SCHED __builtin_amdgcn_sched_barrier(0)
; template <class Epi, class Sched>
; __device__ __forceinline__ void gemm_phase(PG8_LAS unsigned char* lds, const Gemm g, const Sched& S, const Epi& E) {
;     ...
;             PG8_BAR; PG8_WAIT_L(0); PG8_MMA(0, 1, At, B1); PG8_BAR;
;             PG8_LDA(At, 1, 1); PG8_STAGE(PG8_SA(1, 0), a3, voffA);
;             PG8_BAR; PG8_WAIT_L(0); PG8_MMA(1, 0, At, B0); PG8_BAR; PG8_SCHED;
;             PG8_STAGE(PG8_SB(1, 1), b3 + hstep, voffB);
;             PG8_WAIT_V(6); PG8_BAR; PG8_MMA(1, 1, At, B1); PG8_BAR;
	s_waitcnt lgkmcnt(0)
	s_setprio 1
	v_mfma_f32_16x16x32_bf16 v[132:135], v[226:229], v[148:151], v[132:135]
	v_mfma_f32_16x16x32_bf16 v[128:131], v[234:237], v[148:151], v[128:131]
	v_mfma_f32_16x16x32_bf16 v[116:119], v[226:229], v[196:199], v[116:119]
	v_mfma_f32_16x16x32_bf16 v[112:115], v[234:237], v[196:199], v[112:115]
	v_mfma_f32_16x16x32_bf16 v[100:103], v[226:229], v[210:213], v[100:103]
	v_mfma_f32_16x16x32_bf16 v[96:99], v[234:237], v[210:213], v[96:99]
	v_mfma_f32_16x16x32_bf16 v[84:87], v[226:229], v[218:221], v[84:87]
	v_mfma_f32_16x16x32_bf16 v[80:83], v[234:237], v[218:221], v[80:83]
	v_mfma_f32_16x16x32_bf16 v[132:135], v[230:233], v[192:195], v[132:135]
	v_mfma_f32_16x16x32_bf16 v[128:131], v[238:241], v[192:195], v[128:131]
	v_mfma_f32_16x16x32_bf16 v[116:119], v[230:233], v[200:203], v[116:119]
	v_mfma_f32_16x16x32_bf16 v[112:115], v[238:241], v[200:203], v[112:115]
	v_mfma_f32_16x16x32_bf16 v[100:103], v[230:233], v[214:217], v[100:103]
	v_mfma_f32_16x16x32_bf16 v[96:99], v[238:241], v[214:217], v[96:99]
	v_mfma_f32_16x16x32_bf16 v[84:87], v[230:233], v[222:225], v[84:87]
	v_mfma_f32_16x16x32_bf16 v[80:83], v[238:241], v[222:225], v[80:83]
	s_setprio 0
	s_mov_b32 m0, s33
	v_lshl_add_u64 v[18:19], v[244:245], 0, s[4:5]
	s_barrier
	ds_read_b128 v[148:151], v163 offset:49152
	ds_read_b128 v[192:195], v163 offset:50176
	ds_read_b128 v[196:199], v163 offset:51200
	ds_read_b128 v[200:203], v163 offset:52224
	ds_read_b128 v[210:213], v163 offset:53248
	ds_read_b128 v[214:217], v163 offset:54272
	ds_read_b128 v[218:221], v163 offset:55296
	ds_read_b128 v[222:225], v163 offset:56320
	global_load_lds_dwordx4 v[18:19], off
	s_mov_b32 m0, s7
	v_lshl_add_u64 v[18:19], v[246:247], 0, s[4:5]
	global_load_lds_dwordx4 v[18:19], off
	s_barrier
	s_waitcnt lgkmcnt(0)
	s_setprio 1
	v_mfma_f32_16x16x32_bf16 v[76:79], v[52:55], v[148:151], v[76:79]
	v_mfma_f32_16x16x32_bf16 v[72:75], v[68:71], v[148:151], v[72:75]
	v_mfma_f32_16x16x32_bf16 v[60:63], v[52:55], v[196:199], v[60:63]
	v_mfma_f32_16x16x32_bf16 v[56:59], v[68:71], v[196:199], v[56:59]
	v_mfma_f32_16x16x32_bf16 v[44:47], v[52:55], v[210:213], v[44:47]
	v_mfma_f32_16x16x32_bf16 v[40:43], v[68:71], v[210:213], v[40:43]
	v_mfma_f32_16x16x32_bf16 v[14:17], v[52:55], v[218:221], v[14:17]
	v_mfma_f32_16x16x32_bf16 v[8:11], v[68:71], v[218:221], v[8:11]
	v_mfma_f32_16x16x32_bf16 v[76:79], v[64:67], v[192:195], v[76:79]
	v_mfma_f32_16x16x32_bf16 v[72:75], v[144:147], v[192:195], v[72:75]
	v_mfma_f32_16x16x32_bf16 v[60:63], v[64:67], v[200:203], v[60:63]
	v_mfma_f32_16x16x32_bf16 v[56:59], v[144:147], v[200:203], v[56:59]
	v_mfma_f32_16x16x32_bf16 v[44:47], v[64:67], v[214:217], v[44:47]
	v_mfma_f32_16x16x32_bf16 v[40:43], v[144:147], v[214:217], v[40:43]
	v_mfma_f32_16x16x32_bf16 v[16:19], v[64:67], v[222:225], v[14:17]
	v_mfma_f32_16x16x32_bf16 v[8:11], v[144:147], v[222:225], v[8:11]
	s_setprio 0
	s_barrier
	s_add_u32 s20, s20, 0x40080
	s_addc_u32 s21, s21, 0
	s_add_i32 s22, s22, s9
	s_mov_b32 m0, s22
	v_lshl_add_u64 v[14:15], s[20:21], 0, v[166:167]
	global_load_lds_dwordx4 v[14:15], off
	s_add_i32 m0, s22, 0x2000
	v_lshl_add_u64 v[14:15], s[20:21], 0, v[170:171]
	global_load_lds_dwordx4 v[14:15], off
	s_waitcnt vmcnt(6)
	s_barrier
	s_setprio 1
	v_mfma_f32_16x16x32_bf16 v[24:27], v[226:229], v[148:151], v[24:27]
	v_mfma_f32_16x16x32_bf16 v[68:71], v[230:233], v[192:195], v[24:27]
	v_mfma_f32_16x16x32_bf16 v[24:27], v[234:237], v[148:151], v[32:35]
	v_mfma_f32_16x16x32_bf16 v[64:67], v[238:241], v[192:195], v[24:27]
	v_mfma_f32_16x16x32_bf16 v[24:27], v[226:229], v[196:199], v[36:39]
	v_mfma_f32_16x16x32_bf16 v[52:55], v[230:233], v[200:203], v[24:27]
	v_mfma_f32_16x16x32_bf16 v[24:27], v[234:237], v[196:199], v[48:51]
	v_mfma_f32_16x16x32_bf16 v[48:51], v[238:241], v[200:203], v[24:27]
	v_mfma_f32_16x16x32_bf16 v[24:27], v[226:229], v[210:213], v[28:31]
	v_mfma_f32_16x16x32_bf16 v[20:23], v[234:237], v[210:213], v[20:23]
	v_mfma_f32_16x16x32_bf16 v[4:7], v[226:229], v[218:221], v[4:7]
	v_mfma_f32_16x16x32_bf16 v[0:3], v[234:237], v[218:221], v[0:3]
	v_mfma_f32_16x16x32_bf16 v[28:31], v[230:233], v[214:217], v[24:27]
	v_mfma_f32_16x16x32_bf16 v[20:23], v[238:241], v[214:217], v[20:23]
	v_mfma_f32_16x16x32_bf16 v[4:7], v[230:233], v[222:225], v[4:7]
	v_mfma_f32_16x16x32_bf16 v[0:3], v[238:241], v[222:225], v[0:3]
	s_setprio 0
	s_add_i32 s3, s3, 2
	s_add_u32 s0, s0, 0x100
	s_addc_u32 s1, s1, 0
	s_add_u32 vcc_hi, vcc_hi, 0x100
	s_addc_u32 s2, s2, 0
	s_cmp_lt_u32 s3, 14
	s_barrier
	s_cbranch_scc0 .LBB0_197

; #define PG8_STAGE(bufoff, gbase, voff) do { _Pragma("unroll") for (int _i = 0; _i < 2; ++_i) \
;         __builtin_amdgcn_global_load_lds((const unsigned*)((const char*)(gbase) + (voff)[_i]), (PG8_LAS unsigned*)(lds + (bufoff) + ldsw + _i * 8192), 16, 0, 0); } while (0)
; #define PG8_LDA(dst, b, h) do { _Pragma("unroll") for (int m = 0; m < 4; ++m) _Pragma("unroll") for (int k = 0; k < 2; ++k) dst[m][k] = *(const PG8_LAS bf16x8*)(lds + PG8_SA(b, h) + aoff + m * 2048 + k * 1024); } while (0)
; #define PG8_LDB(dst, b, h) do { _Pragma("unroll") for (int n = 0; n < 2; ++n) _Pragma("unroll") for (int k = 0; k < 2; ++k) dst[n][k] = *(const PG8_LAS bf16x8*)(lds + PG8_SB(b, h) + boff + n * 2048 + k * 1024); } while (0)
; #define PG8_MMA(ai, bj, At, Bt) do { __builtin_amdgcn_s_setprio(1); _Pragma("unroll") for (int m = 0; m < 4; ++m) _Pragma("unroll") for (int n = 0; n < 2; ++n) _Pragma("unroll") for (int k = 0; k < 2; ++k) \
;         acc[ai][bj][m][n] = __builtin_amdgcn_mfma_f32_16x16x32_bf16(Bt[n][k], At[m][k], acc[ai][bj][m][n], 0, 0, 0); __builtin_amdgcn_s_setprio(0); } while (0)
; #define PG8_WAIT_L(n) asm volatile("s_waitcnt lgkmcnt(" #n ")" ::: "memory")
; #define PG8_BAR __builtin_amdgcn_s_barrier()
; #define PG8_SCHED __builtin_amdgcn_sched_barrier(0)
; template <class Epi, class Sched>
; __device__ __forceinline__ void gemm_phase(PG8_LAS unsigned char* lds, const Gemm g, const Sched& S, const Epi& E) {
;     ...
;             const bool last = (t == cnk - 2);
;             const char* a1 = cA + (size_t)(t + 1) * kstep;
;             const char* a2 = last ? nA : cA + (size_t)(t + 2) * kstep; const char* b2 = last ? nB : cB + (size_t)(t + 2) * kstep;
;             const char* a3 = a2 + kstep; const char* b3 = b2 + kstep;
;             if (last && has_next) S.a_ready(nxt);
;             if (last) E.prefetch(pre, cur, wr, fr);
;             PG8_LDB(B0, 0, 0); PG8_SCHED; PG8_LDA(At, 0, 0); PG8_STAGE(PG8_SA(1, 1), a1 + hstep, voffA);
;             PG8_WAIT_L(8); PG8_BAR; PG8_WAIT_L(0); PG8_MMA(0, 0, At, B0); PG8_BAR; PG8_SCHED;
;             PG8_LDB(B1, 0, 1); PG8_STAGE(PG8_SB(0, 0), b2, voffB);
;             PG8_BAR; PG8_WAIT_L(0); PG8_MMA(0, 1, At, B1); PG8_BAR;
;             PG8_LDA(At, 0, 1); PG8_STAGE(PG8_SA(0, 0), a2, voffA);
;             PG8_BAR; PG8_WAIT_L(0); PG8_MMA(1, 0, At, B0); PG8_BAR; PG8_SCHED;
.LBB0_1191:
	ds_read_b128 v[128:131], v163
	ds_read_b128 v[132:135], v163 offset:1024
	ds_read_b128 v[136:139], v163 offset:2048
	ds_read_b128 v[168:171], v163 offset:3072
	s_add_u32 s16, s14, 0xfffe0080
	s_addc_u32 s17, s15, -1
	s_cmp_eq_u32 s41, 4
	s_cselect_b32 s19, s7, s17
	s_cselect_b32 s18, s37, s16
	s_cselect_b32 s17, s5, s40
	s_cselect_b32 s16, s38, s39
	v_lshl_add_u64 v[206:207], s[14:15], 0, v[148:149]
	s_add_i32 m0, s13, 0xc000
	ds_read_b128 v[172:175], v176
	ds_read_b128 v[178:181], v176 offset:1024
	ds_read_b128 v[182:185], v176 offset:2048
	ds_read_b128 v[186:189], v176 offset:3072
	ds_read_b128 v[190:193], v176 offset:4096
	ds_read_b128 v[194:197], v176 offset:5120
	ds_read_b128 v[198:201], v176 offset:6144
	ds_read_b128 v[202:205], v176 offset:7168
	global_load_lds_dwordx4 v[206:207], off
	s_add_i32 m0, s13, 0xe000
	v_lshl_add_u64 v[206:207], s[14:15], 0, v[150:151]
	global_load_lds_dwordx4 v[206:207], off
	s_waitcnt lgkmcnt(8)
	s_barrier
	s_waitcnt lgkmcnt(0)
	s_setprio 1
	v_mfma_f32_16x16x32_bf16 v[124:127], v[128:131], v[172:175], v[124:127]
	v_mfma_f32_16x16x32_bf16 v[120:123], v[136:139], v[172:175], v[120:123]
	v_mfma_f32_16x16x32_bf16 v[108:111], v[128:131], v[182:185], v[108:111]
	v_mfma_f32_16x16x32_bf16 v[104:107], v[136:139], v[182:185], v[104:107]
	v_mfma_f32_16x16x32_bf16 v[92:95], v[128:131], v[190:193], v[92:95]
	v_mfma_f32_16x16x32_bf16 v[88:91], v[136:139], v[190:193], v[88:91]
	v_mfma_f32_16x16x32_bf16 v[76:79], v[128:131], v[198:201], v[76:79]
	v_mfma_f32_16x16x32_bf16 v[72:75], v[136:139], v[198:201], v[72:75]
	v_mfma_f32_16x16x32_bf16 v[124:127], v[132:135], v[178:181], v[124:127]
	v_mfma_f32_16x16x32_bf16 v[120:123], v[168:171], v[178:181], v[120:123]
	v_mfma_f32_16x16x32_bf16 v[108:111], v[132:135], v[186:189], v[108:111]
	v_mfma_f32_16x16x32_bf16 v[104:107], v[168:171], v[186:189], v[104:107]
	v_mfma_f32_16x16x32_bf16 v[92:95], v[132:135], v[194:197], v[92:95]
	v_mfma_f32_16x16x32_bf16 v[88:91], v[168:171], v[194:197], v[88:91]
	v_mfma_f32_16x16x32_bf16 v[76:79], v[132:135], v[202:205], v[76:79]
	v_mfma_f32_16x16x32_bf16 v[72:75], v[168:171], v[202:205], v[72:75]
	s_setprio 0
	s_barrier
	s_add_i32 s30, s34, s22
	v_lshl_add_u64 v[222:223], s[16:17], 0, v[142:143]
	s_mov_b32 m0, s30
	ds_read_b128 v[206:209], v177
	ds_read_b128 v[210:213], v177 offset:1024
	ds_read_b128 v[214:217], v177 offset:2048
	ds_read_b128 v[218:221], v177 offset:3072
	global_load_lds_dwordx4 v[222:223], off
	s_add_i32 m0, s30, 0x2000
	v_lshl_add_u64 v[224:225], s[16:17], 0, v[146:147]
	global_load_lds_dwordx4 v[224:225], off
	s_barrier
	s_waitcnt lgkmcnt(0)
	s_setprio 1
	v_mfma_f32_16x16x32_bf16 v[116:119], v[206:209], v[172:175], v[116:119]
	v_mfma_f32_16x16x32_bf16 v[112:115], v[214:217], v[172:175], v[112:115]
	v_mfma_f32_16x16x32_bf16 v[100:103], v[206:209], v[182:185], v[100:103]
	v_mfma_f32_16x16x32_bf16 v[96:99], v[214:217], v[182:185], v[96:99]
	v_mfma_f32_16x16x32_bf16 v[84:87], v[206:209], v[190:193], v[84:87]
	v_mfma_f32_16x16x32_bf16 v[80:83], v[214:217], v[190:193], v[80:83]
	v_mfma_f32_16x16x32_bf16 v[68:71], v[206:209], v[198:201], v[68:71]
	v_mfma_f32_16x16x32_bf16 v[64:67], v[214:217], v[198:201], v[64:67]
	v_mfma_f32_16x16x32_bf16 v[116:119], v[210:213], v[178:181], v[116:119]
	v_mfma_f32_16x16x32_bf16 v[112:115], v[218:221], v[178:181], v[112:115]
	v_mfma_f32_16x16x32_bf16 v[100:103], v[210:213], v[186:189], v[100:103]
	v_mfma_f32_16x16x32_bf16 v[96:99], v[218:221], v[186:189], v[96:99]
	v_mfma_f32_16x16x32_bf16 v[84:87], v[210:213], v[194:197], v[84:87]
	v_mfma_f32_16x16x32_bf16 v[80:83], v[218:221], v[194:197], v[80:83]
	v_mfma_f32_16x16x32_bf16 v[68:71], v[210:213], v[202:205], v[68:71]
	v_mfma_f32_16x16x32_bf16 v[64:67], v[218:221], v[202:205], v[64:67]
	s_setprio 0
	s_mov_b32 m0, s13
	v_lshl_add_u64 v[226:227], s[18:19], 0, v[140:141]
	s_barrier
	ds_read_b128 v[172:175], v176 offset:16384
	ds_read_b128 v[178:181], v176 offset:17408
	ds_read_b128 v[182:185], v176 offset:18432
	ds_read_b128 v[186:189], v176 offset:19456
	ds_read_b128 v[190:193], v176 offset:20480
	ds_read_b128 v[194:197], v176 offset:21504
	ds_read_b128 v[198:201], v176 offset:22528
	ds_read_b128 v[202:205], v176 offset:23552
	global_load_lds_dwordx4 v[226:227], off
	s_mov_b32 m0, s23
	v_lshl_add_u64 v[228:229], s[18:19], 0, v[144:145]
	global_load_lds_dwordx4 v[228:229], off
	s_barrier
	s_waitcnt lgkmcnt(0)
	s_setprio 1
	v_mfma_f32_16x16x32_bf16 v[60:63], v[128:131], v[172:175], v[60:63]
	v_mfma_f32_16x16x32_bf16 v[56:59], v[136:139], v[172:175], v[56:59]
	v_mfma_f32_16x16x32_bf16 v[44:47], v[128:131], v[182:185], v[44:47]
	v_mfma_f32_16x16x32_bf16 v[40:43], v[136:139], v[182:185], v[40:43]
	v_mfma_f32_16x16x32_bf16 v[28:31], v[128:131], v[190:193], v[28:31]
	v_mfma_f32_16x16x32_bf16 v[24:27], v[136:139], v[190:193], v[24:27]
	v_mfma_f32_16x16x32_bf16 v[12:15], v[128:131], v[198:201], v[12:15]
	v_mfma_f32_16x16x32_bf16 v[8:11], v[136:139], v[198:201], v[8:11]
	v_mfma_f32_16x16x32_bf16 v[60:63], v[132:135], v[178:181], v[60:63]
	v_mfma_f32_16x16x32_bf16 v[56:59], v[168:171], v[178:181], v[56:59]
	v_mfma_f32_16x16x32_bf16 v[44:47], v[132:135], v[186:189], v[44:47]
	v_mfma_f32_16x16x32_bf16 v[40:43], v[168:171], v[186:189], v[40:43]
	v_mfma_f32_16x16x32_bf16 v[28:31], v[132:135], v[194:197], v[28:31]
	v_mfma_f32_16x16x32_bf16 v[24:27], v[168:171], v[194:197], v[24:27]
	v_mfma_f32_16x16x32_bf16 v[12:15], v[132:135], v[202:205], v[12:15]
	v_mfma_f32_16x16x32_bf16 v[8:11], v[168:171], v[202:205], v[8:11]
	s_setprio 0
	s_barrier
; #define PG8_STAGE(bufoff, gbase, voff) do { _Pragma("unroll") for (int _i = 0; _i < 2; ++_i) \
;         __builtin_amdgcn_global_load_lds((const unsigned*)((const char*)(gbase) + (voff)[_i]), (PG8_LAS unsigned*)(lds + (bufoff) + ldsw + _i * 8192), 16, 0, 0); } while (0)
; #define PG8_LDA(dst, b, h) do { _Pragma("unroll") for (int m = 0; m < 4; ++m) _Pragma("unroll") for (int k = 0; k < 2; ++k) dst[m][k] = *(const PG8_LAS bf16x8*)(lds + PG8_SA(b, h) + aoff + m * 2048 + k * 1024); } while (0)
; #define PG8_LDB(dst, b, h) do { _Pragma("unroll") for (int n = 0; n < 2; ++n) _Pragma("unroll") for (int k = 0; k < 2; ++k) dst[n][k] = *(const PG8_LAS bf16x8*)(lds + PG8_SB(b, h) + boff + n * 2048 + k * 1024); } while (0)
; #define PG8_MMA(ai, bj, At, Bt) do { __builtin_amdgcn_s_setprio(1); _Pragma("unroll") for (int m = 0; m < 4; ++m) _Pragma("unroll") for (int n = 0; n < 2; ++n) _Pragma("unroll") for (int k = 0; k < 2; ++k) \
;         acc[ai][bj][m][n] = __builtin_amdgcn_mfma_f32_16x16x32_bf16(Bt[n][k], At[m][k], acc[ai][bj][m][n], 0, 0, 0); __builtin_amdgcn_s_setprio(0); } while (0)
; #define PG8_WAIT_V(n) asm volatile("s_waitcnt vmcnt(" #n ")" ::: "memory")
; #define PG8_WAIT_L(n) asm volatile("s_waitcnt lgkmcnt(" #n ")" ::: "memory")
; #define PG8_BAR __builtin_amdgcn_s_barrier()
; #define PG8_SCHED __builtin_amdgcn_sched_barrier(0)
; template <class Epi, class Sched>
; __device__ __forceinline__ void gemm_phase(PG8_LAS unsigned char* lds, const Gemm g, const Sched& S, const Epi& E) {
;     ...
;             PG8_STAGE(PG8_SB(0, 1), b2 + hstep, voffB);
;             PG8_WAIT_V(6); PG8_BAR; PG8_MMA(1, 1, At, B1); PG8_BAR;
;             PG8_LDB(B0, 1, 0); PG8_SCHED; PG8_LDA(At, 1, 0); PG8_STAGE(PG8_SA(0, 1), a2 + hstep, voffA);
;             PG8_WAIT_L(8); PG8_BAR; PG8_WAIT_L(0); PG8_MMA(0, 0, At, B0); PG8_BAR; PG8_SCHED;
;             PG8_LDB(B1, 1, 1); PG8_STAGE(PG8_SB(1, 0), b3, voffB);
;             PG8_BAR; PG8_WAIT_L(0); PG8_MMA(0, 1, At, B1); PG8_BAR;
;             PG8_LDA(At, 1, 1); PG8_STAGE(PG8_SA(1, 0), a3, voffA);
	s_add_u32 s42, s16, 0x20000
	s_addc_u32 s43, s17, 0
	s_add_i32 s30, s35, s22
	s_mov_b32 m0, s30
	v_lshl_add_u64 v[128:129], s[42:43], 0, v[142:143]
	global_load_lds_dwordx4 v[128:129], off
	s_add_i32 m0, s30, 0x2000
	v_lshl_add_u64 v[128:129], s[42:43], 0, v[146:147]
	global_load_lds_dwordx4 v[128:129], off
	s_waitcnt vmcnt(6)
	s_barrier
	s_setprio 1
	v_mfma_f32_16x16x32_bf16 v[52:55], v[206:209], v[172:175], v[52:55]
	v_mfma_f32_16x16x32_bf16 v[48:51], v[214:217], v[172:175], v[48:51]
	v_mfma_f32_16x16x32_bf16 v[36:39], v[206:209], v[182:185], v[36:39]
	v_mfma_f32_16x16x32_bf16 v[32:35], v[214:217], v[182:185], v[32:35]
	v_mfma_f32_16x16x32_bf16 v[20:23], v[206:209], v[190:193], v[20:23]
	v_mfma_f32_16x16x32_bf16 v[16:19], v[214:217], v[190:193], v[16:19]
	v_mfma_f32_16x16x32_bf16 v[4:7], v[206:209], v[198:201], v[4:7]
	v_mfma_f32_16x16x32_bf16 v[0:3], v[214:217], v[198:201], v[0:3]
	v_mfma_f32_16x16x32_bf16 v[52:55], v[210:213], v[178:181], v[52:55]
	v_mfma_f32_16x16x32_bf16 v[48:51], v[218:221], v[178:181], v[48:51]
	v_mfma_f32_16x16x32_bf16 v[36:39], v[210:213], v[186:189], v[36:39]
	v_mfma_f32_16x16x32_bf16 v[32:35], v[218:221], v[186:189], v[32:35]
	v_mfma_f32_16x16x32_bf16 v[20:23], v[210:213], v[194:197], v[20:23]
	v_mfma_f32_16x16x32_bf16 v[16:19], v[218:221], v[194:197], v[16:19]
	v_mfma_f32_16x16x32_bf16 v[4:7], v[210:213], v[202:205], v[4:7]
	v_mfma_f32_16x16x32_bf16 v[0:3], v[218:221], v[202:205], v[0:3]
	s_setprio 0
	s_add_i32 s30, 0, 0x18000
	v_add_u32_e32 v168, s30, v159
	s_barrier
	ds_read_b128 v[128:131], v168
	ds_read_b128 v[132:135], v168 offset:1024
	ds_read_b128 v[136:139], v168 offset:2048
	ds_read_b128 v[168:171], v168 offset:3072
	s_add_u32 s18, s18, 0x20000
	s_addc_u32 s19, s19, 0
	s_mov_b32 m0, s24
	v_lshl_add_u64 v[206:207], s[18:19], 0, v[140:141]
	ds_read_b128 v[172:175], v176 offset:32768
	ds_read_b128 v[178:181], v176 offset:33792
	ds_read_b128 v[182:185], v176 offset:34816
	ds_read_b128 v[186:189], v176 offset:35840
	ds_read_b128 v[190:193], v176 offset:36864
	ds_read_b128 v[194:197], v176 offset:37888
	ds_read_b128 v[198:201], v176 offset:38912
	ds_read_b128 v[202:205], v176 offset:39936
	global_load_lds_dwordx4 v[206:207], off
	s_mov_b32 m0, s25
	v_lshl_add_u64 v[206:207], s[18:19], 0, v[144:145]
	global_load_lds_dwordx4 v[206:207], off
	s_waitcnt lgkmcnt(8)
	s_barrier
	s_waitcnt lgkmcnt(0)
	s_setprio 1
	v_mfma_f32_16x16x32_bf16 v[124:127], v[128:131], v[172:175], v[124:127]
	v_mfma_f32_16x16x32_bf16 v[120:123], v[136:139], v[172:175], v[120:123]
	v_mfma_f32_16x16x32_bf16 v[108:111], v[128:131], v[182:185], v[108:111]
	v_mfma_f32_16x16x32_bf16 v[104:107], v[136:139], v[182:185], v[104:107]
	v_mfma_f32_16x16x32_bf16 v[92:95], v[128:131], v[190:193], v[92:95]
	v_mfma_f32_16x16x32_bf16 v[88:91], v[136:139], v[190:193], v[88:91]
	v_mfma_f32_16x16x32_bf16 v[76:79], v[128:131], v[198:201], v[76:79]
	v_mfma_f32_16x16x32_bf16 v[72:75], v[136:139], v[198:201], v[72:75]
	v_mfma_f32_16x16x32_bf16 v[124:127], v[132:135], v[178:181], v[124:127]
	v_mfma_f32_16x16x32_bf16 v[120:123], v[168:171], v[178:181], v[120:123]
	v_mfma_f32_16x16x32_bf16 v[108:111], v[132:135], v[186:189], v[108:111]
	v_mfma_f32_16x16x32_bf16 v[104:107], v[168:171], v[186:189], v[104:107]
	v_mfma_f32_16x16x32_bf16 v[92:95], v[132:135], v[194:197], v[92:95]
	v_mfma_f32_16x16x32_bf16 v[88:91], v[168:171], v[194:197], v[88:91]
	v_mfma_f32_16x16x32_bf16 v[76:79], v[132:135], v[202:205], v[76:79]
	v_mfma_f32_16x16x32_bf16 v[72:75], v[168:171], v[202:205], v[72:75]
	s_setprio 0
	s_barrier
	s_add_i32 s18, 0, 0x1c000
	s_add_i32 s19, s30, s22
	v_add_u32_e32 v218, s18, v159
	v_lshl_add_u64 v[222:223], v[222:223], 0, s[2:3]
	s_mov_b32 m0, s19
	ds_read_b128 v[206:209], v218
	ds_read_b128 v[210:213], v218 offset:1024
	ds_read_b128 v[214:217], v218 offset:2048
	ds_read_b128 v[218:221], v218 offset:3072
	global_load_lds_dwordx4 v[222:223], off
	s_add_i32 m0, s19, 0x2000
	v_lshl_add_u64 v[222:223], v[224:225], 0, s[2:3]
	global_load_lds_dwordx4 v[222:223], off
	s_barrier
	s_waitcnt lgkmcnt(0)
	s_setprio 1
	v_mfma_f32_16x16x32_bf16 v[116:119], v[206:209], v[172:175], v[116:119]
	v_mfma_f32_16x16x32_bf16 v[112:115], v[214:217], v[172:175], v[112:115]
	v_mfma_f32_16x16x32_bf16 v[100:103], v[206:209], v[182:185], v[100:103]
	v_mfma_f32_16x16x32_bf16 v[96:99], v[214:217], v[182:185], v[96:99]
	v_mfma_f32_16x16x32_bf16 v[84:87], v[206:209], v[190:193], v[84:87]
	v_mfma_f32_16x16x32_bf16 v[80:83], v[214:217], v[190:193], v[80:83]
	v_mfma_f32_16x16x32_bf16 v[68:71], v[206:209], v[198:201], v[68:71]
	v_mfma_f32_16x16x32_bf16 v[64:67], v[214:217], v[198:201], v[64:67]
	v_mfma_f32_16x16x32_bf16 v[116:119], v[210:213], v[178:181], v[116:119]
	v_mfma_f32_16x16x32_bf16 v[112:115], v[218:221], v[178:181], v[112:115]
	v_mfma_f32_16x16x32_bf16 v[100:103], v[210:213], v[186:189], v[100:103]
	v_mfma_f32_16x16x32_bf16 v[96:99], v[218:221], v[186:189], v[96:99]
	v_mfma_f32_16x16x32_bf16 v[84:87], v[210:213], v[194:197], v[84:87]
	v_mfma_f32_16x16x32_bf16 v[80:83], v[218:221], v[194:197], v[80:83]
	v_mfma_f32_16x16x32_bf16 v[68:71], v[210:213], v[202:205], v[68:71]
	v_mfma_f32_16x16x32_bf16 v[64:67], v[218:221], v[202:205], v[64:67]
	s_setprio 0
	s_mov_b32 m0, s27
	v_lshl_add_u64 v[222:223], v[226:227], 0, s[2:3]
	s_barrier
	ds_read_b128 v[172:175], v176 offset:49152
	ds_read_b128 v[178:181], v176 offset:50176
	ds_read_b128 v[182:185], v176 offset:51200
	ds_read_b128 v[186:189], v176 offset:52224
	ds_read_b128 v[190:193], v176 offset:53248
	ds_read_b128 v[194:197], v176 offset:54272
	ds_read_b128 v[198:201], v176 offset:55296
	ds_read_b128 v[202:205], v176 offset:56320
	global_load_lds_dwordx4 v[222:223], off
	s_mov_b32 m0, s29
	v_lshl_add_u64 v[222:223], v[228:229], 0, s[2:3]
	global_load_lds_dwordx4 v[222:223], off
	s_barrier
; #define PG8_STAGE(bufoff, gbase, voff) do { _Pragma("unroll") for (int _i = 0; _i < 2; ++_i) \
;         __builtin_amdgcn_global_load_lds((const unsigned*)((const char*)(gbase) + (voff)[_i]), (PG8_LAS unsigned*)(lds + (bufoff) + ldsw + _i * 8192), 16, 0, 0); } while (0)
; #define PG8_MMA(ai, bj, At, Bt) do { __builtin_amdgcn_s_setprio(1); _Pragma("unroll") for (int m = 0; m < 4; ++m) _Pragma("unroll") for (int n = 0; n < 2; ++n) _Pragma("unroll") for (int k = 0; k < 2; ++k) \
;         acc[ai][bj][m][n] = __builtin_amdgcn_mfma_f32_16x16x32_bf16(Bt[n][k], At[m][k], acc[ai][bj][m][n], 0, 0, 0); __builtin_amdgcn_s_setprio(0); } while (0)
; #define PG8_WAIT_V(n) asm volatile("s_waitcnt vmcnt(" #n ")" ::: "memory")
; #define PG8_WAIT_L(n) asm volatile("s_waitcnt lgkmcnt(" #n ")" ::: "memory")
; #define PG8_BAR __builtin_amdgcn_s_barrier()
; template <class Epi, class Sched>
; __device__ __forceinline__ void gemm_phase(PG8_LAS unsigned char* lds, const Gemm g, const Sched& S, const Epi& E) {
;     ...
;             PG8_BAR; PG8_WAIT_L(0); PG8_MMA(1, 0, At, B0); PG8_BAR; PG8_SCHED;
;             PG8_STAGE(PG8_SB(1, 1), b3 + hstep, voffB);
;             PG8_WAIT_V(6); PG8_BAR; PG8_MMA(1, 1, At, B1); PG8_BAR;
;     DI void operator()(const f32x4 (&acc)[2][2][4][2], const Unit& u, int wr, int wc, int fr, int fq, const Pre& pre) const {
;         const int cb = u.pn * 256 + wc * 32 + 8 * fq, row0 = u.pm * 256 + wr * 64 + fr;
; #pragma unroll
;         for (int ai = 0; ai < 2; ++ai) {
;             u32x4v y[4][2];
; #pragma unroll
;             for (int m = 0; m < 4; ++m)
; #pragma unroll
;                 for (int bj = 0; bj < 2; ++bj) y[m][bj] = *(const u32x4v*)(YG + (size_t)(row0 + ai * 128 + m * 16) * 512 + cb + bj * 128);
; #pragma unroll
;             for (int m = 0; m < 4; ++m) { const int row = row0 + ai * 128 + m * 16;
; #pragma unroll
;                 for (int bj = 0; bj < 2; ++bj) { const f32x4 v0 = acc[ai][bj][m][0], v1 = acc[ai][bj][m][1]; const u32x4v yy = y[m][bj]; u32x4v o;
;                     o.x = pk2(bflo(yy.x) * sigm(v0[0]), bfhi(yy.x) * sigm(v0[1])); o.y = pk2(bflo(yy.y) * sigm(v0[2]), bfhi(yy.y) * sigm(v0[3]));
;                     o.z = pk2(bflo(yy.z) * sigm(v1[0]), bfhi(yy.z) * sigm(v1[1])); o.w = pk2(bflo(yy.w) * sigm(v1[2]), bfhi(yy.w) * sigm(v1[3]));
;                     *(u32x4v*)(CAT + (size_t)row * 1024 + 512 + cb + bj * 128) = o; } } }
	s_waitcnt lgkmcnt(0)
	s_setprio 1
	v_mfma_f32_16x16x32_bf16 v[60:63], v[128:131], v[172:175], v[60:63]
	v_mfma_f32_16x16x32_bf16 v[56:59], v[136:139], v[172:175], v[56:59]
	v_mfma_f32_16x16x32_bf16 v[44:47], v[128:131], v[182:185], v[44:47]
	v_mfma_f32_16x16x32_bf16 v[40:43], v[136:139], v[182:185], v[40:43]
	v_mfma_f32_16x16x32_bf16 v[28:31], v[128:131], v[190:193], v[28:31]
	v_mfma_f32_16x16x32_bf16 v[24:27], v[136:139], v[190:193], v[24:27]
	v_mfma_f32_16x16x32_bf16 v[12:15], v[128:131], v[198:201], v[12:15]
	v_mfma_f32_16x16x32_bf16 v[8:11], v[136:139], v[198:201], v[8:11]
	v_mfma_f32_16x16x32_bf16 v[60:63], v[132:135], v[178:181], v[60:63]
	v_mfma_f32_16x16x32_bf16 v[56:59], v[168:171], v[178:181], v[56:59]
	v_mfma_f32_16x16x32_bf16 v[44:47], v[132:135], v[186:189], v[44:47]
	v_mfma_f32_16x16x32_bf16 v[40:43], v[168:171], v[186:189], v[40:43]
	v_mfma_f32_16x16x32_bf16 v[28:31], v[132:135], v[194:197], v[28:31]
	v_mfma_f32_16x16x32_bf16 v[24:27], v[168:171], v[194:197], v[24:27]
	v_mfma_f32_16x16x32_bf16 v[12:15], v[132:135], v[202:205], v[12:15]
	v_mfma_f32_16x16x32_bf16 v[8:11], v[168:171], v[202:205], v[8:11]
	s_setprio 0
	s_barrier
	s_add_u32 s16, s16, 0x20080
	s_addc_u32 s17, s17, 0
	s_add_i32 s18, s18, s22
	s_mov_b32 m0, s18
	v_lshl_add_u64 v[128:129], s[16:17], 0, v[142:143]
	global_load_lds_dwordx4 v[128:129], off
	s_add_i32 m0, s18, 0x2000
	v_lshl_add_u64 v[128:129], s[16:17], 0, v[146:147]
	global_load_lds_dwordx4 v[128:129], off
	s_waitcnt vmcnt(6)
	s_barrier
	s_setprio 1
	v_mfma_f32_16x16x32_bf16 v[52:55], v[206:209], v[172:175], v[52:55]
	v_mfma_f32_16x16x32_bf16 v[48:51], v[214:217], v[172:175], v[48:51]
	v_mfma_f32_16x16x32_bf16 v[36:39], v[206:209], v[182:185], v[36:39]
	v_mfma_f32_16x16x32_bf16 v[32:35], v[214:217], v[182:185], v[32:35]
	v_mfma_f32_16x16x32_bf16 v[20:23], v[206:209], v[190:193], v[20:23]
	v_mfma_f32_16x16x32_bf16 v[16:19], v[214:217], v[190:193], v[16:19]
	v_mfma_f32_16x16x32_bf16 v[4:7], v[206:209], v[198:201], v[4:7]
	v_mfma_f32_16x16x32_bf16 v[0:3], v[214:217], v[198:201], v[0:3]
	v_mfma_f32_16x16x32_bf16 v[52:55], v[210:213], v[178:181], v[52:55]
	v_mfma_f32_16x16x32_bf16 v[48:51], v[218:221], v[178:181], v[48:51]
	v_mfma_f32_16x16x32_bf16 v[36:39], v[210:213], v[186:189], v[36:39]
	v_mfma_f32_16x16x32_bf16 v[32:35], v[218:221], v[186:189], v[32:35]
	v_mfma_f32_16x16x32_bf16 v[20:23], v[210:213], v[194:197], v[20:23]
	v_mfma_f32_16x16x32_bf16 v[16:19], v[218:221], v[194:197], v[16:19]
	v_mfma_f32_16x16x32_bf16 v[4:7], v[210:213], v[202:205], v[4:7]
	v_mfma_f32_16x16x32_bf16 v[0:3], v[218:221], v[202:205], v[0:3]
	s_setprio 0
	s_add_i32 s41, s41, 2
	s_add_u32 s14, s14, 0x100
	s_addc_u32 s15, s15, 0
	s_add_u32 s39, s39, 0x100
	s_addc_u32 s40, s40, 0
	s_cmp_lt_u32 s41, 6
	s_barrier
	s_cbranch_scc1 .LBB0_1191
	v_lshl_or_b32 v128, s36, 8, v161
	v_lshl_add_u32 v170, s12, 8, v157
	v_ashrrev_i32_e32 v129, 31, v128
	v_readlane_b32 s36, v255, 8
	v_lshlrev_b64 v[168:169], 1, v[128:129]
	v_readlane_b32 s44, v255, 16
	v_readlane_b32 s45, v255, 17
	v_ashrrev_i32_e32 v171, 31, v170
	v_lshlrev_b64 v[128:129], 10, v[170:171]
	v_lshl_add_u64 v[172:173], s[44:45], 0, v[168:169]
	v_lshl_add_u64 v[128:129], v[172:173], 0, v[128:129]
	global_load_dwordx4 v[178:181], v[128:129], off
	global_load_dwordx4 v[182:185], v[128:129], off offset:256
	v_or_b32_e32 v190, 16, v170
	v_or_b32_e32 v174, 32, v170
	v_mul_f32_e32 v124, 0xbfb8aa3b, v124
	v_mul_f32_e32 v125, 0xbfb8aa3b, v125
	v_mul_f32_e32 v120, 0xbfb8aa3b, v120
	v_mul_f32_e32 v121, 0xbfb8aa3b, v121
	v_mul_f32_e32 v122, 0xbfb8aa3b, v122
	v_mul_f32_e32 v123, 0xbfb8aa3b, v123
	v_mul_f32_e32 v128, 0xbfb8aa3b, v116
	v_mul_f32_e32 v117, 0xbfb8aa3b, v117
	v_or_b32_e32 v116, 48, v170
	v_ashrrev_i32_e32 v191, 31, v190
	v_ashrrev_i32_e32 v175, 31, v174
	v_readlane_b32 s46, v255, 18
	v_readlane_b32 s47, v255, 19
	v_mul_f32_e32 v126, 0xbfb8aa3b, v126
	v_mul_f32_e32 v127, 0xbfb8aa3b, v127
	v_exp_f32_e32 v196, v124
	v_exp_f32_e32 v197, v125
	v_exp_f32_e32 v200, v120
	v_exp_f32_e32 v201, v121
	v_exp_f32_e32 v202, v122
	v_exp_f32_e32 v203, v123
	v_exp_f32_e32 v205, v117
	v_ashrrev_i32_e32 v117, 31, v116
	v_lshlrev_b64 v[120:121], 11, v[170:171]
	v_lshlrev_b64 v[122:123], 10, v[190:191]
	v_lshlrev_b64 v[124:125], 10, v[174:175]
	v_exp_f32_e32 v198, v126
	v_exp_f32_e32 v199, v127
	v_lshlrev_b64 v[126:127], 10, v[116:117]
	v_lshl_add_u64 v[120:121], s[46:47], 0, v[120:121]
	v_lshl_add_u64 v[122:123], v[172:173], 0, v[122:123]
	v_lshl_add_u64 v[124:125], v[172:173], 0, v[124:125]
	v_exp_f32_e32 v204, v128
	v_lshl_add_u64 v[192:193], v[172:173], 0, v[126:127]
	v_lshl_add_u64 v[194:195], v[120:121], 0, v[168:169]
	global_load_dwordx4 v[186:189], v[122:123], off
	global_load_dwordx4 v[136:139], v[122:123], off offset:256
	global_load_dwordx4 v[132:135], v[124:125], off
	global_load_dwordx4 v[128:131], v[124:125], off offset:256
	s_nop 0
	global_load_dwordx4 v[124:127], v[192:193], off
	global_load_dwordx4 v[120:123], v[192:193], off offset:256
	v_add_f32_e32 v192, 1.0, v197
	v_add_f32_e32 v171, 1.0, v196
	v_add_f32_e32 v193, 1.0, v198
	v_add_f32_e32 v196, 1.0, v199
	v_add_f32_e32 v197, 1.0, v200
	v_add_f32_e32 v198, 1.0, v201
	v_add_f32_e32 v200, 1.0, v203
	v_rcp_f32_e32 v192, v192
	v_add_f32_e32 v199, 1.0, v202
	v_rcp_f32_e32 v171, v171
	v_rcp_f32_e32 v196, v196
	v_rcp_f32_e32 v198, v198
	v_rcp_f32_e32 v200, v200
	v_rcp_f32_e32 v193, v193
	v_rcp_f32_e32 v197, v197
	v_rcp_f32_e32 v199, v199
	v_mul_f32_e32 v118, 0xbfb8aa3b, v118
	v_add_f32_e32 v201, 1.0, v204
	v_exp_f32_e32 v118, v118
	v_mul_f32_e32 v119, 0xbfb8aa3b, v119
	v_exp_f32_e32 v119, v119
	v_mul_f32_e32 v112, 0xbfb8aa3b, v112
	v_exp_f32_e32 v112, v112
	v_mul_f32_e32 v113, 0xbfb8aa3b, v113
	v_exp_f32_e32 v113, v113
	v_add_f32_e32 v118, 1.0, v118
	v_rcp_f32_e32 v118, v118
	v_add_f32_e32 v119, 1.0, v119
	v_rcp_f32_e32 v119, v119
	v_add_f32_e32 v112, 1.0, v112
	v_rcp_f32_e32 v112, v112
	v_add_f32_e32 v113, 1.0, v113
	v_mul_f32_e32 v114, 0xbfb8aa3b, v114
	v_rcp_f32_e32 v113, v113
	v_exp_f32_e32 v114, v114
	v_mul_f32_e32 v115, 0xbfb8aa3b, v115
	v_exp_f32_e32 v115, v115
	v_mul_f32_e32 v108, 0xbfb8aa3b, v108
	v_exp_f32_e32 v108, v108
	v_mul_f32_e32 v109, 0xbfb8aa3b, v109
	s_waitcnt vmcnt(0)
; DI unsigned pk2(float lo, float hi) { unsigned r; asm volatile("v_cvt_pk_bf16_f32 %0, %1, %2" : "=v"(r) : "v"(lo), "v"(hi)); return r; }
; DI float bflo(unsigned u) { return __uint_as_float(u << 16); }
; DI float bfhi(unsigned u) { return __uint_as_float(u & 0xffff0000u); }
; DI float sigm(float x) { return __builtin_amdgcn_rcpf(1.f + __expf(-x)); }
;     DI void operator()(const f32x4 (&acc)[2][2][4][2], const Unit& u, int wr, int wc, int fr, int fq, const Pre& pre) const {
;     ...
;                 for (int bj = 0; bj < 2; ++bj) y[m][bj] = *(const u32x4v*)(YG + (size_t)(row0 + ai * 128 + m * 16) * 512 + cb + bj * 128);
; #pragma unroll
;             for (int m = 0; m < 4; ++m) { const int row = row0 + ai * 128 + m * 16;
; #pragma unroll
;                 for (int bj = 0; bj < 2; ++bj) { const f32x4 v0 = acc[ai][bj][m][0], v1 = acc[ai][bj][m][1]; const u32x4v yy = y[m][bj]; u32x4v o;
;                     o.x = pk2(bflo(yy.x) * sigm(v0[0]), bfhi(yy.x) * sigm(v0[1])); o.y = pk2(bflo(yy.y) * sigm(v0[2]), bfhi(yy.y) * sigm(v0[3]));
;                     o.z = pk2(bflo(yy.z) * sigm(v1[0]), bfhi(yy.z) * sigm(v1[1])); o.w = pk2(bflo(yy.w) * sigm(v1[2]), bfhi(yy.w) * sigm(v1[3]));
;                     *(u32x4v*)(CAT + (size_t)row * 1024 + 512 + cb + bj * 128) = o; } } }
	v_lshlrev_b32_e32 v202, 16, v178
	v_and_b32_e32 v178, 0xffff0000, v178
	v_lshlrev_b32_e32 v203, 16, v179
	v_and_b32_e32 v179, 0xffff0000, v179
	v_lshlrev_b32_e32 v204, 16, v180
	v_and_b32_e32 v180, 0xffff0000, v180
	v_lshlrev_b32_e32 v206, 16, v181
	v_and_b32_e32 v181, 0xffff0000, v181
	v_mul_f32_e32 v178, v192, v178
	v_mul_f32_e32 v171, v171, v202
	v_mul_f32_e32 v179, v196, v179
	v_mul_f32_e32 v180, v198, v180
	v_mul_f32_e32 v181, v200, v181
	v_cvt_pk_bf16_f32 v178, v171, v178
	v_mul_f32_e32 v192, v193, v203
	v_mul_f32_e32 v193, v197, v204
	v_mul_f32_e32 v196, v199, v206
	v_cvt_pk_bf16_f32 v179, v192, v179
	v_cvt_pk_bf16_f32 v180, v193, v180
	v_cvt_pk_bf16_f32 v181, v196, v181
	global_store_dwordx4 v[194:195], v[178:181], off offset:1024
	v_rcp_f32_e32 v171, v201
	v_exp_f32_e32 v109, v109
	v_add_f32_e32 v178, 1.0, v205
	v_rcp_f32_e32 v178, v178
	v_lshlrev_b32_e32 v179, 16, v182
	v_mul_f32_e32 v171, v171, v179
	v_and_b32_e32 v179, 0xffff0000, v182
	v_mul_f32_e32 v178, v178, v179
	v_cvt_pk_bf16_f32 v178, v171, v178
	v_lshlrev_b32_e32 v171, 16, v183
	v_mul_f32_e32 v118, v118, v171
	v_and_b32_e32 v171, 0xffff0000, v183
	v_mul_f32_e32 v119, v119, v171
	v_cvt_pk_bf16_f32 v179, v118, v119
	v_lshlrev_b32_e32 v118, 16, v184
	v_mul_f32_e32 v112, v112, v118
	v_and_b32_e32 v118, 0xffff0000, v184
	v_mul_f32_e32 v113, v113, v118
	v_cvt_pk_bf16_f32 v180, v112, v113
	v_add_f32_e32 v112, 1.0, v114
	v_rcp_f32_e32 v112, v112
	v_add_f32_e32 v113, 1.0, v115
	v_rcp_f32_e32 v113, v113
	v_add_f32_e32 v108, 1.0, v108
	v_rcp_f32_e32 v108, v108
	v_add_f32_e32 v109, 1.0, v109
	v_lshlrev_b32_e32 v114, 16, v185
	v_rcp_f32_e32 v109, v109
	v_mul_f32_e32 v110, 0xbfb8aa3b, v110
	v_mul_f32_e32 v112, v112, v114
	v_and_b32_e32 v114, 0xffff0000, v185
	v_exp_f32_e32 v110, v110
	v_mul_f32_e32 v111, 0xbfb8aa3b, v111
	v_mul_f32_e32 v113, v113, v114
	v_lshlrev_b32_e32 v114, 16, v186
	v_exp_f32_e32 v111, v111
	v_mul_f32_e32 v108, v108, v114
	v_and_b32_e32 v114, 0xffff0000, v186
	v_mul_f32_e32 v104, 0xbfb8aa3b, v104
	v_mul_f32_e32 v109, v109, v114
	v_exp_f32_e32 v104, v104
	v_mul_f32_e32 v105, 0xbfb8aa3b, v105
	v_cvt_pk_bf16_f32 v181, v112, v113
	global_store_dwordx4 v[194:195], v[178:181], off offset:1280
	v_cvt_pk_bf16_f32 v108, v108, v109
	v_add_f32_e32 v109, 1.0, v110
	v_exp_f32_e32 v105, v105
	v_rcp_f32_e32 v109, v109
	v_add_f32_e32 v110, 1.0, v111
	v_rcp_f32_e32 v110, v110
	v_add_f32_e32 v104, 1.0, v104
	v_lshlrev_b32_e32 v111, 16, v187
	v_rcp_f32_e32 v104, v104
	v_add_f32_e32 v105, 1.0, v105
	v_mul_f32_e32 v106, 0xbfb8aa3b, v106
	v_mul_f32_e32 v109, v109, v111
	v_and_b32_e32 v111, 0xffff0000, v187
	v_rcp_f32_e32 v105, v105
	v_exp_f32_e32 v106, v106
	v_mul_f32_e32 v107, 0xbfb8aa3b, v107
	v_mul_f32_e32 v110, v110, v111
	v_exp_f32_e32 v107, v107
	v_mul_f32_e32 v100, 0xbfb8aa3b, v100
	v_cvt_pk_bf16_f32 v109, v109, v110
	v_lshlrev_b32_e32 v110, 16, v188
	v_exp_f32_e32 v100, v100
	v_mul_f32_e32 v101, 0xbfb8aa3b, v101
	v_mul_f32_e32 v104, v104, v110
	v_and_b32_e32 v110, 0xffff0000, v188
	v_exp_f32_e32 v101, v101
	v_mul_f32_e32 v105, v105, v110
	v_cvt_pk_bf16_f32 v110, v104, v105
	v_add_f32_e32 v104, 1.0, v106
	v_rcp_f32_e32 v104, v104
	v_add_f32_e32 v105, 1.0, v107
	v_rcp_f32_e32 v105, v105
	v_add_f32_e32 v100, 1.0, v100
	v_rcp_f32_e32 v100, v100
	v_add_f32_e32 v101, 1.0, v101
	v_lshlrev_b32_e32 v106, 16, v189
	v_rcp_f32_e32 v101, v101
	v_mul_f32_e32 v102, 0xbfb8aa3b, v102
	v_mul_f32_e32 v104, v104, v106
	v_and_b32_e32 v106, 0xffff0000, v189
	v_exp_f32_e32 v102, v102
	v_mul_f32_e32 v103, 0xbfb8aa3b, v103
	v_lshlrev_b64 v[112:113], 11, v[190:191]
	v_mul_f32_e32 v105, v105, v106
	v_lshlrev_b32_e32 v106, 16, v136
	v_exp_f32_e32 v103, v103
	v_cvt_pk_bf16_f32 v111, v104, v105
	v_lshl_add_u64 v[104:105], s[46:47], 0, v[112:113]
	v_mul_f32_e32 v100, v100, v106
	v_and_b32_e32 v106, 0xffff0000, v136
	v_mul_f32_e32 v96, 0xbfb8aa3b, v96
	v_lshl_add_u64 v[104:105], v[104:105], 0, v[168:169]
	v_mul_f32_e32 v101, v101, v106
	v_exp_f32_e32 v96, v96
	v_mul_f32_e32 v97, 0xbfb8aa3b, v97
	global_store_dwordx4 v[104:105], v[108:111], off offset:1024
	v_cvt_pk_bf16_f32 v100, v100, v101
	v_add_f32_e32 v101, 1.0, v102
	v_exp_f32_e32 v97, v97
	v_rcp_f32_e32 v101, v101
	v_add_f32_e32 v102, 1.0, v103
	v_rcp_f32_e32 v102, v102
	v_add_f32_e32 v96, 1.0, v96
	v_lshlrev_b32_e32 v103, 16, v137
	v_rcp_f32_e32 v96, v96
	v_add_f32_e32 v97, 1.0, v97
	v_mul_f32_e32 v98, 0xbfb8aa3b, v98
	v_mul_f32_e32 v101, v101, v103
	v_and_b32_e32 v103, 0xffff0000, v137
	v_rcp_f32_e32 v97, v97
	v_exp_f32_e32 v98, v98
	v_mul_f32_e32 v99, 0xbfb8aa3b, v99
	v_mul_f32_e32 v102, v102, v103
	v_exp_f32_e32 v99, v99
	v_mul_f32_e32 v92, 0xbfb8aa3b, v92
	v_cvt_pk_bf16_f32 v101, v101, v102
	v_lshlrev_b32_e32 v102, 16, v138
	v_exp_f32_e32 v92, v92
	v_mul_f32_e32 v93, 0xbfb8aa3b, v93
	v_mul_f32_e32 v96, v96, v102
	v_and_b32_e32 v102, 0xffff0000, v138
	v_exp_f32_e32 v93, v93
	v_mul_f32_e32 v97, v97, v102
	v_cvt_pk_bf16_f32 v102, v96, v97
	v_add_f32_e32 v96, 1.0, v98
	v_rcp_f32_e32 v96, v96
	v_add_f32_e32 v97, 1.0, v99
	v_rcp_f32_e32 v97, v97
	v_add_f32_e32 v92, 1.0, v92
	v_rcp_f32_e32 v92, v92
	v_add_f32_e32 v93, 1.0, v93
	v_lshlrev_b32_e32 v98, 16, v139
	v_rcp_f32_e32 v93, v93
	v_mul_f32_e32 v94, 0xbfb8aa3b, v94
	v_mul_f32_e32 v96, v96, v98
	v_and_b32_e32 v98, 0xffff0000, v139
	v_exp_f32_e32 v94, v94
	v_mul_f32_e32 v95, 0xbfb8aa3b, v95
	v_mul_f32_e32 v97, v97, v98
	v_lshlrev_b32_e32 v98, 16, v132
	v_exp_f32_e32 v95, v95
	v_mul_f32_e32 v92, v92, v98
	v_and_b32_e32 v98, 0xffff0000, v132
	v_mul_f32_e32 v88, 0xbfb8aa3b, v88
	v_mul_f32_e32 v93, v93, v98
	v_exp_f32_e32 v88, v88
	v_mul_f32_e32 v89, 0xbfb8aa3b, v89
	v_cvt_pk_bf16_f32 v103, v96, v97
; DI unsigned pk2(float lo, float hi) { unsigned r; asm volatile("v_cvt_pk_bf16_f32 %0, %1, %2" : "=v"(r) : "v"(lo), "v"(hi)); return r; }
; DI float bflo(unsigned u) { return __uint_as_float(u << 16); }
; DI float bfhi(unsigned u) { return __uint_as_float(u & 0xffff0000u); }
; DI float sigm(float x) { return __builtin_amdgcn_rcpf(1.f + __expf(-x)); }
;     DI void operator()(const f32x4 (&acc)[2][2][4][2], const Unit& u, int wr, int wc, int fr, int fq, const Pre& pre) const {
;     ...
;                 for (int bj = 0; bj < 2; ++bj) y[m][bj] = *(const u32x4v*)(YG + (size_t)(row0 + ai * 128 + m * 16) * 512 + cb + bj * 128);
; #pragma unroll
;             for (int m = 0; m < 4; ++m) { const int row = row0 + ai * 128 + m * 16;
; #pragma unroll
;                 for (int bj = 0; bj < 2; ++bj) { const f32x4 v0 = acc[ai][bj][m][0], v1 = acc[ai][bj][m][1]; const u32x4v yy = y[m][bj]; u32x4v o;
;                     o.x = pk2(bflo(yy.x) * sigm(v0[0]), bfhi(yy.x) * sigm(v0[1])); o.y = pk2(bflo(yy.y) * sigm(v0[2]), bfhi(yy.y) * sigm(v0[3]));
;                     o.z = pk2(bflo(yy.z) * sigm(v1[0]), bfhi(yy.z) * sigm(v1[1])); o.w = pk2(bflo(yy.w) * sigm(v1[2]), bfhi(yy.w) * sigm(v1[3]));
;                     *(u32x4v*)(CAT + (size_t)row * 1024 + 512 + cb + bj * 128) = o; } } }
	global_store_dwordx4 v[104:105], v[100:103], off offset:1280
	v_cvt_pk_bf16_f32 v92, v92, v93
	v_add_f32_e32 v93, 1.0, v94
	v_exp_f32_e32 v89, v89
	v_rcp_f32_e32 v93, v93
	v_add_f32_e32 v94, 1.0, v95
	v_rcp_f32_e32 v94, v94
	v_add_f32_e32 v88, 1.0, v88
	v_lshlrev_b32_e32 v95, 16, v133
	v_rcp_f32_e32 v88, v88
	v_add_f32_e32 v89, 1.0, v89
	v_mul_f32_e32 v90, 0xbfb8aa3b, v90
	v_mul_f32_e32 v93, v93, v95
	v_and_b32_e32 v95, 0xffff0000, v133
	v_rcp_f32_e32 v89, v89
	v_exp_f32_e32 v90, v90
	v_mul_f32_e32 v91, 0xbfb8aa3b, v91
	v_mul_f32_e32 v94, v94, v95
	v_exp_f32_e32 v91, v91
	v_mul_f32_e32 v84, 0xbfb8aa3b, v84
	v_cvt_pk_bf16_f32 v93, v93, v94
	v_lshlrev_b32_e32 v94, 16, v134
	v_exp_f32_e32 v84, v84
	v_mul_f32_e32 v85, 0xbfb8aa3b, v85
	v_mul_f32_e32 v88, v88, v94
	v_and_b32_e32 v94, 0xffff0000, v134
	v_exp_f32_e32 v85, v85
	v_mul_f32_e32 v89, v89, v94
	v_cvt_pk_bf16_f32 v94, v88, v89
	v_add_f32_e32 v88, 1.0, v90
	v_rcp_f32_e32 v88, v88
	v_add_f32_e32 v89, 1.0, v91
	v_rcp_f32_e32 v89, v89
	v_add_f32_e32 v84, 1.0, v84
	v_rcp_f32_e32 v84, v84
	v_add_f32_e32 v85, 1.0, v85
	v_lshlrev_b32_e32 v90, 16, v135
	v_rcp_f32_e32 v85, v85
	v_mul_f32_e32 v86, 0xbfb8aa3b, v86
	v_mul_f32_e32 v88, v88, v90
	v_and_b32_e32 v90, 0xffff0000, v135
	v_exp_f32_e32 v86, v86
	v_mul_f32_e32 v87, 0xbfb8aa3b, v87
	v_lshlrev_b64 v[96:97], 11, v[174:175]
	v_mul_f32_e32 v89, v89, v90
	v_lshlrev_b32_e32 v90, 16, v128
	v_exp_f32_e32 v87, v87
	v_cvt_pk_bf16_f32 v95, v88, v89
	v_lshl_add_u64 v[88:89], s[46:47], 0, v[96:97]
	v_mul_f32_e32 v84, v84, v90
	v_and_b32_e32 v90, 0xffff0000, v128
	v_mul_f32_e32 v80, 0xbfb8aa3b, v80
	v_lshl_add_u64 v[88:89], v[88:89], 0, v[168:169]
	v_mul_f32_e32 v85, v85, v90
	v_exp_f32_e32 v80, v80
	v_mul_f32_e32 v81, 0xbfb8aa3b, v81
	global_store_dwordx4 v[88:89], v[92:95], off offset:1024
	v_cvt_pk_bf16_f32 v84, v84, v85
	v_add_f32_e32 v85, 1.0, v86
	v_exp_f32_e32 v81, v81
	v_rcp_f32_e32 v85, v85
	v_add_f32_e32 v86, 1.0, v87
	v_rcp_f32_e32 v86, v86
	v_add_f32_e32 v80, 1.0, v80
	v_lshlrev_b32_e32 v87, 16, v129
	v_rcp_f32_e32 v80, v80
	v_add_f32_e32 v81, 1.0, v81
	v_mul_f32_e32 v82, 0xbfb8aa3b, v82
	v_mul_f32_e32 v85, v85, v87
	v_and_b32_e32 v87, 0xffff0000, v129
	v_rcp_f32_e32 v81, v81
	v_exp_f32_e32 v82, v82
	v_mul_f32_e32 v83, 0xbfb8aa3b, v83
	v_mul_f32_e32 v86, v86, v87
	v_exp_f32_e32 v83, v83
	v_mul_f32_e32 v76, 0xbfb8aa3b, v76
	v_cvt_pk_bf16_f32 v85, v85, v86
	v_lshlrev_b32_e32 v86, 16, v130
	v_exp_f32_e32 v76, v76
	v_mul_f32_e32 v77, 0xbfb8aa3b, v77
	v_mul_f32_e32 v80, v80, v86
	v_and_b32_e32 v86, 0xffff0000, v130
	v_exp_f32_e32 v77, v77
	v_mul_f32_e32 v81, v81, v86
	v_cvt_pk_bf16_f32 v86, v80, v81
	v_add_f32_e32 v80, 1.0, v82
	v_rcp_f32_e32 v80, v80
	v_add_f32_e32 v81, 1.0, v83
	v_rcp_f32_e32 v81, v81
	v_add_f32_e32 v76, 1.0, v76
	v_rcp_f32_e32 v76, v76
	v_add_f32_e32 v77, 1.0, v77
	v_lshlrev_b32_e32 v82, 16, v131
	v_rcp_f32_e32 v77, v77
	v_mul_f32_e32 v78, 0xbfb8aa3b, v78
	v_mul_f32_e32 v80, v80, v82
	v_and_b32_e32 v82, 0xffff0000, v131
	v_exp_f32_e32 v78, v78
	v_mul_f32_e32 v79, 0xbfb8aa3b, v79
	v_mul_f32_e32 v81, v81, v82
	v_lshlrev_b32_e32 v82, 16, v124
	v_exp_f32_e32 v79, v79
	v_mul_f32_e32 v76, v76, v82
	v_and_b32_e32 v82, 0xffff0000, v124
	v_mul_f32_e32 v72, 0xbfb8aa3b, v72
	v_mul_f32_e32 v77, v77, v82
	v_exp_f32_e32 v72, v72
	v_mul_f32_e32 v73, 0xbfb8aa3b, v73
	v_cvt_pk_bf16_f32 v87, v80, v81
	global_store_dwordx4 v[88:89], v[84:87], off offset:1280
	v_cvt_pk_bf16_f32 v76, v76, v77
	v_add_f32_e32 v77, 1.0, v78
	v_exp_f32_e32 v73, v73
	v_rcp_f32_e32 v77, v77
	v_add_f32_e32 v78, 1.0, v79
	v_rcp_f32_e32 v78, v78
	v_add_f32_e32 v72, 1.0, v72
	v_lshlrev_b32_e32 v79, 16, v125
	v_rcp_f32_e32 v72, v72
	v_add_f32_e32 v73, 1.0, v73
	v_mul_f32_e32 v74, 0xbfb8aa3b, v74
	v_mul_f32_e32 v77, v77, v79
	v_and_b32_e32 v79, 0xffff0000, v125
	v_rcp_f32_e32 v73, v73
	v_exp_f32_e32 v74, v74
	v_mul_f32_e32 v75, 0xbfb8aa3b, v75
	v_mul_f32_e32 v78, v78, v79
	v_exp_f32_e32 v75, v75
	v_mul_f32_e32 v68, 0xbfb8aa3b, v68
	v_cvt_pk_bf16_f32 v77, v77, v78
	v_lshlrev_b32_e32 v78, 16, v126
	v_exp_f32_e32 v68, v68
	v_mul_f32_e32 v69, 0xbfb8aa3b, v69
	v_mul_f32_e32 v72, v72, v78
	v_and_b32_e32 v78, 0xffff0000, v126
	v_exp_f32_e32 v69, v69
	v_mul_f32_e32 v73, v73, v78
	v_cvt_pk_bf16_f32 v78, v72, v73
	v_add_f32_e32 v72, 1.0, v74
	v_rcp_f32_e32 v72, v72
	v_add_f32_e32 v73, 1.0, v75
	v_rcp_f32_e32 v73, v73
	v_add_f32_e32 v68, 1.0, v68
	v_rcp_f32_e32 v68, v68
	v_add_f32_e32 v69, 1.0, v69
	v_lshlrev_b32_e32 v74, 16, v127
	v_rcp_f32_e32 v69, v69
	v_mul_f32_e32 v70, 0xbfb8aa3b, v70
	v_mul_f32_e32 v72, v72, v74
	v_and_b32_e32 v74, 0xffff0000, v127
	v_exp_f32_e32 v70, v70
	v_mul_f32_e32 v71, 0xbfb8aa3b, v71
	v_lshlrev_b64 v[80:81], 11, v[116:117]
	v_mul_f32_e32 v73, v73, v74
	v_lshlrev_b32_e32 v74, 16, v120
	v_exp_f32_e32 v71, v71
	v_cvt_pk_bf16_f32 v79, v72, v73
	v_lshl_add_u64 v[72:73], s[46:47], 0, v[80:81]
	v_mul_f32_e32 v68, v68, v74
	v_and_b32_e32 v74, 0xffff0000, v120
	v_mul_f32_e32 v64, 0xbfb8aa3b, v64
	v_lshl_add_u64 v[72:73], v[72:73], 0, v[168:169]
	v_mul_f32_e32 v69, v69, v74
	v_exp_f32_e32 v64, v64
	v_mul_f32_e32 v65, 0xbfb8aa3b, v65
	global_store_dwordx4 v[72:73], v[76:79], off offset:1024
	v_cvt_pk_bf16_f32 v68, v68, v69
	v_add_f32_e32 v69, 1.0, v70
	v_exp_f32_e32 v65, v65
	v_rcp_f32_e32 v69, v69
	v_add_f32_e32 v70, 1.0, v71
	v_rcp_f32_e32 v70, v70
	v_add_f32_e32 v64, 1.0, v64
	v_lshlrev_b32_e32 v71, 16, v121
	v_rcp_f32_e32 v64, v64
	v_add_f32_e32 v65, 1.0, v65
	v_mul_f32_e32 v66, 0xbfb8aa3b, v66
	v_mul_f32_e32 v69, v69, v71
	v_and_b32_e32 v71, 0xffff0000, v121
	v_rcp_f32_e32 v65, v65
	v_exp_f32_e32 v66, v66
	v_mul_f32_e32 v67, 0xbfb8aa3b, v67
	v_mul_f32_e32 v70, v70, v71
; DI unsigned pk2(float lo, float hi) { unsigned r; asm volatile("v_cvt_pk_bf16_f32 %0, %1, %2" : "=v"(r) : "v"(lo), "v"(hi)); return r; }
; DI float bflo(unsigned u) { return __uint_as_float(u << 16); }
; DI float bfhi(unsigned u) { return __uint_as_float(u & 0xffff0000u); }
; DI float sigm(float x) { return __builtin_amdgcn_rcpf(1.f + __expf(-x)); }
;     DI void operator()(const f32x4 (&acc)[2][2][4][2], const Unit& u, int wr, int wc, int fr, int fq, const Pre& pre) const {
;     ...
;                 for (int bj = 0; bj < 2; ++bj) y[m][bj] = *(const u32x4v*)(YG + (size_t)(row0 + ai * 128 + m * 16) * 512 + cb + bj * 128);
; #pragma unroll
;             for (int m = 0; m < 4; ++m) { const int row = row0 + ai * 128 + m * 16;
; #pragma unroll
;                 for (int bj = 0; bj < 2; ++bj) { const f32x4 v0 = acc[ai][bj][m][0], v1 = acc[ai][bj][m][1]; const u32x4v yy = y[m][bj]; u32x4v o;
;                     o.x = pk2(bflo(yy.x) * sigm(v0[0]), bfhi(yy.x) * sigm(v0[1])); o.y = pk2(bflo(yy.y) * sigm(v0[2]), bfhi(yy.y) * sigm(v0[3]));
;                     o.z = pk2(bflo(yy.z) * sigm(v1[0]), bfhi(yy.z) * sigm(v1[1])); o.w = pk2(bflo(yy.w) * sigm(v1[2]), bfhi(yy.w) * sigm(v1[3]));
;                     *(u32x4v*)(CAT + (size_t)row * 1024 + 512 + cb + bj * 128) = o; } } }
	v_exp_f32_e32 v67, v67
	v_cvt_pk_bf16_f32 v69, v69, v70
	v_lshlrev_b32_e32 v70, 16, v122
	v_mul_f32_e32 v64, v64, v70
	v_and_b32_e32 v70, 0xffff0000, v122
	v_mul_f32_e32 v65, v65, v70
	v_cvt_pk_bf16_f32 v70, v64, v65
	v_add_f32_e32 v64, 1.0, v66
	v_rcp_f32_e32 v64, v64
	v_add_f32_e32 v65, 1.0, v67
	v_rcp_f32_e32 v65, v65
	v_lshlrev_b32_e32 v66, 16, v123
	v_mul_f32_e32 v64, v64, v66
	v_and_b32_e32 v66, 0xffff0000, v123
	v_add_u32_e32 v100, 0x80, v170
	v_mul_f32_e32 v65, v65, v66
	v_ashrrev_i32_e32 v101, 31, v100
	v_cvt_pk_bf16_f32 v71, v64, v65
	v_lshlrev_b64 v[64:65], 10, v[100:101]
	global_store_dwordx4 v[72:73], v[68:71], off offset:1280
	v_lshl_add_u64 v[64:65], v[172:173], 0, v[64:65]
	global_load_dwordx4 v[92:95], v[64:65], off
	global_load_dwordx4 v[96:99], v[64:65], off offset:256
	v_add_u32_e32 v102, 0x90, v170
	v_ashrrev_i32_e32 v103, 31, v102
	v_lshlrev_b64 v[64:65], 10, v[102:103]
	v_lshl_add_u64 v[64:65], v[172:173], 0, v[64:65]
	global_load_dwordx4 v[84:87], v[64:65], off
	global_load_dwordx4 v[80:83], v[64:65], off offset:256
	v_add_u32_e32 v90, 0xa0, v170
	v_ashrrev_i32_e32 v91, 31, v90
	v_lshlrev_b64 v[64:65], 10, v[90:91]
	v_lshl_add_u64 v[64:65], v[172:173], 0, v[64:65]
	v_mul_f32_e32 v60, 0xbfb8aa3b, v60
	v_mul_f32_e32 v61, 0xbfb8aa3b, v61
	global_load_dwordx4 v[76:79], v[64:65], off
	global_load_dwordx4 v[72:75], v[64:65], off offset:256
	v_exp_f32_e32 v60, v60
	v_exp_f32_e32 v61, v61
	v_mul_f32_e32 v62, 0xbfb8aa3b, v62
	v_add_u32_e32 v88, 0xb0, v170
	v_add_f32_e32 v60, 1.0, v60
	v_add_f32_e32 v61, 1.0, v61
	v_rcp_f32_e32 v60, v60
	v_rcp_f32_e32 v61, v61
	v_exp_f32_e32 v62, v62
	v_mul_f32_e32 v63, 0xbfb8aa3b, v63
	v_ashrrev_i32_e32 v89, 31, v88
	v_exp_f32_e32 v63, v63
	v_lshlrev_b64 v[64:65], 10, v[88:89]
	v_mul_f32_e32 v56, 0xbfb8aa3b, v56
	v_lshl_add_u64 v[64:65], v[172:173], 0, v[64:65]
	v_exp_f32_e32 v56, v56
	v_mul_f32_e32 v57, 0xbfb8aa3b, v57
	global_load_dwordx4 v[68:71], v[64:65], off
	s_nop 0
	global_load_dwordx4 v[64:67], v[64:65], off offset:256
	v_exp_f32_e32 v57, v57
	v_add_f32_e32 v56, 1.0, v56
	v_rcp_f32_e32 v56, v56
	v_mul_f32_e32 v58, 0xbfb8aa3b, v58
	v_add_f32_e32 v57, 1.0, v57
	v_rcp_f32_e32 v57, v57
	v_exp_f32_e32 v58, v58
	v_mul_f32_e32 v59, 0xbfb8aa3b, v59
	v_exp_f32_e32 v59, v59
	v_mul_f32_e32 v52, 0xbfb8aa3b, v52
	v_exp_f32_e32 v52, v52
	v_mul_f32_e32 v53, 0xbfb8aa3b, v53
	v_exp_f32_e32 v53, v53
	v_mul_f32_e32 v54, 0xbfb8aa3b, v54
	v_add_f32_e32 v52, 1.0, v52
	v_rcp_f32_e32 v52, v52
	v_add_f32_e32 v53, 1.0, v53
	v_rcp_f32_e32 v53, v53
	v_exp_f32_e32 v54, v54
	v_mul_f32_e32 v55, 0xbfb8aa3b, v55
	v_lshlrev_b64 v[100:101], 11, v[100:101]
	v_exp_f32_e32 v55, v55
	v_mul_f32_e32 v48, 0xbfb8aa3b, v48
	v_exp_f32_e32 v48, v48
	v_mul_f32_e32 v49, 0xbfb8aa3b, v49
	v_exp_f32_e32 v49, v49
	v_mul_f32_e32 v50, 0xbfb8aa3b, v50
	v_add_f32_e32 v48, 1.0, v48
	v_rcp_f32_e32 v48, v48
	v_add_f32_e32 v49, 1.0, v49
	v_rcp_f32_e32 v49, v49
	v_exp_f32_e32 v50, v50
	v_mul_f32_e32 v51, 0xbfb8aa3b, v51
	v_exp_f32_e32 v51, v51
	v_mul_f32_e32 v44, 0xbfb8aa3b, v44
	v_exp_f32_e32 v44, v44
	v_mul_f32_e32 v45, 0xbfb8aa3b, v45
	v_exp_f32_e32 v45, v45
	v_mul_f32_e32 v46, 0xbfb8aa3b, v46
	v_add_f32_e32 v44, 1.0, v44
	v_rcp_f32_e32 v44, v44
	v_add_f32_e32 v45, 1.0, v45
	v_rcp_f32_e32 v45, v45
	v_exp_f32_e32 v46, v46
	v_mul_f32_e32 v47, 0xbfb8aa3b, v47
	v_exp_f32_e32 v47, v47
	v_mul_f32_e32 v40, 0xbfb8aa3b, v40
	v_exp_f32_e32 v40, v40
	s_waitcnt vmcnt(0)
	v_lshlrev_b32_e32 v104, 16, v92
	v_and_b32_e32 v92, 0xffff0000, v92
	v_mul_f32_e32 v60, v60, v104
	v_mul_f32_e32 v61, v61, v92
	v_cvt_pk_bf16_f32 v60, v60, v61
	v_add_f32_e32 v61, 1.0, v62
	v_rcp_f32_e32 v61, v61
	v_add_f32_e32 v62, 1.0, v63
	v_rcp_f32_e32 v62, v62
	v_lshlrev_b32_e32 v63, 16, v93
	v_mul_f32_e32 v61, v61, v63
	v_and_b32_e32 v63, 0xffff0000, v93
	v_mul_f32_e32 v62, v62, v63
	v_cvt_pk_bf16_f32 v61, v61, v62
	v_lshlrev_b32_e32 v62, 16, v94
	v_mul_f32_e32 v56, v56, v62
	v_and_b32_e32 v62, 0xffff0000, v94
	v_mul_f32_e32 v57, v57, v62
	v_cvt_pk_bf16_f32 v62, v56, v57
	v_add_f32_e32 v56, 1.0, v58
	v_rcp_f32_e32 v56, v56
	v_add_f32_e32 v57, 1.0, v59
	v_rcp_f32_e32 v57, v57
	v_lshlrev_b32_e32 v58, 16, v95
	v_mul_f32_e32 v56, v56, v58
	v_and_b32_e32 v58, 0xffff0000, v95
	v_mul_f32_e32 v57, v57, v58
	v_lshlrev_b32_e32 v58, 16, v96
	v_cvt_pk_bf16_f32 v63, v56, v57
	v_lshl_add_u64 v[56:57], s[46:47], 0, v[100:101]
	v_mul_f32_e32 v52, v52, v58
	v_and_b32_e32 v58, 0xffff0000, v96
	v_lshl_add_u64 v[56:57], v[56:57], 0, v[168:169]
	v_mul_f32_e32 v53, v53, v58
	global_store_dwordx4 v[56:57], v[60:63], off offset:1024
	v_cvt_pk_bf16_f32 v52, v52, v53
	v_add_f32_e32 v53, 1.0, v54
	v_rcp_f32_e32 v53, v53
	v_add_f32_e32 v54, 1.0, v55
	v_rcp_f32_e32 v54, v54
	v_lshlrev_b32_e32 v55, 16, v97
	v_mul_f32_e32 v53, v53, v55
	v_and_b32_e32 v55, 0xffff0000, v97
	v_mul_f32_e32 v54, v54, v55
	v_cvt_pk_bf16_f32 v53, v53, v54
	v_lshlrev_b32_e32 v54, 16, v98
	v_mul_f32_e32 v48, v48, v54
	v_and_b32_e32 v54, 0xffff0000, v98
	v_mul_f32_e32 v49, v49, v54
	v_cvt_pk_bf16_f32 v54, v48, v49
	v_add_f32_e32 v48, 1.0, v50
	v_rcp_f32_e32 v48, v48
	v_add_f32_e32 v49, 1.0, v51
	v_rcp_f32_e32 v49, v49
	v_lshlrev_b32_e32 v50, 16, v99
	v_mul_f32_e32 v48, v48, v50
	v_and_b32_e32 v50, 0xffff0000, v99
	v_mul_f32_e32 v49, v49, v50
	v_lshlrev_b32_e32 v50, 16, v84
	v_mul_f32_e32 v44, v44, v50
	v_and_b32_e32 v50, 0xffff0000, v84
	v_mul_f32_e32 v45, v45, v50
	v_mul_f32_e32 v41, 0xbfb8aa3b, v41
	v_cvt_pk_bf16_f32 v55, v48, v49
	global_store_dwordx4 v[56:57], v[52:55], off offset:1280
	v_cvt_pk_bf16_f32 v44, v44, v45
	v_add_f32_e32 v45, 1.0, v46
	v_exp_f32_e32 v41, v41
	v_rcp_f32_e32 v45, v45
	v_add_f32_e32 v46, 1.0, v47
; DI unsigned pk2(float lo, float hi) { unsigned r; asm volatile("v_cvt_pk_bf16_f32 %0, %1, %2" : "=v"(r) : "v"(lo), "v"(hi)); return r; }
; DI float bflo(unsigned u) { return __uint_as_float(u << 16); }
; DI float bfhi(unsigned u) { return __uint_as_float(u & 0xffff0000u); }
; DI float sigm(float x) { return __builtin_amdgcn_rcpf(1.f + __expf(-x)); }
;     DI void operator()(const f32x4 (&acc)[2][2][4][2], const Unit& u, int wr, int wc, int fr, int fq, const Pre& pre) const {
;     ...
;                 for (int bj = 0; bj < 2; ++bj) y[m][bj] = *(const u32x4v*)(YG + (size_t)(row0 + ai * 128 + m * 16) * 512 + cb + bj * 128);
; #pragma unroll
;             for (int m = 0; m < 4; ++m) { const int row = row0 + ai * 128 + m * 16;
; #pragma unroll
;                 for (int bj = 0; bj < 2; ++bj) { const f32x4 v0 = acc[ai][bj][m][0], v1 = acc[ai][bj][m][1]; const u32x4v yy = y[m][bj]; u32x4v o;
;                     o.x = pk2(bflo(yy.x) * sigm(v0[0]), bfhi(yy.x) * sigm(v0[1])); o.y = pk2(bflo(yy.y) * sigm(v0[2]), bfhi(yy.y) * sigm(v0[3]));
;                     o.z = pk2(bflo(yy.z) * sigm(v1[0]), bfhi(yy.z) * sigm(v1[1])); o.w = pk2(bflo(yy.w) * sigm(v1[2]), bfhi(yy.w) * sigm(v1[3]));
;                     *(u32x4v*)(CAT + (size_t)row * 1024 + 512 + cb + bj * 128) = o; } } }
	v_rcp_f32_e32 v46, v46
	v_add_f32_e32 v40, 1.0, v40
	v_lshlrev_b32_e32 v47, 16, v85
	v_rcp_f32_e32 v40, v40
	v_add_f32_e32 v41, 1.0, v41
	v_mul_f32_e32 v42, 0xbfb8aa3b, v42
	v_mul_f32_e32 v45, v45, v47
	v_and_b32_e32 v47, 0xffff0000, v85
	v_rcp_f32_e32 v41, v41
	v_exp_f32_e32 v42, v42
	v_mul_f32_e32 v43, 0xbfb8aa3b, v43
	v_mul_f32_e32 v46, v46, v47
	v_exp_f32_e32 v43, v43
	v_mul_f32_e32 v36, 0xbfb8aa3b, v36
	v_cvt_pk_bf16_f32 v45, v45, v46
	v_lshlrev_b32_e32 v46, 16, v86
	v_exp_f32_e32 v36, v36
	v_mul_f32_e32 v37, 0xbfb8aa3b, v37
	v_mul_f32_e32 v40, v40, v46
	v_and_b32_e32 v46, 0xffff0000, v86
	v_exp_f32_e32 v37, v37
	v_mul_f32_e32 v41, v41, v46
	v_cvt_pk_bf16_f32 v46, v40, v41
	v_add_f32_e32 v40, 1.0, v42
	v_rcp_f32_e32 v40, v40
	v_add_f32_e32 v41, 1.0, v43
	v_rcp_f32_e32 v41, v41
	v_add_f32_e32 v36, 1.0, v36
	v_rcp_f32_e32 v36, v36
	v_add_f32_e32 v37, 1.0, v37
	v_lshlrev_b32_e32 v42, 16, v87
	v_rcp_f32_e32 v37, v37
	v_mul_f32_e32 v38, 0xbfb8aa3b, v38
	v_mul_f32_e32 v40, v40, v42
	v_and_b32_e32 v42, 0xffff0000, v87
	v_exp_f32_e32 v38, v38
	v_mul_f32_e32 v39, 0xbfb8aa3b, v39
	v_lshlrev_b64 v[48:49], 11, v[102:103]
	v_mul_f32_e32 v41, v41, v42
	v_lshlrev_b32_e32 v42, 16, v80
	v_exp_f32_e32 v39, v39
	v_cvt_pk_bf16_f32 v47, v40, v41
	v_lshl_add_u64 v[40:41], s[46:47], 0, v[48:49]
	v_mul_f32_e32 v36, v36, v42
	v_and_b32_e32 v42, 0xffff0000, v80
	v_mul_f32_e32 v32, 0xbfb8aa3b, v32
	v_lshl_add_u64 v[40:41], v[40:41], 0, v[168:169]
	v_mul_f32_e32 v37, v37, v42
	v_exp_f32_e32 v32, v32
	v_mul_f32_e32 v33, 0xbfb8aa3b, v33
	global_store_dwordx4 v[40:41], v[44:47], off offset:1024
	v_cvt_pk_bf16_f32 v36, v36, v37
	v_add_f32_e32 v37, 1.0, v38
	v_exp_f32_e32 v33, v33
	v_rcp_f32_e32 v37, v37
	v_add_f32_e32 v38, 1.0, v39
	v_rcp_f32_e32 v38, v38
	v_add_f32_e32 v32, 1.0, v32
	v_lshlrev_b32_e32 v39, 16, v81
	v_rcp_f32_e32 v32, v32
	v_add_f32_e32 v33, 1.0, v33
	v_mul_f32_e32 v34, 0xbfb8aa3b, v34
	v_mul_f32_e32 v37, v37, v39
	v_and_b32_e32 v39, 0xffff0000, v81
	v_rcp_f32_e32 v33, v33
	v_exp_f32_e32 v34, v34
	v_mul_f32_e32 v35, 0xbfb8aa3b, v35
	v_mul_f32_e32 v38, v38, v39
	v_exp_f32_e32 v35, v35
	v_mul_f32_e32 v28, 0xbfb8aa3b, v28
	v_cvt_pk_bf16_f32 v37, v37, v38
	v_lshlrev_b32_e32 v38, 16, v82
	v_exp_f32_e32 v28, v28
	v_mul_f32_e32 v29, 0xbfb8aa3b, v29
	v_mul_f32_e32 v32, v32, v38
	v_and_b32_e32 v38, 0xffff0000, v82
	v_exp_f32_e32 v29, v29
	v_mul_f32_e32 v33, v33, v38
	v_cvt_pk_bf16_f32 v38, v32, v33
	v_add_f32_e32 v32, 1.0, v34
	v_rcp_f32_e32 v32, v32
	v_add_f32_e32 v33, 1.0, v35
	v_rcp_f32_e32 v33, v33
	v_add_f32_e32 v28, 1.0, v28
	v_rcp_f32_e32 v28, v28
	v_add_f32_e32 v29, 1.0, v29
	v_lshlrev_b32_e32 v34, 16, v83
	v_rcp_f32_e32 v29, v29
	v_mul_f32_e32 v30, 0xbfb8aa3b, v30
	v_mul_f32_e32 v32, v32, v34
	v_and_b32_e32 v34, 0xffff0000, v83
	v_exp_f32_e32 v30, v30
	v_mul_f32_e32 v31, 0xbfb8aa3b, v31
	v_mul_f32_e32 v33, v33, v34
	v_lshlrev_b32_e32 v34, 16, v76
	v_exp_f32_e32 v31, v31
	v_mul_f32_e32 v28, v28, v34
	v_and_b32_e32 v34, 0xffff0000, v76
	v_mul_f32_e32 v24, 0xbfb8aa3b, v24
	v_mul_f32_e32 v29, v29, v34
	v_exp_f32_e32 v24, v24
	v_mul_f32_e32 v25, 0xbfb8aa3b, v25
	v_cvt_pk_bf16_f32 v39, v32, v33
	global_store_dwordx4 v[40:41], v[36:39], off offset:1280
	v_cvt_pk_bf16_f32 v28, v28, v29
	v_add_f32_e32 v29, 1.0, v30
	v_exp_f32_e32 v25, v25
	v_rcp_f32_e32 v29, v29
	v_add_f32_e32 v30, 1.0, v31
	v_rcp_f32_e32 v30, v30
	v_add_f32_e32 v24, 1.0, v24
	v_lshlrev_b32_e32 v31, 16, v77
	v_rcp_f32_e32 v24, v24
	v_add_f32_e32 v25, 1.0, v25
	v_mul_f32_e32 v26, 0xbfb8aa3b, v26
	v_mul_f32_e32 v29, v29, v31
	v_and_b32_e32 v31, 0xffff0000, v77
	v_rcp_f32_e32 v25, v25
	v_exp_f32_e32 v26, v26
	v_mul_f32_e32 v27, 0xbfb8aa3b, v27
	v_mul_f32_e32 v30, v30, v31
	v_exp_f32_e32 v27, v27
	v_mul_f32_e32 v20, 0xbfb8aa3b, v20
	v_cvt_pk_bf16_f32 v29, v29, v30
	v_lshlrev_b32_e32 v30, 16, v78
	v_exp_f32_e32 v20, v20
	v_mul_f32_e32 v21, 0xbfb8aa3b, v21
	v_mul_f32_e32 v24, v24, v30
	v_and_b32_e32 v30, 0xffff0000, v78
	v_exp_f32_e32 v21, v21
	v_mul_f32_e32 v25, v25, v30
	v_cvt_pk_bf16_f32 v30, v24, v25
	v_add_f32_e32 v24, 1.0, v26
	v_rcp_f32_e32 v24, v24
	v_add_f32_e32 v25, 1.0, v27
	v_rcp_f32_e32 v25, v25
	v_add_f32_e32 v20, 1.0, v20
	v_rcp_f32_e32 v20, v20
	v_add_f32_e32 v21, 1.0, v21
	v_lshlrev_b32_e32 v26, 16, v79
	v_rcp_f32_e32 v21, v21
	v_mul_f32_e32 v22, 0xbfb8aa3b, v22
	v_mul_f32_e32 v24, v24, v26
	v_and_b32_e32 v26, 0xffff0000, v79
	v_exp_f32_e32 v22, v22
	v_mul_f32_e32 v23, 0xbfb8aa3b, v23
	v_lshlrev_b64 v[32:33], 11, v[90:91]
	v_mul_f32_e32 v25, v25, v26
	v_lshlrev_b32_e32 v26, 16, v72
	v_exp_f32_e32 v23, v23
	v_cvt_pk_bf16_f32 v31, v24, v25
	v_lshl_add_u64 v[24:25], s[46:47], 0, v[32:33]
	v_mul_f32_e32 v20, v20, v26
	v_and_b32_e32 v26, 0xffff0000, v72
	v_mul_f32_e32 v16, 0xbfb8aa3b, v16
	v_lshl_add_u64 v[24:25], v[24:25], 0, v[168:169]
	v_mul_f32_e32 v21, v21, v26
	v_exp_f32_e32 v16, v16
	v_mul_f32_e32 v17, 0xbfb8aa3b, v17
; #define PG8_WAIT_V(n) asm volatile("s_waitcnt vmcnt(" #n ")" ::: "memory")
; #define PG8_BAR __builtin_amdgcn_s_barrier()
; DI unsigned pk2(float lo, float hi) { unsigned r; asm volatile("v_cvt_pk_bf16_f32 %0, %1, %2" : "=v"(r) : "v"(lo), "v"(hi)); return r; }
; DI float bflo(unsigned u) { return __uint_as_float(u << 16); }
; DI float bfhi(unsigned u) { return __uint_as_float(u & 0xffff0000u); }
; DI float sigm(float x) { return __builtin_amdgcn_rcpf(1.f + __expf(-x)); }
; template <class Epi, class Sched>
; __device__ __forceinline__ void gemm_phase(PG8_LAS unsigned char* lds, const Gemm g, const Sched& S, const Epi& E) {
;     ...
;         if (!has_next) break;
; #pragma unroll
;         for (int a = 0; a < 2; ++a)
; #pragma unroll
;             for (int b = 0; b < 2; ++b)
; #pragma unroll
;                 for (int m = 0; m < 4; ++m)
; #pragma unroll
;                     for (int n = 0; n < 2; ++n) acc[a][b][m][n] = (f32x4){0.f, 0.f, 0.f, 0.f};
;         cur = nxt; cA = nA; cB = nB; ++ui;
;     }
;     PG8_WAIT_V(0);
;     if (wr == 0) PG8_BAR;
;     PG8_BAR;
;     DI void operator()(const f32x4 (&acc)[2][2][4][2], const Unit& u, int wr, int wc, int fr, int fq, const Pre& pre) const {
;     ...
;                 for (int bj = 0; bj < 2; ++bj) y[m][bj] = *(const u32x4v*)(YG + (size_t)(row0 + ai * 128 + m * 16) * 512 + cb + bj * 128);
; #pragma unroll
;             for (int m = 0; m < 4; ++m) { const int row = row0 + ai * 128 + m * 16;
; #pragma unroll
;                 for (int bj = 0; bj < 2; ++bj) { const f32x4 v0 = acc[ai][bj][m][0], v1 = acc[ai][bj][m][1]; const u32x4v yy = y[m][bj]; u32x4v o;
;                     o.x = pk2(bflo(yy.x) * sigm(v0[0]), bfhi(yy.x) * sigm(v0[1])); o.y = pk2(bflo(yy.y) * sigm(v0[2]), bfhi(yy.y) * sigm(v0[3]));
;                     o.z = pk2(bflo(yy.z) * sigm(v1[0]), bfhi(yy.z) * sigm(v1[1])); o.w = pk2(bflo(yy.w) * sigm(v1[2]), bfhi(yy.w) * sigm(v1[3]));
;                     *(u32x4v*)(CAT + (size_t)row * 1024 + 512 + cb + bj * 128) = o; } } }
	global_store_dwordx4 v[24:25], v[28:31], off offset:1024
	v_cvt_pk_bf16_f32 v20, v20, v21
	v_add_f32_e32 v21, 1.0, v22
	v_exp_f32_e32 v17, v17
	v_rcp_f32_e32 v21, v21
	v_add_f32_e32 v22, 1.0, v23
	v_rcp_f32_e32 v22, v22
	v_add_f32_e32 v16, 1.0, v16
	v_lshlrev_b32_e32 v23, 16, v73
	v_rcp_f32_e32 v16, v16
	v_add_f32_e32 v17, 1.0, v17
	v_mul_f32_e32 v18, 0xbfb8aa3b, v18
	v_mul_f32_e32 v21, v21, v23
	v_and_b32_e32 v23, 0xffff0000, v73
	v_rcp_f32_e32 v17, v17
	v_exp_f32_e32 v18, v18
	v_mul_f32_e32 v19, 0xbfb8aa3b, v19
	v_mul_f32_e32 v22, v22, v23
	v_exp_f32_e32 v19, v19
	v_mul_f32_e32 v12, 0xbfb8aa3b, v12
	v_cvt_pk_bf16_f32 v21, v21, v22
	v_lshlrev_b32_e32 v22, 16, v74
	v_exp_f32_e32 v12, v12
	v_mul_f32_e32 v13, 0xbfb8aa3b, v13
	v_mul_f32_e32 v16, v16, v22
	v_and_b32_e32 v22, 0xffff0000, v74
	v_exp_f32_e32 v13, v13
	v_mul_f32_e32 v17, v17, v22
	v_cvt_pk_bf16_f32 v22, v16, v17
	v_add_f32_e32 v16, 1.0, v18
	v_rcp_f32_e32 v16, v16
	v_add_f32_e32 v17, 1.0, v19
	v_rcp_f32_e32 v17, v17
	v_add_f32_e32 v12, 1.0, v12
	v_rcp_f32_e32 v12, v12
	v_add_f32_e32 v13, 1.0, v13
	v_lshlrev_b32_e32 v18, 16, v75
	v_rcp_f32_e32 v13, v13
	v_mul_f32_e32 v14, 0xbfb8aa3b, v14
	v_mul_f32_e32 v16, v16, v18
	v_and_b32_e32 v18, 0xffff0000, v75
	v_exp_f32_e32 v14, v14
	v_mul_f32_e32 v15, 0xbfb8aa3b, v15
	v_mul_f32_e32 v17, v17, v18
	v_lshlrev_b32_e32 v18, 16, v68
	v_exp_f32_e32 v15, v15
	v_mul_f32_e32 v12, v12, v18
	v_and_b32_e32 v18, 0xffff0000, v68
	v_mul_f32_e32 v8, 0xbfb8aa3b, v8
	v_mul_f32_e32 v13, v13, v18
	v_exp_f32_e32 v8, v8
	v_mul_f32_e32 v9, 0xbfb8aa3b, v9
	v_cvt_pk_bf16_f32 v23, v16, v17
	global_store_dwordx4 v[24:25], v[20:23], off offset:1280
	v_cvt_pk_bf16_f32 v12, v12, v13
	v_add_f32_e32 v13, 1.0, v14
	v_exp_f32_e32 v9, v9
	v_rcp_f32_e32 v13, v13
	v_add_f32_e32 v14, 1.0, v15
	v_rcp_f32_e32 v14, v14
	v_add_f32_e32 v8, 1.0, v8
	v_lshlrev_b32_e32 v15, 16, v69
	v_rcp_f32_e32 v8, v8
	v_add_f32_e32 v9, 1.0, v9
	v_mul_f32_e32 v10, 0xbfb8aa3b, v10
	v_mul_f32_e32 v13, v13, v15
	v_and_b32_e32 v15, 0xffff0000, v69
	v_rcp_f32_e32 v9, v9
	v_exp_f32_e32 v10, v10
	v_mul_f32_e32 v11, 0xbfb8aa3b, v11
	v_mul_f32_e32 v14, v14, v15
	v_exp_f32_e32 v11, v11
	v_mul_f32_e32 v4, 0xbfb8aa3b, v4
	v_cvt_pk_bf16_f32 v13, v13, v14
	v_lshlrev_b32_e32 v14, 16, v70
	v_exp_f32_e32 v4, v4
	v_mul_f32_e32 v5, 0xbfb8aa3b, v5
	v_mul_f32_e32 v8, v8, v14
	v_and_b32_e32 v14, 0xffff0000, v70
	v_exp_f32_e32 v5, v5
	v_mul_f32_e32 v9, v9, v14
	v_cvt_pk_bf16_f32 v14, v8, v9
	v_add_f32_e32 v8, 1.0, v10
	v_rcp_f32_e32 v8, v8
	v_add_f32_e32 v9, 1.0, v11
	v_rcp_f32_e32 v9, v9
	v_add_f32_e32 v4, 1.0, v4
	v_rcp_f32_e32 v4, v4
	v_add_f32_e32 v5, 1.0, v5
	v_lshlrev_b32_e32 v10, 16, v71
	v_rcp_f32_e32 v5, v5
	v_mul_f32_e32 v6, 0xbfb8aa3b, v6
	v_mul_f32_e32 v8, v8, v10
	v_and_b32_e32 v10, 0xffff0000, v71
	v_exp_f32_e32 v6, v6
	v_mul_f32_e32 v7, 0xbfb8aa3b, v7
	v_lshlrev_b64 v[16:17], 11, v[88:89]
	v_mul_f32_e32 v9, v9, v10
	v_lshlrev_b32_e32 v10, 16, v64
	v_exp_f32_e32 v7, v7
	v_cvt_pk_bf16_f32 v15, v8, v9
	v_lshl_add_u64 v[8:9], s[46:47], 0, v[16:17]
	v_mul_f32_e32 v4, v4, v10
	v_and_b32_e32 v10, 0xffff0000, v64
	v_mul_f32_e32 v0, 0xbfb8aa3b, v0
	v_lshl_add_u64 v[8:9], v[8:9], 0, v[168:169]
	v_mul_f32_e32 v5, v5, v10
	v_exp_f32_e32 v0, v0
	v_mul_f32_e32 v1, 0xbfb8aa3b, v1
	global_store_dwordx4 v[8:9], v[12:15], off offset:1024
	v_cvt_pk_bf16_f32 v4, v4, v5
	v_add_f32_e32 v5, 1.0, v6
	v_exp_f32_e32 v1, v1
	v_rcp_f32_e32 v5, v5
	v_add_f32_e32 v6, 1.0, v7
	v_rcp_f32_e32 v6, v6
	v_add_f32_e32 v0, 1.0, v0
	v_lshlrev_b32_e32 v7, 16, v65
	v_rcp_f32_e32 v0, v0
	v_add_f32_e32 v1, 1.0, v1
	v_mul_f32_e32 v2, 0xbfb8aa3b, v2
	v_mul_f32_e32 v5, v5, v7
	v_and_b32_e32 v7, 0xffff0000, v65
	v_rcp_f32_e32 v1, v1
	v_exp_f32_e32 v2, v2
	v_mul_f32_e32 v3, 0xbfb8aa3b, v3
	v_mul_f32_e32 v6, v6, v7
	v_exp_f32_e32 v3, v3
	v_cvt_pk_bf16_f32 v5, v5, v6
	v_lshlrev_b32_e32 v6, 16, v66
	v_mul_f32_e32 v0, v0, v6
	v_and_b32_e32 v6, 0xffff0000, v66
	v_mul_f32_e32 v1, v1, v6
	v_cvt_pk_bf16_f32 v6, v0, v1
	v_add_f32_e32 v0, 1.0, v2
	v_rcp_f32_e32 v0, v0
	v_add_f32_e32 v1, 1.0, v3
	v_rcp_f32_e32 v1, v1
	v_lshlrev_b32_e32 v2, 16, v67
	v_mul_f32_e32 v0, v0, v2
	v_and_b32_e32 v2, 0xffff0000, v67
	s_andn2_b64 vcc, exec, s[0:1]
	s_mov_b32 s12, s6
	s_mov_b32 s36, s4
	s_mov_b64 s[16:17], s[10:11]
	s_mov_b64 s[14:15], s[8:9]
	v_readlane_b32 s37, v255, 9
	v_readlane_b32 s38, v255, 10
	v_readlane_b32 s39, v255, 11
	v_readlane_b32 s40, v255, 12
	v_readlane_b32 s41, v255, 13
	v_readlane_b32 s42, v255, 14
	v_readlane_b32 s43, v255, 15
	v_readlane_b32 s48, v255, 20
	v_readlane_b32 s49, v255, 21
	v_readlane_b32 s50, v255, 22
	v_readlane_b32 s51, v255, 23
	v_mul_f32_e32 v1, v1, v2
	v_cvt_pk_bf16_f32 v7, v0, v1
	global_store_dwordx4 v[8:9], v[4:7], off offset:1280
	s_cbranch_vccnz .LBB0_1184
	s_waitcnt vmcnt(0)
	s_cmpk_gt_u32 s20, 0xff
	s_cbranch_scc1 .LBB0_1195
	s_barrier

; #define PG8_STAGE(bufoff, gbase, voff) do { _Pragma("unroll") for (int _i = 0; _i < 2; ++_i) \
;         __builtin_amdgcn_global_load_lds((const unsigned*)((const char*)(gbase) + (voff)[_i]), (PG8_LAS unsigned*)(lds + (bufoff) + ldsw + _i * 8192), 16, 0, 0); } while (0)
; #define PG8_LDA(dst, b, h) do { _Pragma("unroll") for (int m = 0; m < 4; ++m) _Pragma("unroll") for (int k = 0; k < 2; ++k) dst[m][k] = *(const PG8_LAS bf16x8*)(lds + PG8_SA(b, h) + aoff + m * 2048 + k * 1024); } while (0)
; #define PG8_LDB(dst, b, h) do { _Pragma("unroll") for (int n = 0; n < 2; ++n) _Pragma("unroll") for (int k = 0; k < 2; ++k) dst[n][k] = *(const PG8_LAS bf16x8*)(lds + PG8_SB(b, h) + boff + n * 2048 + k * 1024); } while (0)
; #define PG8_MMA(ai, bj, At, Bt) do { __builtin_amdgcn_s_setprio(1); _Pragma("unroll") for (int m = 0; m < 4; ++m) _Pragma("unroll") for (int n = 0; n < 2; ++n) _Pragma("unroll") for (int k = 0; k < 2; ++k) \
;         acc[ai][bj][m][n] = __builtin_amdgcn_mfma_f32_16x16x32_bf16(Bt[n][k], At[m][k], acc[ai][bj][m][n], 0, 0, 0); __builtin_amdgcn_s_setprio(0); } while (0)
; #define PG8_WAIT_L(n) asm volatile("s_waitcnt lgkmcnt(" #n ")" ::: "memory")
; #define PG8_BAR __builtin_amdgcn_s_barrier()
; #define PG8_SCHED __builtin_amdgcn_sched_barrier(0)
; template <class Epi, class Sched>
; __device__ __forceinline__ void gemm_phase(PG8_LAS unsigned char* lds, const Gemm g, const Sched& S, const Epi& E) {
;     ...
;             const bool last = (t == cnk - 2);
;             const char* a1 = cA + (size_t)(t + 1) * kstep;
;             const char* a2 = last ? nA : cA + (size_t)(t + 2) * kstep; const char* b2 = last ? nB : cB + (size_t)(t + 2) * kstep;
;             const char* a3 = a2 + kstep; const char* b3 = b2 + kstep;
;             if (last && has_next) S.a_ready(nxt);
;             if (last) E.prefetch(pre, cur, wr, fr);
;             PG8_LDB(B0, 0, 0); PG8_SCHED; PG8_LDA(At, 0, 0); PG8_STAGE(PG8_SA(1, 1), a1 + hstep, voffA);
;             PG8_WAIT_L(8); PG8_BAR; PG8_WAIT_L(0); PG8_MMA(0, 0, At, B0); PG8_BAR; PG8_SCHED;
;             PG8_LDB(B1, 0, 1); PG8_STAGE(PG8_SB(0, 0), b2, voffB);
;             PG8_BAR; PG8_WAIT_L(0); PG8_MMA(0, 1, At, B1); PG8_BAR;
;             PG8_LDA(At, 0, 1); PG8_STAGE(PG8_SA(0, 0), a2, voffA);
;             PG8_BAR; PG8_WAIT_L(0); PG8_MMA(1, 0, At, B0); PG8_BAR; PG8_SCHED;
.LBB0_1313:
	ds_read_b128 v[128:131], v163
	ds_read_b128 v[132:135], v163 offset:1024
	ds_read_b128 v[136:139], v163 offset:2048
	ds_read_b128 v[140:143], v163 offset:3072
	s_add_i32 vcc_lo, s27, 2
	s_add_u32 s30, s40, 0xfffc0080
	s_addc_u32 s42, s41, -1
	s_cmp_eq_u32 s17, s27
	s_cselect_b32 s45, s37, s42
	s_cselect_b32 s44, s36, s30
	s_cselect_b32 s43, s39, s21
	s_cselect_b32 s42, s38, s19
	v_lshl_add_u64 v[196:197], s[40:41], 0, v[174:175]
	s_add_i32 m0, s31, 0xc000
	ds_read_b128 v[144:147], v198
	ds_read_b128 v[148:151], v198 offset:1024
	ds_read_b128 v[180:183], v198 offset:2048
	ds_read_b128 v[184:187], v198 offset:3072
	ds_read_b128 v[188:191], v198 offset:4096
	ds_read_b128 v[192:195], v198 offset:5120
	ds_read_b128 v[202:205], v198 offset:6144
	ds_read_b128 v[206:209], v198 offset:7168
	global_load_lds_dwordx4 v[196:197], off
	s_add_i32 m0, s31, 0xe000
	v_lshl_add_u64 v[196:197], s[40:41], 0, v[176:177]
	global_load_lds_dwordx4 v[196:197], off
	s_waitcnt lgkmcnt(8)
	s_barrier
	s_waitcnt lgkmcnt(0)
	s_setprio 1
	v_mfma_f32_16x16x32_bf16 v[124:127], v[128:131], v[144:147], v[124:127]
	v_mfma_f32_16x16x32_bf16 v[120:123], v[136:139], v[144:147], v[120:123]
	v_mfma_f32_16x16x32_bf16 v[108:111], v[128:131], v[180:183], v[108:111]
	v_mfma_f32_16x16x32_bf16 v[104:107], v[136:139], v[180:183], v[104:107]
	v_mfma_f32_16x16x32_bf16 v[92:95], v[128:131], v[188:191], v[92:95]
	v_mfma_f32_16x16x32_bf16 v[88:91], v[136:139], v[188:191], v[88:91]
	v_mfma_f32_16x16x32_bf16 v[76:79], v[128:131], v[202:205], v[76:79]
	v_mfma_f32_16x16x32_bf16 v[72:75], v[136:139], v[202:205], v[72:75]
	v_mfma_f32_16x16x32_bf16 v[124:127], v[132:135], v[148:151], v[124:127]
	v_mfma_f32_16x16x32_bf16 v[120:123], v[140:143], v[148:151], v[120:123]
	v_mfma_f32_16x16x32_bf16 v[108:111], v[132:135], v[184:187], v[108:111]
	v_mfma_f32_16x16x32_bf16 v[104:107], v[140:143], v[184:187], v[104:107]
	v_mfma_f32_16x16x32_bf16 v[92:95], v[132:135], v[192:195], v[92:95]
	v_mfma_f32_16x16x32_bf16 v[88:91], v[140:143], v[192:195], v[88:91]
	v_mfma_f32_16x16x32_bf16 v[76:79], v[132:135], v[206:209], v[76:79]
	v_mfma_f32_16x16x32_bf16 v[72:75], v[140:143], v[206:209], v[72:75]
	s_setprio 0
	s_barrier
	s_add_i32 s27, s88, s29
	v_lshl_add_u64 v[196:197], s[42:43], 0, v[166:167]
	s_mov_b32 m0, s27
	ds_read_b128 v[210:213], v199
	ds_read_b128 v[214:217], v199 offset:1024
	ds_read_b128 v[218:221], v199 offset:2048
	ds_read_b128 v[222:225], v199 offset:3072
	global_load_lds_dwordx4 v[196:197], off
	s_add_i32 m0, s27, 0x2000
	v_lshl_add_u64 v[226:227], s[42:43], 0, v[170:171]
	global_load_lds_dwordx4 v[226:227], off
	s_barrier
	s_waitcnt lgkmcnt(0)
	s_setprio 1
	v_mfma_f32_16x16x32_bf16 v[116:119], v[210:213], v[144:147], v[116:119]
	v_mfma_f32_16x16x32_bf16 v[112:115], v[218:221], v[144:147], v[112:115]
	v_mfma_f32_16x16x32_bf16 v[100:103], v[210:213], v[180:183], v[100:103]
	v_mfma_f32_16x16x32_bf16 v[96:99], v[218:221], v[180:183], v[96:99]
	v_mfma_f32_16x16x32_bf16 v[84:87], v[210:213], v[188:191], v[84:87]
	v_mfma_f32_16x16x32_bf16 v[80:83], v[218:221], v[188:191], v[80:83]
	v_mfma_f32_16x16x32_bf16 v[68:71], v[210:213], v[202:205], v[68:71]
	v_mfma_f32_16x16x32_bf16 v[64:67], v[218:221], v[202:205], v[64:67]
	v_mfma_f32_16x16x32_bf16 v[116:119], v[214:217], v[148:151], v[116:119]
	v_mfma_f32_16x16x32_bf16 v[112:115], v[222:225], v[148:151], v[112:115]
	v_mfma_f32_16x16x32_bf16 v[100:103], v[214:217], v[184:187], v[100:103]
	v_mfma_f32_16x16x32_bf16 v[96:99], v[222:225], v[184:187], v[96:99]
	v_mfma_f32_16x16x32_bf16 v[84:87], v[214:217], v[192:195], v[84:87]
	v_mfma_f32_16x16x32_bf16 v[80:83], v[222:225], v[192:195], v[80:83]
	v_mfma_f32_16x16x32_bf16 v[68:71], v[214:217], v[206:209], v[68:71]
	v_mfma_f32_16x16x32_bf16 v[64:67], v[222:225], v[206:209], v[64:67]
	s_setprio 0
	s_mov_b32 m0, s31
	v_lshl_add_u64 v[228:229], s[44:45], 0, v[164:165]
	s_barrier
	ds_read_b128 v[144:147], v198 offset:16384
	ds_read_b128 v[148:151], v198 offset:17408
	ds_read_b128 v[180:183], v198 offset:18432
	ds_read_b128 v[184:187], v198 offset:19456
	ds_read_b128 v[188:191], v198 offset:20480
	ds_read_b128 v[192:195], v198 offset:21504
	ds_read_b128 v[202:205], v198 offset:22528
	ds_read_b128 v[206:209], v198 offset:23552
	global_load_lds_dwordx4 v[228:229], off
	s_mov_b32 m0, s33
	v_lshl_add_u64 v[230:231], s[44:45], 0, v[168:169]
	global_load_lds_dwordx4 v[230:231], off
	s_barrier
	s_waitcnt lgkmcnt(0)
	s_setprio 1
	v_mfma_f32_16x16x32_bf16 v[60:63], v[128:131], v[144:147], v[60:63]
	v_mfma_f32_16x16x32_bf16 v[56:59], v[136:139], v[144:147], v[56:59]
	v_mfma_f32_16x16x32_bf16 v[44:47], v[128:131], v[180:183], v[44:47]
	v_mfma_f32_16x16x32_bf16 v[40:43], v[136:139], v[180:183], v[40:43]
	v_mfma_f32_16x16x32_bf16 v[28:31], v[128:131], v[188:191], v[28:31]
	v_mfma_f32_16x16x32_bf16 v[24:27], v[136:139], v[188:191], v[24:27]
	v_mfma_f32_16x16x32_bf16 v[12:15], v[128:131], v[202:205], v[12:15]
	v_mfma_f32_16x16x32_bf16 v[8:11], v[136:139], v[202:205], v[8:11]
	v_mfma_f32_16x16x32_bf16 v[60:63], v[132:135], v[148:151], v[60:63]
	v_mfma_f32_16x16x32_bf16 v[56:59], v[140:143], v[148:151], v[56:59]
	v_mfma_f32_16x16x32_bf16 v[44:47], v[132:135], v[184:187], v[44:47]
	v_mfma_f32_16x16x32_bf16 v[40:43], v[140:143], v[184:187], v[40:43]
	v_mfma_f32_16x16x32_bf16 v[28:31], v[132:135], v[192:195], v[28:31]
	v_mfma_f32_16x16x32_bf16 v[24:27], v[140:143], v[192:195], v[24:27]
	v_mfma_f32_16x16x32_bf16 v[12:15], v[132:135], v[206:209], v[12:15]
	v_mfma_f32_16x16x32_bf16 v[8:11], v[140:143], v[206:209], v[8:11]
	s_setprio 0
	s_barrier
; #define PG8_STAGE(bufoff, gbase, voff) do { _Pragma("unroll") for (int _i = 0; _i < 2; ++_i) \
;         __builtin_amdgcn_global_load_lds((const unsigned*)((const char*)(gbase) + (voff)[_i]), (PG8_LAS unsigned*)(lds + (bufoff) + ldsw + _i * 8192), 16, 0, 0); } while (0)
; #define PG8_LDA(dst, b, h) do { _Pragma("unroll") for (int m = 0; m < 4; ++m) _Pragma("unroll") for (int k = 0; k < 2; ++k) dst[m][k] = *(const PG8_LAS bf16x8*)(lds + PG8_SA(b, h) + aoff + m * 2048 + k * 1024); } while (0)
; #define PG8_LDB(dst, b, h) do { _Pragma("unroll") for (int n = 0; n < 2; ++n) _Pragma("unroll") for (int k = 0; k < 2; ++k) dst[n][k] = *(const PG8_LAS bf16x8*)(lds + PG8_SB(b, h) + boff + n * 2048 + k * 1024); } while (0)
; #define PG8_MMA(ai, bj, At, Bt) do { __builtin_amdgcn_s_setprio(1); _Pragma("unroll") for (int m = 0; m < 4; ++m) _Pragma("unroll") for (int n = 0; n < 2; ++n) _Pragma("unroll") for (int k = 0; k < 2; ++k) \
;         acc[ai][bj][m][n] = __builtin_amdgcn_mfma_f32_16x16x32_bf16(Bt[n][k], At[m][k], acc[ai][bj][m][n], 0, 0, 0); __builtin_amdgcn_s_setprio(0); } while (0)
; #define PG8_WAIT_V(n) asm volatile("s_waitcnt vmcnt(" #n ")" ::: "memory")
; #define PG8_WAIT_L(n) asm volatile("s_waitcnt lgkmcnt(" #n ")" ::: "memory")
; #define PG8_BAR __builtin_amdgcn_s_barrier()
; #define PG8_SCHED __builtin_amdgcn_sched_barrier(0)
; template <class Epi, class Sched>
; __device__ __forceinline__ void gemm_phase(PG8_LAS unsigned char* lds, const Gemm g, const Sched& S, const Epi& E) {
;     ...
;             PG8_STAGE(PG8_SB(0, 1), b2 + hstep, voffB);
;             PG8_WAIT_V(6); PG8_BAR; PG8_MMA(1, 1, At, B1); PG8_BAR;
;             PG8_LDB(B0, 1, 0); PG8_SCHED; PG8_LDA(At, 1, 0); PG8_STAGE(PG8_SA(0, 1), a2 + hstep, voffA);
;             PG8_WAIT_L(8); PG8_BAR; PG8_WAIT_L(0); PG8_MMA(0, 0, At, B0); PG8_BAR; PG8_SCHED;
;             PG8_LDB(B1, 1, 1); PG8_STAGE(PG8_SB(1, 0), b3, voffB);
	s_add_u32 s96, s42, 0x40000
	s_addc_u32 s97, s43, 0
	s_add_i32 s27, s89, s29
	s_mov_b32 m0, s27
	v_lshl_add_u64 v[128:129], s[96:97], 0, v[166:167]
	global_load_lds_dwordx4 v[128:129], off
	s_add_i32 m0, s27, 0x2000
	v_lshl_add_u64 v[128:129], s[96:97], 0, v[170:171]
	global_load_lds_dwordx4 v[128:129], off
	s_waitcnt vmcnt(6)
	s_barrier
	s_setprio 1
	v_mfma_f32_16x16x32_bf16 v[52:55], v[210:213], v[144:147], v[52:55]
	v_mfma_f32_16x16x32_bf16 v[48:51], v[218:221], v[144:147], v[48:51]
	v_mfma_f32_16x16x32_bf16 v[36:39], v[210:213], v[180:183], v[36:39]
	v_mfma_f32_16x16x32_bf16 v[32:35], v[218:221], v[180:183], v[32:35]
	v_mfma_f32_16x16x32_bf16 v[20:23], v[210:213], v[188:191], v[20:23]
	v_mfma_f32_16x16x32_bf16 v[16:19], v[218:221], v[188:191], v[16:19]
	v_mfma_f32_16x16x32_bf16 v[4:7], v[210:213], v[202:205], v[4:7]
	v_mfma_f32_16x16x32_bf16 v[0:3], v[218:221], v[202:205], v[0:3]
	v_mfma_f32_16x16x32_bf16 v[52:55], v[214:217], v[148:151], v[52:55]
	v_mfma_f32_16x16x32_bf16 v[48:51], v[222:225], v[148:151], v[48:51]
	v_mfma_f32_16x16x32_bf16 v[36:39], v[214:217], v[184:187], v[36:39]
	v_mfma_f32_16x16x32_bf16 v[32:35], v[222:225], v[184:187], v[32:35]
	v_mfma_f32_16x16x32_bf16 v[20:23], v[214:217], v[192:195], v[20:23]
	v_mfma_f32_16x16x32_bf16 v[16:19], v[222:225], v[192:195], v[16:19]
	v_mfma_f32_16x16x32_bf16 v[4:7], v[214:217], v[206:209], v[4:7]
	v_mfma_f32_16x16x32_bf16 v[0:3], v[222:225], v[206:209], v[0:3]
	s_setprio 0
	s_add_i32 s27, 0, 0x18000
	v_add_u32_e32 v140, s27, v159
	s_barrier
	ds_read_b128 v[128:131], v140
	ds_read_b128 v[132:135], v140 offset:1024
	ds_read_b128 v[136:139], v140 offset:2048
	ds_read_b128 v[140:143], v140 offset:3072
	s_add_u32 s44, s44, 0x40000
	s_addc_u32 s45, s45, 0
	s_mov_b32 m0, s34
	v_lshl_add_u64 v[210:211], s[44:45], 0, v[164:165]
	ds_read_b128 v[144:147], v198 offset:32768
	ds_read_b128 v[148:151], v198 offset:33792
	ds_read_b128 v[180:183], v198 offset:34816
	ds_read_b128 v[184:187], v198 offset:35840
	ds_read_b128 v[188:191], v198 offset:36864
	ds_read_b128 v[192:195], v198 offset:37888
	ds_read_b128 v[202:205], v198 offset:38912
	ds_read_b128 v[206:209], v198 offset:39936
	global_load_lds_dwordx4 v[210:211], off
	s_mov_b32 m0, s35
	v_lshl_add_u64 v[210:211], s[44:45], 0, v[168:169]
	global_load_lds_dwordx4 v[210:211], off
	s_waitcnt lgkmcnt(8)
	s_barrier
	s_waitcnt lgkmcnt(0)
	s_setprio 1
	v_mfma_f32_16x16x32_bf16 v[124:127], v[128:131], v[144:147], v[124:127]
	v_mfma_f32_16x16x32_bf16 v[120:123], v[136:139], v[144:147], v[120:123]
	v_mfma_f32_16x16x32_bf16 v[108:111], v[128:131], v[180:183], v[108:111]
	v_mfma_f32_16x16x32_bf16 v[104:107], v[136:139], v[180:183], v[104:107]
	v_mfma_f32_16x16x32_bf16 v[92:95], v[128:131], v[188:191], v[92:95]
	v_mfma_f32_16x16x32_bf16 v[88:91], v[136:139], v[188:191], v[88:91]
	v_mfma_f32_16x16x32_bf16 v[76:79], v[128:131], v[202:205], v[76:79]
	v_mfma_f32_16x16x32_bf16 v[72:75], v[136:139], v[202:205], v[72:75]
	v_mfma_f32_16x16x32_bf16 v[124:127], v[132:135], v[148:151], v[124:127]
	v_mfma_f32_16x16x32_bf16 v[120:123], v[140:143], v[148:151], v[120:123]
	v_mfma_f32_16x16x32_bf16 v[108:111], v[132:135], v[184:187], v[108:111]
	v_mfma_f32_16x16x32_bf16 v[104:107], v[140:143], v[184:187], v[104:107]
	v_mfma_f32_16x16x32_bf16 v[92:95], v[132:135], v[192:195], v[92:95]
	v_mfma_f32_16x16x32_bf16 v[88:91], v[140:143], v[192:195], v[88:91]
	v_mfma_f32_16x16x32_bf16 v[76:79], v[132:135], v[206:209], v[76:79]
	v_mfma_f32_16x16x32_bf16 v[72:75], v[140:143], v[206:209], v[72:75]
	s_setprio 0
	s_barrier
	s_add_i32 s30, 0, 0x1c000
	s_add_i32 s27, s27, s29
	v_add_u32_e32 v201, s30, v159
	v_lshl_add_u64 v[196:197], v[196:197], 0, s[10:11]
	s_mov_b32 m0, s27
	ds_read_b128 v[210:213], v201
	ds_read_b128 v[214:217], v201 offset:1024
	ds_read_b128 v[218:221], v201 offset:2048
	ds_read_b128 v[222:225], v201 offset:3072
	global_load_lds_dwordx4 v[196:197], off
	s_add_i32 m0, s27, 0x2000
	v_lshl_add_u64 v[196:197], v[226:227], 0, s[10:11]
	global_load_lds_dwordx4 v[196:197], off
	s_barrier
; #define PG8_STAGE(bufoff, gbase, voff) do { _Pragma("unroll") for (int _i = 0; _i < 2; ++_i) \
;         __builtin_amdgcn_global_load_lds((const unsigned*)((const char*)(gbase) + (voff)[_i]), (PG8_LAS unsigned*)(lds + (bufoff) + ldsw + _i * 8192), 16, 0, 0); } while (0)
; #define PG8_LDA(dst, b, h) do { _Pragma("unroll") for (int m = 0; m < 4; ++m) _Pragma("unroll") for (int k = 0; k < 2; ++k) dst[m][k] = *(const PG8_LAS bf16x8*)(lds + PG8_SA(b, h) + aoff + m * 2048 + k * 1024); } while (0)
; #define PG8_MMA(ai, bj, At, Bt) do { __builtin_amdgcn_s_setprio(1); _Pragma("unroll") for (int m = 0; m < 4; ++m) _Pragma("unroll") for (int n = 0; n < 2; ++n) _Pragma("unroll") for (int k = 0; k < 2; ++k) \
;         acc[ai][bj][m][n] = __builtin_amdgcn_mfma_f32_16x16x32_bf16(Bt[n][k], At[m][k], acc[ai][bj][m][n], 0, 0, 0); __builtin_amdgcn_s_setprio(0); } while (0)
; #define PG8_WAIT_V(n) asm volatile("s_waitcnt vmcnt(" #n ")" ::: "memory")
; #define PG8_WAIT_L(n) asm volatile("s_waitcnt lgkmcnt(" #n ")" ::: "memory")
; #define PG8_BAR __builtin_amdgcn_s_barrier()
; #define PG8_SCHED __builtin_amdgcn_sched_barrier(0)
; template <class Epi, class Sched>
; __device__ __forceinline__ void gemm_phase(PG8_LAS unsigned char* lds, const Gemm g, const Sched& S, const Epi& E) {
;     ...
;         for (int t = 0; t < cnk; t += 2) {
;     ...
;             PG8_BAR; PG8_WAIT_L(0); PG8_MMA(0, 1, At, B1); PG8_BAR;
;             PG8_LDA(At, 1, 1); PG8_STAGE(PG8_SA(1, 0), a3, voffA);
;             PG8_BAR; PG8_WAIT_L(0); PG8_MMA(1, 0, At, B0); PG8_BAR; PG8_SCHED;
;             PG8_STAGE(PG8_SB(1, 1), b3 + hstep, voffB);
;             PG8_WAIT_V(6); PG8_BAR; PG8_MMA(1, 1, At, B1); PG8_BAR;
;         }
	s_waitcnt lgkmcnt(0)
	s_setprio 1
	v_mfma_f32_16x16x32_bf16 v[116:119], v[210:213], v[144:147], v[116:119]
	v_mfma_f32_16x16x32_bf16 v[112:115], v[218:221], v[144:147], v[112:115]
	v_mfma_f32_16x16x32_bf16 v[100:103], v[210:213], v[180:183], v[100:103]
	v_mfma_f32_16x16x32_bf16 v[96:99], v[218:221], v[180:183], v[96:99]
	v_mfma_f32_16x16x32_bf16 v[84:87], v[210:213], v[188:191], v[84:87]
	v_mfma_f32_16x16x32_bf16 v[80:83], v[218:221], v[188:191], v[80:83]
	v_mfma_f32_16x16x32_bf16 v[68:71], v[210:213], v[202:205], v[68:71]
	v_mfma_f32_16x16x32_bf16 v[64:67], v[218:221], v[202:205], v[64:67]
	v_mfma_f32_16x16x32_bf16 v[116:119], v[214:217], v[148:151], v[116:119]
	v_mfma_f32_16x16x32_bf16 v[112:115], v[222:225], v[148:151], v[112:115]
	v_mfma_f32_16x16x32_bf16 v[100:103], v[214:217], v[184:187], v[100:103]
	v_mfma_f32_16x16x32_bf16 v[96:99], v[222:225], v[184:187], v[96:99]
	v_mfma_f32_16x16x32_bf16 v[84:87], v[214:217], v[192:195], v[84:87]
	v_mfma_f32_16x16x32_bf16 v[80:83], v[222:225], v[192:195], v[80:83]
	v_mfma_f32_16x16x32_bf16 v[68:71], v[214:217], v[206:209], v[68:71]
	v_mfma_f32_16x16x32_bf16 v[64:67], v[222:225], v[206:209], v[64:67]
	s_setprio 0
	s_mov_b32 m0, s47
	v_lshl_add_u64 v[196:197], v[228:229], 0, s[10:11]
	s_barrier
	ds_read_b128 v[144:147], v198 offset:49152
	ds_read_b128 v[148:151], v198 offset:50176
	ds_read_b128 v[180:183], v198 offset:51200
	ds_read_b128 v[184:187], v198 offset:52224
	ds_read_b128 v[188:191], v198 offset:53248
	ds_read_b128 v[192:195], v198 offset:54272
	ds_read_b128 v[202:205], v198 offset:55296
	ds_read_b128 v[206:209], v198 offset:56320
	global_load_lds_dwordx4 v[196:197], off
	s_mov_b32 m0, s48
	v_lshl_add_u64 v[196:197], v[230:231], 0, s[10:11]
	global_load_lds_dwordx4 v[196:197], off
	s_barrier
	s_waitcnt lgkmcnt(0)
	s_setprio 1
	v_mfma_f32_16x16x32_bf16 v[60:63], v[128:131], v[144:147], v[60:63]
	v_mfma_f32_16x16x32_bf16 v[56:59], v[136:139], v[144:147], v[56:59]
	v_mfma_f32_16x16x32_bf16 v[44:47], v[128:131], v[180:183], v[44:47]
	v_mfma_f32_16x16x32_bf16 v[40:43], v[136:139], v[180:183], v[40:43]
	v_mfma_f32_16x16x32_bf16 v[28:31], v[128:131], v[188:191], v[28:31]
	v_mfma_f32_16x16x32_bf16 v[24:27], v[136:139], v[188:191], v[24:27]
	v_mfma_f32_16x16x32_bf16 v[12:15], v[128:131], v[202:205], v[12:15]
	v_mfma_f32_16x16x32_bf16 v[8:11], v[136:139], v[202:205], v[8:11]
	v_mfma_f32_16x16x32_bf16 v[60:63], v[132:135], v[148:151], v[60:63]
	v_mfma_f32_16x16x32_bf16 v[56:59], v[140:143], v[148:151], v[56:59]
	v_mfma_f32_16x16x32_bf16 v[44:47], v[132:135], v[184:187], v[44:47]
	v_mfma_f32_16x16x32_bf16 v[40:43], v[140:143], v[184:187], v[40:43]
	v_mfma_f32_16x16x32_bf16 v[28:31], v[132:135], v[192:195], v[28:31]
	v_mfma_f32_16x16x32_bf16 v[24:27], v[140:143], v[192:195], v[24:27]
	v_mfma_f32_16x16x32_bf16 v[12:15], v[132:135], v[206:209], v[12:15]
	v_mfma_f32_16x16x32_bf16 v[8:11], v[140:143], v[206:209], v[8:11]
	s_setprio 0
	s_barrier
	s_add_u32 s42, s42, 0x40080
	s_addc_u32 s43, s43, 0
	s_add_i32 s27, s30, s29
	s_mov_b32 m0, s27
	v_lshl_add_u64 v[128:129], s[42:43], 0, v[166:167]
	global_load_lds_dwordx4 v[128:129], off
	s_add_i32 m0, s27, 0x2000
	v_lshl_add_u64 v[128:129], s[42:43], 0, v[170:171]
	global_load_lds_dwordx4 v[128:129], off
	s_waitcnt vmcnt(6)
	s_barrier
	s_setprio 1
	v_mfma_f32_16x16x32_bf16 v[52:55], v[210:213], v[144:147], v[52:55]
	v_mfma_f32_16x16x32_bf16 v[48:51], v[218:221], v[144:147], v[48:51]
	v_mfma_f32_16x16x32_bf16 v[36:39], v[210:213], v[180:183], v[36:39]
	v_mfma_f32_16x16x32_bf16 v[32:35], v[218:221], v[180:183], v[32:35]
	v_mfma_f32_16x16x32_bf16 v[20:23], v[210:213], v[188:191], v[20:23]
	v_mfma_f32_16x16x32_bf16 v[16:19], v[218:221], v[188:191], v[16:19]
	v_mfma_f32_16x16x32_bf16 v[4:7], v[210:213], v[202:205], v[4:7]
	v_mfma_f32_16x16x32_bf16 v[0:3], v[218:221], v[202:205], v[0:3]
	v_mfma_f32_16x16x32_bf16 v[52:55], v[214:217], v[148:151], v[52:55]
	v_mfma_f32_16x16x32_bf16 v[48:51], v[222:225], v[148:151], v[48:51]
	v_mfma_f32_16x16x32_bf16 v[36:39], v[214:217], v[184:187], v[36:39]
	v_mfma_f32_16x16x32_bf16 v[32:35], v[222:225], v[184:187], v[32:35]
	v_mfma_f32_16x16x32_bf16 v[20:23], v[214:217], v[192:195], v[20:23]
	v_mfma_f32_16x16x32_bf16 v[16:19], v[222:225], v[192:195], v[16:19]
	v_mfma_f32_16x16x32_bf16 v[4:7], v[214:217], v[206:209], v[4:7]
	v_mfma_f32_16x16x32_bf16 v[0:3], v[222:225], v[206:209], v[0:3]
	s_setprio 0
	s_add_u32 s40, s40, 0x100
	s_addc_u32 s41, s41, 0
	s_add_u32 s19, s19, 0x100
	s_addc_u32 s21, s21, 0
	s_cmp_ge_i32 vcc_lo, s15
	s_mov_b32 s27, vcc_lo
	s_barrier
	s_cbranch_scc0 .LBB0_1313
	s_cmp_gt_i32 s8, -1
	s_mov_b64 s[40:41], -1
	s_cbranch_scc0 .LBB0_1316

; #define PG8_STAGE(bufoff, gbase, voff) do { _Pragma("unroll") for (int _i = 0; _i < 2; ++_i) \
;         __builtin_amdgcn_global_load_lds((const unsigned*)((const char*)(gbase) + (voff)[_i]), (PG8_LAS unsigned*)(lds + (bufoff) + ldsw + _i * 8192), 16, 0, 0); } while (0)
; #define PG8_LDA(dst, b, h) do { _Pragma("unroll") for (int m = 0; m < 4; ++m) _Pragma("unroll") for (int k = 0; k < 2; ++k) dst[m][k] = *(const PG8_LAS bf16x8*)(lds + PG8_SA(b, h) + aoff + m * 2048 + k * 1024); } while (0)
; #define PG8_LDB(dst, b, h) do { _Pragma("unroll") for (int n = 0; n < 2; ++n) _Pragma("unroll") for (int k = 0; k < 2; ++k) dst[n][k] = *(const PG8_LAS bf16x8*)(lds + PG8_SB(b, h) + boff + n * 2048 + k * 1024); } while (0)
; #define PG8_MMA(ai, bj, At, Bt) do { __builtin_amdgcn_s_setprio(1); _Pragma("unroll") for (int m = 0; m < 4; ++m) _Pragma("unroll") for (int n = 0; n < 2; ++n) _Pragma("unroll") for (int k = 0; k < 2; ++k) \
;         acc[ai][bj][m][n] = __builtin_amdgcn_mfma_f32_16x16x32_bf16(Bt[n][k], At[m][k], acc[ai][bj][m][n], 0, 0, 0); __builtin_amdgcn_s_setprio(0); } while (0)
; #define PG8_WAIT_L(n) asm volatile("s_waitcnt lgkmcnt(" #n ")" ::: "memory")
; #define PG8_BAR __builtin_amdgcn_s_barrier()
; #define PG8_SCHED __builtin_amdgcn_sched_barrier(0)
; template <class Epi, class Sched>
; __device__ __forceinline__ void gemm_phase(PG8_LAS unsigned char* lds, const Gemm g, const Sched& S, const Epi& E) {
;     ...
;             const bool last = (t == cnk - 2);
;             const char* a1 = cA + (size_t)(t + 1) * kstep;
;             const char* a2 = last ? nA : cA + (size_t)(t + 2) * kstep; const char* b2 = last ? nB : cB + (size_t)(t + 2) * kstep;
;             const char* a3 = a2 + kstep; const char* b3 = b2 + kstep;
;             if (last && has_next) S.a_ready(nxt);
;             if (last) E.prefetch(pre, cur, wr, fr);
;             PG8_LDB(B0, 0, 0); PG8_SCHED; PG8_LDA(At, 0, 0); PG8_STAGE(PG8_SA(1, 1), a1 + hstep, voffA);
;             PG8_WAIT_L(8); PG8_BAR; PG8_WAIT_L(0); PG8_MMA(0, 0, At, B0); PG8_BAR; PG8_SCHED;
;             PG8_LDB(B1, 0, 1); PG8_STAGE(PG8_SB(0, 0), b2, voffB);
;             PG8_BAR; PG8_WAIT_L(0); PG8_MMA(0, 1, At, B1); PG8_BAR;
;             PG8_LDA(At, 0, 1); PG8_STAGE(PG8_SA(0, 0), a2, voffA);
;             PG8_BAR; PG8_WAIT_L(0); PG8_MMA(1, 0, At, B0); PG8_BAR; PG8_SCHED;
.LBB0_1509:
	v_add_u32_e32 v142, s33, v159
	ds_read_b128 v[130:133], v142
	ds_read_b128 v[134:137], v142 offset:1024
	ds_read_b128 v[138:141], v142 offset:2048
	ds_read_b128 v[142:145], v142 offset:3072
	s_add_u32 s30, s4, 0xfffc0080
	s_addc_u32 s40, s5, -1
	s_and_b64 s[38:39], s[38:39], exec
	s_cselect_b32 s41, s23, s40
	s_cselect_b32 s40, s43, s30
	s_cselect_b32 s39, s21, s46
	s_cselect_b32 s38, s44, s45
	v_lshl_add_u64 v[150:151], s[4:5], 0, v[174:175]
	s_add_i32 m0, s16, 0xc000
	ds_read_b128 v[146:149], v163
	ds_read_b128 v[192:195], v163 offset:1024
	ds_read_b128 v[196:199], v163 offset:2048
	ds_read_b128 v[200:203], v163 offset:3072
	ds_read_b128 v[206:209], v163 offset:4096
	ds_read_b128 v[210:213], v163 offset:5120
	ds_read_b128 v[214:217], v163 offset:6144
	ds_read_b128 v[218:221], v163 offset:7168
	global_load_lds_dwordx4 v[150:151], off
	s_add_i32 m0, s16, 0xe000
	v_lshl_add_u64 v[150:151], s[4:5], 0, v[176:177]
	global_load_lds_dwordx4 v[150:151], off
	s_waitcnt lgkmcnt(8)
	s_barrier
	s_waitcnt lgkmcnt(0)
	s_setprio 1
	v_mfma_f32_16x16x32_bf16 v[124:127], v[130:133], v[146:149], v[124:127]
	v_mfma_f32_16x16x32_bf16 v[120:123], v[138:141], v[146:149], v[120:123]
	v_mfma_f32_16x16x32_bf16 v[108:111], v[130:133], v[196:199], v[108:111]
	v_mfma_f32_16x16x32_bf16 v[104:107], v[138:141], v[196:199], v[104:107]
	v_mfma_f32_16x16x32_bf16 v[92:95], v[130:133], v[206:209], v[92:95]
	v_mfma_f32_16x16x32_bf16 v[88:91], v[138:141], v[206:209], v[88:91]
	v_mfma_f32_16x16x32_bf16 v[76:79], v[130:133], v[214:217], v[76:79]
	v_mfma_f32_16x16x32_bf16 v[72:75], v[138:141], v[214:217], v[72:75]
	v_mfma_f32_16x16x32_bf16 v[124:127], v[134:137], v[192:195], v[124:127]
	v_mfma_f32_16x16x32_bf16 v[120:123], v[142:145], v[192:195], v[120:123]
	v_mfma_f32_16x16x32_bf16 v[108:111], v[134:137], v[200:203], v[108:111]
	v_mfma_f32_16x16x32_bf16 v[104:107], v[142:145], v[200:203], v[104:107]
	v_mfma_f32_16x16x32_bf16 v[92:95], v[134:137], v[210:213], v[92:95]
	v_mfma_f32_16x16x32_bf16 v[88:91], v[142:145], v[210:213], v[88:91]
	v_mfma_f32_16x16x32_bf16 v[76:79], v[134:137], v[218:221], v[76:79]
	v_mfma_f32_16x16x32_bf16 v[72:75], v[142:145], v[218:221], v[72:75]
	s_setprio 0
	s_barrier
	v_add_u32_e32 v150, s34, v159
	s_add_i32 s30, s33, s3
	ds_read_b128 v[222:225], v150
	ds_read_b128 v[226:229], v150 offset:1024
	ds_read_b128 v[230:233], v150 offset:2048
	ds_read_b128 v[234:237], v150 offset:3072
	v_lshl_add_u64 v[150:151], s[38:39], 0, v[168:169]
	s_mov_b32 m0, s30
	v_lshl_add_u64 v[238:239], s[38:39], 0, v[164:165]
	global_load_lds_dwordx4 v[150:151], off
	s_add_i32 m0, s30, 0x2000
	s_nop 0
	global_load_lds_dwordx4 v[238:239], off
	s_barrier
	s_waitcnt lgkmcnt(0)
	s_setprio 1
	v_mfma_f32_16x16x32_bf16 v[116:119], v[222:225], v[146:149], v[116:119]
	v_mfma_f32_16x16x32_bf16 v[112:115], v[230:233], v[146:149], v[112:115]
	v_mfma_f32_16x16x32_bf16 v[100:103], v[222:225], v[196:199], v[100:103]
	v_mfma_f32_16x16x32_bf16 v[96:99], v[230:233], v[196:199], v[96:99]
	v_mfma_f32_16x16x32_bf16 v[84:87], v[222:225], v[206:209], v[84:87]
	v_mfma_f32_16x16x32_bf16 v[80:83], v[230:233], v[206:209], v[80:83]
	v_mfma_f32_16x16x32_bf16 v[68:71], v[222:225], v[214:217], v[68:71]
	v_mfma_f32_16x16x32_bf16 v[64:67], v[230:233], v[214:217], v[64:67]
	v_mfma_f32_16x16x32_bf16 v[116:119], v[226:229], v[192:195], v[116:119]
	v_mfma_f32_16x16x32_bf16 v[112:115], v[234:237], v[192:195], v[112:115]
	v_mfma_f32_16x16x32_bf16 v[100:103], v[226:229], v[200:203], v[100:103]
	v_mfma_f32_16x16x32_bf16 v[96:99], v[234:237], v[200:203], v[96:99]
	v_mfma_f32_16x16x32_bf16 v[84:87], v[226:229], v[210:213], v[84:87]
	v_mfma_f32_16x16x32_bf16 v[80:83], v[234:237], v[210:213], v[80:83]
	v_mfma_f32_16x16x32_bf16 v[68:71], v[226:229], v[218:221], v[68:71]
	v_mfma_f32_16x16x32_bf16 v[64:67], v[234:237], v[218:221], v[64:67]
	s_setprio 0
	s_mov_b32 m0, s16
	v_lshl_add_u64 v[240:241], s[40:41], 0, v[170:171]
	s_barrier
	ds_read_b128 v[146:149], v163 offset:16384
	ds_read_b128 v[192:195], v163 offset:17408
	ds_read_b128 v[196:199], v163 offset:18432
	ds_read_b128 v[200:203], v163 offset:19456
	ds_read_b128 v[206:209], v163 offset:20480
	ds_read_b128 v[210:213], v163 offset:21504
	ds_read_b128 v[214:217], v163 offset:22528
	ds_read_b128 v[218:221], v163 offset:23552
	global_load_lds_dwordx4 v[240:241], off
	s_mov_b32 m0, s17
	v_lshl_add_u64 v[242:243], s[40:41], 0, v[166:167]
	global_load_lds_dwordx4 v[242:243], off
	s_barrier
	s_waitcnt lgkmcnt(0)
	s_setprio 1
	v_mfma_f32_16x16x32_bf16 v[60:63], v[130:133], v[146:149], v[60:63]
	v_mfma_f32_16x16x32_bf16 v[56:59], v[138:141], v[146:149], v[56:59]
	v_mfma_f32_16x16x32_bf16 v[44:47], v[130:133], v[196:199], v[44:47]
	v_mfma_f32_16x16x32_bf16 v[40:43], v[138:141], v[196:199], v[40:43]
	v_mfma_f32_16x16x32_bf16 v[28:31], v[130:133], v[206:209], v[28:31]
	v_mfma_f32_16x16x32_bf16 v[24:27], v[138:141], v[206:209], v[24:27]
	v_mfma_f32_16x16x32_bf16 v[12:15], v[130:133], v[214:217], v[12:15]
	v_mfma_f32_16x16x32_bf16 v[8:11], v[138:141], v[214:217], v[8:11]
	v_mfma_f32_16x16x32_bf16 v[60:63], v[134:137], v[192:195], v[60:63]
	v_mfma_f32_16x16x32_bf16 v[56:59], v[142:145], v[192:195], v[56:59]
	v_mfma_f32_16x16x32_bf16 v[44:47], v[134:137], v[200:203], v[44:47]
	v_mfma_f32_16x16x32_bf16 v[40:43], v[142:145], v[200:203], v[40:43]
	v_mfma_f32_16x16x32_bf16 v[28:31], v[134:137], v[210:213], v[28:31]
	v_mfma_f32_16x16x32_bf16 v[24:27], v[142:145], v[210:213], v[24:27]
	v_mfma_f32_16x16x32_bf16 v[12:15], v[134:137], v[218:221], v[12:15]
	v_mfma_f32_16x16x32_bf16 v[8:11], v[142:145], v[218:221], v[8:11]
	s_setprio 0
	s_barrier
; #define PG8_STAGE(bufoff, gbase, voff) do { _Pragma("unroll") for (int _i = 0; _i < 2; ++_i) \
;         __builtin_amdgcn_global_load_lds((const unsigned*)((const char*)(gbase) + (voff)[_i]), (PG8_LAS unsigned*)(lds + (bufoff) + ldsw + _i * 8192), 16, 0, 0); } while (0)
; #define PG8_LDA(dst, b, h) do { _Pragma("unroll") for (int m = 0; m < 4; ++m) _Pragma("unroll") for (int k = 0; k < 2; ++k) dst[m][k] = *(const PG8_LAS bf16x8*)(lds + PG8_SA(b, h) + aoff + m * 2048 + k * 1024); } while (0)
; #define PG8_LDB(dst, b, h) do { _Pragma("unroll") for (int n = 0; n < 2; ++n) _Pragma("unroll") for (int k = 0; k < 2; ++k) dst[n][k] = *(const PG8_LAS bf16x8*)(lds + PG8_SB(b, h) + boff + n * 2048 + k * 1024); } while (0)
; #define PG8_MMA(ai, bj, At, Bt) do { __builtin_amdgcn_s_setprio(1); _Pragma("unroll") for (int m = 0; m < 4; ++m) _Pragma("unroll") for (int n = 0; n < 2; ++n) _Pragma("unroll") for (int k = 0; k < 2; ++k) \
;         acc[ai][bj][m][n] = __builtin_amdgcn_mfma_f32_16x16x32_bf16(Bt[n][k], At[m][k], acc[ai][bj][m][n], 0, 0, 0); __builtin_amdgcn_s_setprio(0); } while (0)
; #define PG8_WAIT_V(n) asm volatile("s_waitcnt vmcnt(" #n ")" ::: "memory")
; #define PG8_WAIT_L(n) asm volatile("s_waitcnt lgkmcnt(" #n ")" ::: "memory")
; #define PG8_BAR __builtin_amdgcn_s_barrier()
; #define PG8_SCHED __builtin_amdgcn_sched_barrier(0)
; template <class Epi, class Sched>
; __device__ __forceinline__ void gemm_phase(PG8_LAS unsigned char* lds, const Gemm g, const Sched& S, const Epi& E) {
;     ...
;             PG8_STAGE(PG8_SB(0, 1), b2 + hstep, voffB);
;             PG8_WAIT_V(6); PG8_BAR; PG8_MMA(1, 1, At, B1); PG8_BAR;
;             PG8_LDB(B0, 1, 0); PG8_SCHED; PG8_LDA(At, 1, 0); PG8_STAGE(PG8_SA(0, 1), a2 + hstep, voffA);
;             PG8_WAIT_L(8); PG8_BAR; PG8_WAIT_L(0); PG8_MMA(0, 0, At, B0); PG8_BAR; PG8_SCHED;
;             PG8_LDB(B1, 1, 1); PG8_STAGE(PG8_SB(1, 0), b3, voffB);
	s_add_u32 s48, s38, 0x40000
	s_addc_u32 s49, s39, 0
	s_add_i32 s30, s34, s3
	s_mov_b32 m0, s30
	v_lshl_add_u64 v[130:131], s[48:49], 0, v[168:169]
	global_load_lds_dwordx4 v[130:131], off
	s_add_i32 m0, s30, 0x2000
	v_lshl_add_u64 v[130:131], s[48:49], 0, v[164:165]
	global_load_lds_dwordx4 v[130:131], off
	s_waitcnt vmcnt(6)
	s_barrier
	s_setprio 1
	v_mfma_f32_16x16x32_bf16 v[52:55], v[222:225], v[146:149], v[52:55]
	v_mfma_f32_16x16x32_bf16 v[48:51], v[230:233], v[146:149], v[48:51]
	v_mfma_f32_16x16x32_bf16 v[36:39], v[222:225], v[196:199], v[36:39]
	v_mfma_f32_16x16x32_bf16 v[32:35], v[230:233], v[196:199], v[32:35]
	v_mfma_f32_16x16x32_bf16 v[20:23], v[222:225], v[206:209], v[20:23]
	v_mfma_f32_16x16x32_bf16 v[16:19], v[230:233], v[206:209], v[16:19]
	v_mfma_f32_16x16x32_bf16 v[4:7], v[222:225], v[214:217], v[4:7]
	v_mfma_f32_16x16x32_bf16 v[0:3], v[230:233], v[214:217], v[0:3]
	v_mfma_f32_16x16x32_bf16 v[52:55], v[226:229], v[192:195], v[52:55]
	v_mfma_f32_16x16x32_bf16 v[48:51], v[234:237], v[192:195], v[48:51]
	v_mfma_f32_16x16x32_bf16 v[36:39], v[226:229], v[200:203], v[36:39]
	v_mfma_f32_16x16x32_bf16 v[32:35], v[234:237], v[200:203], v[32:35]
	v_mfma_f32_16x16x32_bf16 v[20:23], v[226:229], v[210:213], v[20:23]
	v_mfma_f32_16x16x32_bf16 v[16:19], v[234:237], v[210:213], v[16:19]
	v_mfma_f32_16x16x32_bf16 v[4:7], v[226:229], v[218:221], v[4:7]
	v_mfma_f32_16x16x32_bf16 v[0:3], v[234:237], v[218:221], v[0:3]
	s_setprio 0
	s_add_i32 s30, 0, 0x18000
	v_add_u32_e32 v142, s30, v159
	s_barrier
	ds_read_b128 v[130:133], v142
	ds_read_b128 v[134:137], v142 offset:1024
	ds_read_b128 v[138:141], v142 offset:2048
	ds_read_b128 v[142:145], v142 offset:3072
	s_add_u32 s40, s40, 0x40000
	s_addc_u32 s41, s41, 0
	s_mov_b32 m0, s18
	v_lshl_add_u64 v[222:223], s[40:41], 0, v[170:171]
	ds_read_b128 v[146:149], v163 offset:32768
	ds_read_b128 v[192:195], v163 offset:33792
	ds_read_b128 v[196:199], v163 offset:34816
	ds_read_b128 v[200:203], v163 offset:35840
	ds_read_b128 v[206:209], v163 offset:36864
	ds_read_b128 v[210:213], v163 offset:37888
	ds_read_b128 v[214:217], v163 offset:38912
	ds_read_b128 v[218:221], v163 offset:39936
	global_load_lds_dwordx4 v[222:223], off
	s_mov_b32 m0, s19
	v_lshl_add_u64 v[222:223], s[40:41], 0, v[166:167]
	global_load_lds_dwordx4 v[222:223], off
	s_waitcnt lgkmcnt(8)
	s_barrier
	s_waitcnt lgkmcnt(0)
	s_setprio 1
	v_mfma_f32_16x16x32_bf16 v[124:127], v[130:133], v[146:149], v[124:127]
	v_mfma_f32_16x16x32_bf16 v[120:123], v[138:141], v[146:149], v[120:123]
	v_mfma_f32_16x16x32_bf16 v[108:111], v[130:133], v[196:199], v[108:111]
	v_mfma_f32_16x16x32_bf16 v[104:107], v[138:141], v[196:199], v[104:107]
	v_mfma_f32_16x16x32_bf16 v[92:95], v[130:133], v[206:209], v[92:95]
	v_mfma_f32_16x16x32_bf16 v[88:91], v[138:141], v[206:209], v[88:91]
	v_mfma_f32_16x16x32_bf16 v[76:79], v[130:133], v[214:217], v[76:79]
	v_mfma_f32_16x16x32_bf16 v[72:75], v[138:141], v[214:217], v[72:75]
	v_mfma_f32_16x16x32_bf16 v[124:127], v[134:137], v[192:195], v[124:127]
	v_mfma_f32_16x16x32_bf16 v[120:123], v[142:145], v[192:195], v[120:123]
	v_mfma_f32_16x16x32_bf16 v[108:111], v[134:137], v[200:203], v[108:111]
	v_mfma_f32_16x16x32_bf16 v[104:107], v[142:145], v[200:203], v[104:107]
	v_mfma_f32_16x16x32_bf16 v[92:95], v[134:137], v[210:213], v[92:95]
	v_mfma_f32_16x16x32_bf16 v[88:91], v[142:145], v[210:213], v[88:91]
	v_mfma_f32_16x16x32_bf16 v[76:79], v[134:137], v[218:221], v[76:79]
	v_mfma_f32_16x16x32_bf16 v[72:75], v[142:145], v[218:221], v[72:75]
	s_setprio 0
	s_barrier
	s_add_i32 s40, 0, 0x1c000
	s_add_i32 s30, s30, s3
	v_add_u32_e32 v205, s40, v159
	v_lshl_add_u64 v[150:151], v[150:151], 0, s[8:9]
	s_mov_b32 m0, s30
	ds_read_b128 v[222:225], v205
	ds_read_b128 v[226:229], v205 offset:1024
	ds_read_b128 v[230:233], v205 offset:2048
	ds_read_b128 v[234:237], v205 offset:3072
	global_load_lds_dwordx4 v[150:151], off
	s_add_i32 m0, s30, 0x2000
	v_lshl_add_u64 v[150:151], v[238:239], 0, s[8:9]
	global_load_lds_dwordx4 v[150:151], off
	s_barrier
; #define PG8_STAGE(bufoff, gbase, voff) do { _Pragma("unroll") for (int _i = 0; _i < 2; ++_i) \
;         __builtin_amdgcn_global_load_lds((const unsigned*)((const char*)(gbase) + (voff)[_i]), (PG8_LAS unsigned*)(lds + (bufoff) + ldsw + _i * 8192), 16, 0, 0); } while (0)
; #define PG8_LDA(dst, b, h) do { _Pragma("unroll") for (int m = 0; m < 4; ++m) _Pragma("unroll") for (int k = 0; k < 2; ++k) dst[m][k] = *(const PG8_LAS bf16x8*)(lds + PG8_SA(b, h) + aoff + m * 2048 + k * 1024); } while (0)
; #define PG8_MMA(ai, bj, At, Bt) do { __builtin_amdgcn_s_setprio(1); _Pragma("unroll") for (int m = 0; m < 4; ++m) _Pragma("unroll") for (int n = 0; n < 2; ++n) _Pragma("unroll") for (int k = 0; k < 2; ++k) \
;         acc[ai][bj][m][n] = __builtin_amdgcn_mfma_f32_16x16x32_bf16(Bt[n][k], At[m][k], acc[ai][bj][m][n], 0, 0, 0); __builtin_amdgcn_s_setprio(0); } while (0)
; #define PG8_WAIT_V(n) asm volatile("s_waitcnt vmcnt(" #n ")" ::: "memory")
; #define PG8_WAIT_L(n) asm volatile("s_waitcnt lgkmcnt(" #n ")" ::: "memory")
; #define PG8_BAR __builtin_amdgcn_s_barrier()
; #define PG8_SCHED __builtin_amdgcn_sched_barrier(0)
; template <class Epi, class Sched>
; __device__ __forceinline__ void gemm_phase(PG8_LAS unsigned char* lds, const Gemm g, const Sched& S, const Epi& E) {
;     ...
;         for (int t = 0; t < cnk; t += 2) {
;     ...
;             PG8_BAR; PG8_WAIT_L(0); PG8_MMA(0, 1, At, B1); PG8_BAR;
;             PG8_LDA(At, 1, 1); PG8_STAGE(PG8_SA(1, 0), a3, voffA);
;             PG8_BAR; PG8_WAIT_L(0); PG8_MMA(1, 0, At, B0); PG8_BAR; PG8_SCHED;
;             PG8_STAGE(PG8_SB(1, 1), b3 + hstep, voffB);
;             PG8_WAIT_V(6); PG8_BAR; PG8_MMA(1, 1, At, B1); PG8_BAR;
;         }
	s_waitcnt lgkmcnt(0)
	s_setprio 1
	v_mfma_f32_16x16x32_bf16 v[116:119], v[222:225], v[146:149], v[116:119]
	v_mfma_f32_16x16x32_bf16 v[112:115], v[230:233], v[146:149], v[112:115]
	v_mfma_f32_16x16x32_bf16 v[100:103], v[222:225], v[196:199], v[100:103]
	v_mfma_f32_16x16x32_bf16 v[96:99], v[230:233], v[196:199], v[96:99]
	v_mfma_f32_16x16x32_bf16 v[84:87], v[222:225], v[206:209], v[84:87]
	v_mfma_f32_16x16x32_bf16 v[80:83], v[230:233], v[206:209], v[80:83]
	v_mfma_f32_16x16x32_bf16 v[68:71], v[222:225], v[214:217], v[68:71]
	v_mfma_f32_16x16x32_bf16 v[64:67], v[230:233], v[214:217], v[64:67]
	v_mfma_f32_16x16x32_bf16 v[116:119], v[226:229], v[192:195], v[116:119]
	v_mfma_f32_16x16x32_bf16 v[112:115], v[234:237], v[192:195], v[112:115]
	v_mfma_f32_16x16x32_bf16 v[100:103], v[226:229], v[200:203], v[100:103]
	v_mfma_f32_16x16x32_bf16 v[96:99], v[234:237], v[200:203], v[96:99]
	v_mfma_f32_16x16x32_bf16 v[84:87], v[226:229], v[210:213], v[84:87]
	v_mfma_f32_16x16x32_bf16 v[80:83], v[234:237], v[210:213], v[80:83]
	v_mfma_f32_16x16x32_bf16 v[68:71], v[226:229], v[218:221], v[68:71]
	v_mfma_f32_16x16x32_bf16 v[64:67], v[234:237], v[218:221], v[64:67]
	s_setprio 0
	s_mov_b32 m0, s25
	v_lshl_add_u64 v[150:151], v[240:241], 0, s[8:9]
	s_barrier
	ds_read_b128 v[146:149], v163 offset:49152
	ds_read_b128 v[192:195], v163 offset:50176
	ds_read_b128 v[196:199], v163 offset:51200
	ds_read_b128 v[200:203], v163 offset:52224
	ds_read_b128 v[206:209], v163 offset:53248
	ds_read_b128 v[210:213], v163 offset:54272
	ds_read_b128 v[214:217], v163 offset:55296
	ds_read_b128 v[218:221], v163 offset:56320
	global_load_lds_dwordx4 v[150:151], off
	s_mov_b32 m0, s29
	v_lshl_add_u64 v[150:151], v[242:243], 0, s[8:9]
	global_load_lds_dwordx4 v[150:151], off
	s_barrier
	s_waitcnt lgkmcnt(0)
	s_setprio 1
	v_mfma_f32_16x16x32_bf16 v[60:63], v[130:133], v[146:149], v[60:63]
	v_mfma_f32_16x16x32_bf16 v[56:59], v[138:141], v[146:149], v[56:59]
	v_mfma_f32_16x16x32_bf16 v[44:47], v[130:133], v[196:199], v[44:47]
	v_mfma_f32_16x16x32_bf16 v[40:43], v[138:141], v[196:199], v[40:43]
	v_mfma_f32_16x16x32_bf16 v[28:31], v[130:133], v[206:209], v[28:31]
	v_mfma_f32_16x16x32_bf16 v[24:27], v[138:141], v[206:209], v[24:27]
	v_mfma_f32_16x16x32_bf16 v[12:15], v[130:133], v[214:217], v[12:15]
	v_mfma_f32_16x16x32_bf16 v[8:11], v[138:141], v[214:217], v[8:11]
	v_mfma_f32_16x16x32_bf16 v[60:63], v[134:137], v[192:195], v[60:63]
	v_mfma_f32_16x16x32_bf16 v[56:59], v[142:145], v[192:195], v[56:59]
	v_mfma_f32_16x16x32_bf16 v[44:47], v[134:137], v[200:203], v[44:47]
	v_mfma_f32_16x16x32_bf16 v[40:43], v[142:145], v[200:203], v[40:43]
	v_mfma_f32_16x16x32_bf16 v[28:31], v[134:137], v[210:213], v[28:31]
	v_mfma_f32_16x16x32_bf16 v[24:27], v[142:145], v[210:213], v[24:27]
	v_mfma_f32_16x16x32_bf16 v[12:15], v[134:137], v[218:221], v[12:15]
	v_mfma_f32_16x16x32_bf16 v[8:11], v[142:145], v[218:221], v[8:11]
	s_setprio 0
	s_barrier
	s_add_u32 s38, s38, 0x40080
	s_addc_u32 s39, s39, 0
	s_add_i32 s30, s40, s3
	s_mov_b32 m0, s30
	v_lshl_add_u64 v[130:131], s[38:39], 0, v[168:169]
	global_load_lds_dwordx4 v[130:131], off
	s_add_i32 m0, s30, 0x2000
	v_lshl_add_u64 v[130:131], s[38:39], 0, v[164:165]
	global_load_lds_dwordx4 v[130:131], off
	s_waitcnt vmcnt(6)
	s_barrier
	s_setprio 1
	v_mfma_f32_16x16x32_bf16 v[52:55], v[222:225], v[146:149], v[52:55]
	v_mfma_f32_16x16x32_bf16 v[48:51], v[230:233], v[146:149], v[48:51]
	v_mfma_f32_16x16x32_bf16 v[36:39], v[222:225], v[196:199], v[36:39]
	v_mfma_f32_16x16x32_bf16 v[32:35], v[230:233], v[196:199], v[32:35]
	v_mfma_f32_16x16x32_bf16 v[20:23], v[222:225], v[206:209], v[20:23]
	v_mfma_f32_16x16x32_bf16 v[16:19], v[230:233], v[206:209], v[16:19]
	v_mfma_f32_16x16x32_bf16 v[4:7], v[222:225], v[214:217], v[4:7]
	v_mfma_f32_16x16x32_bf16 v[0:3], v[230:233], v[214:217], v[0:3]
	v_mfma_f32_16x16x32_bf16 v[52:55], v[226:229], v[192:195], v[52:55]
	v_mfma_f32_16x16x32_bf16 v[48:51], v[234:237], v[192:195], v[48:51]
	v_mfma_f32_16x16x32_bf16 v[36:39], v[226:229], v[200:203], v[36:39]
	v_mfma_f32_16x16x32_bf16 v[32:35], v[234:237], v[200:203], v[32:35]
	v_mfma_f32_16x16x32_bf16 v[20:23], v[226:229], v[210:213], v[20:23]
	v_mfma_f32_16x16x32_bf16 v[16:19], v[234:237], v[210:213], v[16:19]
	v_mfma_f32_16x16x32_bf16 v[4:7], v[226:229], v[218:221], v[4:7]
	v_mfma_f32_16x16x32_bf16 v[0:3], v[234:237], v[218:221], v[0:3]
	s_setprio 0
	s_add_i32 s47, s47, 2
	s_add_u32 s4, s4, 0x100
	s_addc_u32 s5, s5, 0
	s_add_u32 s45, s45, 0x100
	s_addc_u32 s46, s46, 0
	s_cmp_lt_u32 s47, 14
	s_barrier
	s_cbranch_scc0 .LBB0_1512

; #define PG8_STAGE(bufoff, gbase, voff) do { _Pragma("unroll") for (int _i = 0; _i < 2; ++_i) \
;         __builtin_amdgcn_global_load_lds((const unsigned*)((const char*)(gbase) + (voff)[_i]), (PG8_LAS unsigned*)(lds + (bufoff) + ldsw + _i * 8192), 16, 0, 0); } while (0)
; #define PG8_LDA(dst, b, h) do { _Pragma("unroll") for (int m = 0; m < 4; ++m) _Pragma("unroll") for (int k = 0; k < 2; ++k) dst[m][k] = *(const PG8_LAS bf16x8*)(lds + PG8_SA(b, h) + aoff + m * 2048 + k * 1024); } while (0)
; #define PG8_LDB(dst, b, h) do { _Pragma("unroll") for (int n = 0; n < 2; ++n) _Pragma("unroll") for (int k = 0; k < 2; ++k) dst[n][k] = *(const PG8_LAS bf16x8*)(lds + PG8_SB(b, h) + boff + n * 2048 + k * 1024); } while (0)
; #define PG8_MMA(ai, bj, At, Bt) do { __builtin_amdgcn_s_setprio(1); _Pragma("unroll") for (int m = 0; m < 4; ++m) _Pragma("unroll") for (int n = 0; n < 2; ++n) _Pragma("unroll") for (int k = 0; k < 2; ++k) \
;         acc[ai][bj][m][n] = __builtin_amdgcn_mfma_f32_16x16x32_bf16(Bt[n][k], At[m][k], acc[ai][bj][m][n], 0, 0, 0); __builtin_amdgcn_s_setprio(0); } while (0)
; #define PG8_WAIT_L(n) asm volatile("s_waitcnt lgkmcnt(" #n ")" ::: "memory")
; #define PG8_BAR __builtin_amdgcn_s_barrier()
; #define PG8_SCHED __builtin_amdgcn_sched_barrier(0)
; template <class Epi, class Sched>
; __device__ __forceinline__ void gemm_phase(PG8_LAS unsigned char* lds, const Gemm g, const Sched& S, const Epi& E) {
;     ...
;             const bool last = (t == cnk - 2);
;             const char* a1 = cA + (size_t)(t + 1) * kstep;
;             const char* a2 = last ? nA : cA + (size_t)(t + 2) * kstep; const char* b2 = last ? nB : cB + (size_t)(t + 2) * kstep;
;             const char* a3 = a2 + kstep; const char* b3 = b2 + kstep;
;             if (last && has_next) S.a_ready(nxt);
;             if (last) E.prefetch(pre, cur, wr, fr);
;             PG8_LDB(B0, 0, 0); PG8_SCHED; PG8_LDA(At, 0, 0); PG8_STAGE(PG8_SA(1, 1), a1 + hstep, voffA);
;             PG8_WAIT_L(8); PG8_BAR; PG8_WAIT_L(0); PG8_MMA(0, 0, At, B0); PG8_BAR; PG8_SCHED;
;             PG8_LDB(B1, 0, 1); PG8_STAGE(PG8_SB(0, 0), b2, voffB);
;             PG8_BAR; PG8_WAIT_L(0); PG8_MMA(0, 1, At, B1); PG8_BAR;
;             PG8_LDA(At, 0, 1); PG8_STAGE(PG8_SA(0, 0), a2, voffA);
;             PG8_BAR; PG8_WAIT_L(0); PG8_MMA(1, 0, At, B0); PG8_BAR; PG8_SCHED;
.LBB0_1636:
	ds_read_b128 v[128:131], v163
	ds_read_b128 v[132:135], v163 offset:1024
	ds_read_b128 v[136:139], v163 offset:2048
	ds_read_b128 v[140:143], v163 offset:3072
	s_add_i32 s76, s45, 2
	s_add_u32 s30, s48, 0xfff00080
	s_addc_u32 s50, s49, -1
	s_cmp_eq_u32 s27, s45
	s_cselect_b32 s53, s43, s50
	s_cselect_b32 s52, s42, s30
	s_cselect_b32 s51, s47, s39
	s_cselect_b32 s50, s46, s37
	v_lshl_add_u64 v[196:197], s[48:49], 0, v[174:175]
	s_add_i32 m0, s5, 0xc000
	ds_read_b128 v[144:147], v198
	ds_read_b128 v[148:151], v198 offset:1024
	ds_read_b128 v[180:183], v198 offset:2048
	ds_read_b128 v[184:187], v198 offset:3072
	ds_read_b128 v[188:191], v198 offset:4096
	ds_read_b128 v[192:195], v198 offset:5120
	ds_read_b128 v[202:205], v198 offset:6144
	ds_read_b128 v[206:209], v198 offset:7168
	global_load_lds_dwordx4 v[196:197], off
	s_add_i32 m0, s5, 0xe000
	v_lshl_add_u64 v[196:197], s[48:49], 0, v[176:177]
	global_load_lds_dwordx4 v[196:197], off
	s_waitcnt lgkmcnt(8)
	s_barrier
	s_waitcnt lgkmcnt(0)
	s_setprio 1
	v_mfma_f32_16x16x32_bf16 v[124:127], v[128:131], v[144:147], v[124:127]
	v_mfma_f32_16x16x32_bf16 v[120:123], v[136:139], v[144:147], v[120:123]
	v_mfma_f32_16x16x32_bf16 v[108:111], v[128:131], v[180:183], v[108:111]
	v_mfma_f32_16x16x32_bf16 v[104:107], v[136:139], v[180:183], v[104:107]
	v_mfma_f32_16x16x32_bf16 v[92:95], v[128:131], v[188:191], v[92:95]
	v_mfma_f32_16x16x32_bf16 v[88:91], v[136:139], v[188:191], v[88:91]
	v_mfma_f32_16x16x32_bf16 v[76:79], v[128:131], v[202:205], v[76:79]
	v_mfma_f32_16x16x32_bf16 v[72:75], v[136:139], v[202:205], v[72:75]
	v_mfma_f32_16x16x32_bf16 v[124:127], v[132:135], v[148:151], v[124:127]
	v_mfma_f32_16x16x32_bf16 v[120:123], v[140:143], v[148:151], v[120:123]
	v_mfma_f32_16x16x32_bf16 v[108:111], v[132:135], v[184:187], v[108:111]
	v_mfma_f32_16x16x32_bf16 v[104:107], v[140:143], v[184:187], v[104:107]
	v_mfma_f32_16x16x32_bf16 v[92:95], v[132:135], v[192:195], v[92:95]
	v_mfma_f32_16x16x32_bf16 v[88:91], v[140:143], v[192:195], v[88:91]
	v_mfma_f32_16x16x32_bf16 v[76:79], v[132:135], v[206:209], v[76:79]
	v_mfma_f32_16x16x32_bf16 v[72:75], v[140:143], v[206:209], v[72:75]
	s_setprio 0
	s_barrier
	s_add_i32 s30, s71, s4
	v_lshl_add_u64 v[196:197], s[50:51], 0, v[166:167]
	s_mov_b32 m0, s30
	ds_read_b128 v[210:213], v199
	ds_read_b128 v[214:217], v199 offset:1024
	ds_read_b128 v[218:221], v199 offset:2048
	ds_read_b128 v[222:225], v199 offset:3072
	global_load_lds_dwordx4 v[196:197], off
	s_add_i32 m0, s30, 0x2000
	v_lshl_add_u64 v[226:227], s[50:51], 0, v[170:171]
	global_load_lds_dwordx4 v[226:227], off
	s_barrier
	s_waitcnt lgkmcnt(0)
	s_setprio 1
	v_mfma_f32_16x16x32_bf16 v[116:119], v[210:213], v[144:147], v[116:119]
	v_mfma_f32_16x16x32_bf16 v[112:115], v[218:221], v[144:147], v[112:115]
	v_mfma_f32_16x16x32_bf16 v[100:103], v[210:213], v[180:183], v[100:103]
	v_mfma_f32_16x16x32_bf16 v[96:99], v[218:221], v[180:183], v[96:99]
	v_mfma_f32_16x16x32_bf16 v[84:87], v[210:213], v[188:191], v[84:87]
	v_mfma_f32_16x16x32_bf16 v[80:83], v[218:221], v[188:191], v[80:83]
	v_mfma_f32_16x16x32_bf16 v[68:71], v[210:213], v[202:205], v[68:71]
	v_mfma_f32_16x16x32_bf16 v[64:67], v[218:221], v[202:205], v[64:67]
	v_mfma_f32_16x16x32_bf16 v[116:119], v[214:217], v[148:151], v[116:119]
	v_mfma_f32_16x16x32_bf16 v[112:115], v[222:225], v[148:151], v[112:115]
	v_mfma_f32_16x16x32_bf16 v[100:103], v[214:217], v[184:187], v[100:103]
	v_mfma_f32_16x16x32_bf16 v[96:99], v[222:225], v[184:187], v[96:99]
	v_mfma_f32_16x16x32_bf16 v[84:87], v[214:217], v[192:195], v[84:87]
	v_mfma_f32_16x16x32_bf16 v[80:83], v[222:225], v[192:195], v[80:83]
	v_mfma_f32_16x16x32_bf16 v[68:71], v[214:217], v[206:209], v[68:71]
	v_mfma_f32_16x16x32_bf16 v[64:67], v[222:225], v[206:209], v[64:67]
	s_setprio 0
	s_mov_b32 m0, s5
	v_lshl_add_u64 v[228:229], s[52:53], 0, v[164:165]
	s_barrier
	ds_read_b128 v[144:147], v198 offset:16384
	ds_read_b128 v[148:151], v198 offset:17408
	ds_read_b128 v[180:183], v198 offset:18432
	ds_read_b128 v[184:187], v198 offset:19456
	ds_read_b128 v[188:191], v198 offset:20480
	ds_read_b128 v[192:195], v198 offset:21504
	ds_read_b128 v[202:205], v198 offset:22528
	ds_read_b128 v[206:209], v198 offset:23552
	global_load_lds_dwordx4 v[228:229], off
	s_mov_b32 m0, s16
	v_lshl_add_u64 v[230:231], s[52:53], 0, v[168:169]
	global_load_lds_dwordx4 v[230:231], off
	s_barrier
	s_waitcnt lgkmcnt(0)
	s_setprio 1
	v_mfma_f32_16x16x32_bf16 v[60:63], v[128:131], v[144:147], v[60:63]
	v_mfma_f32_16x16x32_bf16 v[56:59], v[136:139], v[144:147], v[56:59]
	v_mfma_f32_16x16x32_bf16 v[44:47], v[128:131], v[180:183], v[44:47]
	v_mfma_f32_16x16x32_bf16 v[40:43], v[136:139], v[180:183], v[40:43]
	v_mfma_f32_16x16x32_bf16 v[28:31], v[128:131], v[188:191], v[28:31]
	v_mfma_f32_16x16x32_bf16 v[24:27], v[136:139], v[188:191], v[24:27]
	v_mfma_f32_16x16x32_bf16 v[12:15], v[128:131], v[202:205], v[12:15]
	v_mfma_f32_16x16x32_bf16 v[8:11], v[136:139], v[202:205], v[8:11]
	v_mfma_f32_16x16x32_bf16 v[60:63], v[132:135], v[148:151], v[60:63]
	v_mfma_f32_16x16x32_bf16 v[56:59], v[140:143], v[148:151], v[56:59]
	v_mfma_f32_16x16x32_bf16 v[44:47], v[132:135], v[184:187], v[44:47]
	v_mfma_f32_16x16x32_bf16 v[40:43], v[140:143], v[184:187], v[40:43]
	v_mfma_f32_16x16x32_bf16 v[28:31], v[132:135], v[192:195], v[28:31]
	v_mfma_f32_16x16x32_bf16 v[24:27], v[140:143], v[192:195], v[24:27]
	v_mfma_f32_16x16x32_bf16 v[12:15], v[132:135], v[206:209], v[12:15]
	v_mfma_f32_16x16x32_bf16 v[8:11], v[140:143], v[206:209], v[8:11]
	s_setprio 0
	s_barrier
; #define PG8_STAGE(bufoff, gbase, voff) do { _Pragma("unroll") for (int _i = 0; _i < 2; ++_i) \
;         __builtin_amdgcn_global_load_lds((const unsigned*)((const char*)(gbase) + (voff)[_i]), (PG8_LAS unsigned*)(lds + (bufoff) + ldsw + _i * 8192), 16, 0, 0); } while (0)
; #define PG8_LDA(dst, b, h) do { _Pragma("unroll") for (int m = 0; m < 4; ++m) _Pragma("unroll") for (int k = 0; k < 2; ++k) dst[m][k] = *(const PG8_LAS bf16x8*)(lds + PG8_SA(b, h) + aoff + m * 2048 + k * 1024); } while (0)
; #define PG8_LDB(dst, b, h) do { _Pragma("unroll") for (int n = 0; n < 2; ++n) _Pragma("unroll") for (int k = 0; k < 2; ++k) dst[n][k] = *(const PG8_LAS bf16x8*)(lds + PG8_SB(b, h) + boff + n * 2048 + k * 1024); } while (0)
; #define PG8_MMA(ai, bj, At, Bt) do { __builtin_amdgcn_s_setprio(1); _Pragma("unroll") for (int m = 0; m < 4; ++m) _Pragma("unroll") for (int n = 0; n < 2; ++n) _Pragma("unroll") for (int k = 0; k < 2; ++k) \
;         acc[ai][bj][m][n] = __builtin_amdgcn_mfma_f32_16x16x32_bf16(Bt[n][k], At[m][k], acc[ai][bj][m][n], 0, 0, 0); __builtin_amdgcn_s_setprio(0); } while (0)
; #define PG8_WAIT_V(n) asm volatile("s_waitcnt vmcnt(" #n ")" ::: "memory")
; #define PG8_WAIT_L(n) asm volatile("s_waitcnt lgkmcnt(" #n ")" ::: "memory")
; #define PG8_BAR __builtin_amdgcn_s_barrier()
; #define PG8_SCHED __builtin_amdgcn_sched_barrier(0)
; template <class Epi, class Sched>
; __device__ __forceinline__ void gemm_phase(PG8_LAS unsigned char* lds, const Gemm g, const Sched& S, const Epi& E) {
;     ...
;             PG8_STAGE(PG8_SB(0, 1), b2 + hstep, voffB);
;             PG8_WAIT_V(6); PG8_BAR; PG8_MMA(1, 1, At, B1); PG8_BAR;
;             PG8_LDB(B0, 1, 0); PG8_SCHED; PG8_LDA(At, 1, 0); PG8_STAGE(PG8_SA(0, 1), a2 + hstep, voffA);
;             PG8_WAIT_L(8); PG8_BAR; PG8_WAIT_L(0); PG8_MMA(0, 0, At, B0); PG8_BAR; PG8_SCHED;
;             PG8_LDB(B1, 1, 1); PG8_STAGE(PG8_SB(1, 0), b3, voffB);
	s_add_u32 s96, s50, 0x100000
	s_addc_u32 s97, s51, 0
	s_add_i32 s30, s72, s4
	s_mov_b32 m0, s30
	v_lshl_add_u64 v[128:129], s[96:97], 0, v[166:167]
	global_load_lds_dwordx4 v[128:129], off
	s_add_i32 m0, s30, 0x2000
	v_lshl_add_u64 v[128:129], s[96:97], 0, v[170:171]
	global_load_lds_dwordx4 v[128:129], off
	s_waitcnt vmcnt(6)
	s_barrier
	s_setprio 1
	v_mfma_f32_16x16x32_bf16 v[52:55], v[210:213], v[144:147], v[52:55]
	v_mfma_f32_16x16x32_bf16 v[48:51], v[218:221], v[144:147], v[48:51]
	v_mfma_f32_16x16x32_bf16 v[36:39], v[210:213], v[180:183], v[36:39]
	v_mfma_f32_16x16x32_bf16 v[32:35], v[218:221], v[180:183], v[32:35]
	v_mfma_f32_16x16x32_bf16 v[20:23], v[210:213], v[188:191], v[20:23]
	v_mfma_f32_16x16x32_bf16 v[16:19], v[218:221], v[188:191], v[16:19]
	v_mfma_f32_16x16x32_bf16 v[4:7], v[210:213], v[202:205], v[4:7]
	v_mfma_f32_16x16x32_bf16 v[0:3], v[218:221], v[202:205], v[0:3]
	v_mfma_f32_16x16x32_bf16 v[52:55], v[214:217], v[148:151], v[52:55]
	v_mfma_f32_16x16x32_bf16 v[48:51], v[222:225], v[148:151], v[48:51]
	v_mfma_f32_16x16x32_bf16 v[36:39], v[214:217], v[184:187], v[36:39]
	v_mfma_f32_16x16x32_bf16 v[32:35], v[222:225], v[184:187], v[32:35]
	v_mfma_f32_16x16x32_bf16 v[20:23], v[214:217], v[192:195], v[20:23]
	v_mfma_f32_16x16x32_bf16 v[16:19], v[222:225], v[192:195], v[16:19]
	v_mfma_f32_16x16x32_bf16 v[4:7], v[214:217], v[206:209], v[4:7]
	v_mfma_f32_16x16x32_bf16 v[0:3], v[222:225], v[206:209], v[0:3]
	s_setprio 0
	s_add_i32 s30, 0, 0x18000
	v_add_u32_e32 v140, s30, v159
	s_barrier
	ds_read_b128 v[128:131], v140
	ds_read_b128 v[132:135], v140 offset:1024
	ds_read_b128 v[136:139], v140 offset:2048
	ds_read_b128 v[140:143], v140 offset:3072
	s_add_u32 s52, s52, 0x100000
	s_addc_u32 s53, s53, 0
	s_mov_b32 m0, s17
	v_lshl_add_u64 v[210:211], s[52:53], 0, v[164:165]
	ds_read_b128 v[144:147], v198 offset:32768
	ds_read_b128 v[148:151], v198 offset:33792
	ds_read_b128 v[180:183], v198 offset:34816
	ds_read_b128 v[184:187], v198 offset:35840
	ds_read_b128 v[188:191], v198 offset:36864
	ds_read_b128 v[192:195], v198 offset:37888
	ds_read_b128 v[202:205], v198 offset:38912
	ds_read_b128 v[206:209], v198 offset:39936
	global_load_lds_dwordx4 v[210:211], off
	s_mov_b32 m0, s18
	v_lshl_add_u64 v[210:211], s[52:53], 0, v[168:169]
	global_load_lds_dwordx4 v[210:211], off
	s_waitcnt lgkmcnt(8)
	s_barrier
	s_waitcnt lgkmcnt(0)
	s_setprio 1
	v_mfma_f32_16x16x32_bf16 v[124:127], v[128:131], v[144:147], v[124:127]
	v_mfma_f32_16x16x32_bf16 v[120:123], v[136:139], v[144:147], v[120:123]
	v_mfma_f32_16x16x32_bf16 v[108:111], v[128:131], v[180:183], v[108:111]
	v_mfma_f32_16x16x32_bf16 v[104:107], v[136:139], v[180:183], v[104:107]
	v_mfma_f32_16x16x32_bf16 v[92:95], v[128:131], v[188:191], v[92:95]
	v_mfma_f32_16x16x32_bf16 v[88:91], v[136:139], v[188:191], v[88:91]
	v_mfma_f32_16x16x32_bf16 v[76:79], v[128:131], v[202:205], v[76:79]
	v_mfma_f32_16x16x32_bf16 v[72:75], v[136:139], v[202:205], v[72:75]
	v_mfma_f32_16x16x32_bf16 v[124:127], v[132:135], v[148:151], v[124:127]
	v_mfma_f32_16x16x32_bf16 v[120:123], v[140:143], v[148:151], v[120:123]
	v_mfma_f32_16x16x32_bf16 v[108:111], v[132:135], v[184:187], v[108:111]
	v_mfma_f32_16x16x32_bf16 v[104:107], v[140:143], v[184:187], v[104:107]
	v_mfma_f32_16x16x32_bf16 v[92:95], v[132:135], v[192:195], v[92:95]
	v_mfma_f32_16x16x32_bf16 v[88:91], v[140:143], v[192:195], v[88:91]
	v_mfma_f32_16x16x32_bf16 v[76:79], v[132:135], v[206:209], v[76:79]
	v_mfma_f32_16x16x32_bf16 v[72:75], v[140:143], v[206:209], v[72:75]
	s_setprio 0
	s_barrier
	s_add_i32 s45, 0, 0x1c000
	s_add_i32 s30, s30, s4
	v_add_u32_e32 v201, s45, v159
	v_lshl_add_u64 v[196:197], v[196:197], 0, s[14:15]
	s_mov_b32 m0, s30
	ds_read_b128 v[210:213], v201
	ds_read_b128 v[214:217], v201 offset:1024
	ds_read_b128 v[218:221], v201 offset:2048
	ds_read_b128 v[222:225], v201 offset:3072
	global_load_lds_dwordx4 v[196:197], off
	s_add_i32 m0, s30, 0x2000
	v_lshl_add_u64 v[196:197], v[226:227], 0, s[14:15]
	global_load_lds_dwordx4 v[196:197], off
	s_barrier
; #define PG8_STAGE(bufoff, gbase, voff) do { _Pragma("unroll") for (int _i = 0; _i < 2; ++_i) \
;         __builtin_amdgcn_global_load_lds((const unsigned*)((const char*)(gbase) + (voff)[_i]), (PG8_LAS unsigned*)(lds + (bufoff) + ldsw + _i * 8192), 16, 0, 0); } while (0)
; #define PG8_LDA(dst, b, h) do { _Pragma("unroll") for (int m = 0; m < 4; ++m) _Pragma("unroll") for (int k = 0; k < 2; ++k) dst[m][k] = *(const PG8_LAS bf16x8*)(lds + PG8_SA(b, h) + aoff + m * 2048 + k * 1024); } while (0)
; #define PG8_MMA(ai, bj, At, Bt) do { __builtin_amdgcn_s_setprio(1); _Pragma("unroll") for (int m = 0; m < 4; ++m) _Pragma("unroll") for (int n = 0; n < 2; ++n) _Pragma("unroll") for (int k = 0; k < 2; ++k) \
;         acc[ai][bj][m][n] = __builtin_amdgcn_mfma_f32_16x16x32_bf16(Bt[n][k], At[m][k], acc[ai][bj][m][n], 0, 0, 0); __builtin_amdgcn_s_setprio(0); } while (0)
; #define PG8_WAIT_V(n) asm volatile("s_waitcnt vmcnt(" #n ")" ::: "memory")
; #define PG8_WAIT_L(n) asm volatile("s_waitcnt lgkmcnt(" #n ")" ::: "memory")
; #define PG8_BAR __builtin_amdgcn_s_barrier()
; #define PG8_SCHED __builtin_amdgcn_sched_barrier(0)
; template <class Epi, class Sched>
; __device__ __forceinline__ void gemm_phase(PG8_LAS unsigned char* lds, const Gemm g, const Sched& S, const Epi& E) {
;     ...
;         for (int t = 0; t < cnk; t += 2) {
;     ...
;             PG8_BAR; PG8_WAIT_L(0); PG8_MMA(0, 1, At, B1); PG8_BAR;
;             PG8_LDA(At, 1, 1); PG8_STAGE(PG8_SA(1, 0), a3, voffA);
;             PG8_BAR; PG8_WAIT_L(0); PG8_MMA(1, 0, At, B0); PG8_BAR; PG8_SCHED;
;             PG8_STAGE(PG8_SB(1, 1), b3 + hstep, voffB);
;             PG8_WAIT_V(6); PG8_BAR; PG8_MMA(1, 1, At, B1); PG8_BAR;
;         }
	s_waitcnt lgkmcnt(0)
	s_setprio 1
	v_mfma_f32_16x16x32_bf16 v[116:119], v[210:213], v[144:147], v[116:119]
	v_mfma_f32_16x16x32_bf16 v[112:115], v[218:221], v[144:147], v[112:115]
	v_mfma_f32_16x16x32_bf16 v[100:103], v[210:213], v[180:183], v[100:103]
	v_mfma_f32_16x16x32_bf16 v[96:99], v[218:221], v[180:183], v[96:99]
	v_mfma_f32_16x16x32_bf16 v[84:87], v[210:213], v[188:191], v[84:87]
	v_mfma_f32_16x16x32_bf16 v[80:83], v[218:221], v[188:191], v[80:83]
	v_mfma_f32_16x16x32_bf16 v[68:71], v[210:213], v[202:205], v[68:71]
	v_mfma_f32_16x16x32_bf16 v[64:67], v[218:221], v[202:205], v[64:67]
	v_mfma_f32_16x16x32_bf16 v[116:119], v[214:217], v[148:151], v[116:119]
	v_mfma_f32_16x16x32_bf16 v[112:115], v[222:225], v[148:151], v[112:115]
	v_mfma_f32_16x16x32_bf16 v[100:103], v[214:217], v[184:187], v[100:103]
	v_mfma_f32_16x16x32_bf16 v[96:99], v[222:225], v[184:187], v[96:99]
	v_mfma_f32_16x16x32_bf16 v[84:87], v[214:217], v[192:195], v[84:87]
	v_mfma_f32_16x16x32_bf16 v[80:83], v[222:225], v[192:195], v[80:83]
	v_mfma_f32_16x16x32_bf16 v[68:71], v[214:217], v[206:209], v[68:71]
	v_mfma_f32_16x16x32_bf16 v[64:67], v[222:225], v[206:209], v[64:67]
	s_setprio 0
	s_mov_b32 m0, s24
	v_lshl_add_u64 v[196:197], v[228:229], 0, s[14:15]
	s_barrier
	ds_read_b128 v[144:147], v198 offset:49152
	ds_read_b128 v[148:151], v198 offset:50176
	ds_read_b128 v[180:183], v198 offset:51200
	ds_read_b128 v[184:187], v198 offset:52224
	ds_read_b128 v[188:191], v198 offset:53248
	ds_read_b128 v[192:195], v198 offset:54272
	ds_read_b128 v[202:205], v198 offset:55296
	ds_read_b128 v[206:209], v198 offset:56320
	global_load_lds_dwordx4 v[196:197], off
	s_mov_b32 m0, s25
	v_lshl_add_u64 v[196:197], v[230:231], 0, s[14:15]
	global_load_lds_dwordx4 v[196:197], off
	s_barrier
	s_waitcnt lgkmcnt(0)
	s_setprio 1
	v_mfma_f32_16x16x32_bf16 v[60:63], v[128:131], v[144:147], v[60:63]
	v_mfma_f32_16x16x32_bf16 v[56:59], v[136:139], v[144:147], v[56:59]
	v_mfma_f32_16x16x32_bf16 v[44:47], v[128:131], v[180:183], v[44:47]
	v_mfma_f32_16x16x32_bf16 v[40:43], v[136:139], v[180:183], v[40:43]
	v_mfma_f32_16x16x32_bf16 v[28:31], v[128:131], v[188:191], v[28:31]
	v_mfma_f32_16x16x32_bf16 v[24:27], v[136:139], v[188:191], v[24:27]
	v_mfma_f32_16x16x32_bf16 v[12:15], v[128:131], v[202:205], v[12:15]
	v_mfma_f32_16x16x32_bf16 v[8:11], v[136:139], v[202:205], v[8:11]
	v_mfma_f32_16x16x32_bf16 v[60:63], v[132:135], v[148:151], v[60:63]
	v_mfma_f32_16x16x32_bf16 v[56:59], v[140:143], v[148:151], v[56:59]
	v_mfma_f32_16x16x32_bf16 v[44:47], v[132:135], v[184:187], v[44:47]
	v_mfma_f32_16x16x32_bf16 v[40:43], v[140:143], v[184:187], v[40:43]
	v_mfma_f32_16x16x32_bf16 v[28:31], v[132:135], v[192:195], v[28:31]
	v_mfma_f32_16x16x32_bf16 v[24:27], v[140:143], v[192:195], v[24:27]
	v_mfma_f32_16x16x32_bf16 v[12:15], v[132:135], v[206:209], v[12:15]
	v_mfma_f32_16x16x32_bf16 v[8:11], v[140:143], v[206:209], v[8:11]
	s_setprio 0
	s_barrier
	s_add_u32 s50, s50, 0x100080
	s_addc_u32 s51, s51, 0
	s_add_i32 s30, s45, s4
	s_mov_b32 m0, s30
	v_lshl_add_u64 v[128:129], s[50:51], 0, v[166:167]
	global_load_lds_dwordx4 v[128:129], off
	s_add_i32 m0, s30, 0x2000
	v_lshl_add_u64 v[128:129], s[50:51], 0, v[170:171]
	global_load_lds_dwordx4 v[128:129], off
	s_waitcnt vmcnt(6)
	s_barrier
	s_setprio 1
	v_mfma_f32_16x16x32_bf16 v[52:55], v[210:213], v[144:147], v[52:55]
	v_mfma_f32_16x16x32_bf16 v[48:51], v[218:221], v[144:147], v[48:51]
	v_mfma_f32_16x16x32_bf16 v[36:39], v[210:213], v[180:183], v[36:39]
	v_mfma_f32_16x16x32_bf16 v[32:35], v[218:221], v[180:183], v[32:35]
	v_mfma_f32_16x16x32_bf16 v[20:23], v[210:213], v[188:191], v[20:23]
	v_mfma_f32_16x16x32_bf16 v[16:19], v[218:221], v[188:191], v[16:19]
	v_mfma_f32_16x16x32_bf16 v[4:7], v[210:213], v[202:205], v[4:7]
	v_mfma_f32_16x16x32_bf16 v[0:3], v[218:221], v[202:205], v[0:3]
	v_mfma_f32_16x16x32_bf16 v[52:55], v[214:217], v[148:151], v[52:55]
	v_mfma_f32_16x16x32_bf16 v[48:51], v[222:225], v[148:151], v[48:51]
	v_mfma_f32_16x16x32_bf16 v[36:39], v[214:217], v[184:187], v[36:39]
	v_mfma_f32_16x16x32_bf16 v[32:35], v[222:225], v[184:187], v[32:35]
	v_mfma_f32_16x16x32_bf16 v[20:23], v[214:217], v[192:195], v[20:23]
	v_mfma_f32_16x16x32_bf16 v[16:19], v[222:225], v[192:195], v[16:19]
	v_mfma_f32_16x16x32_bf16 v[4:7], v[214:217], v[206:209], v[4:7]
	v_mfma_f32_16x16x32_bf16 v[0:3], v[222:225], v[206:209], v[0:3]
	s_setprio 0
	s_add_u32 s48, s48, 0x100
	s_addc_u32 s49, s49, 0
	s_add_u32 s37, s37, 0x100
	s_addc_u32 s39, s39, 0
	s_cmp_ge_i32 s76, s23
	s_mov_b32 s45, s76
	s_barrier
	s_cbranch_scc0 .LBB0_1636
	s_cmp_gt_i32 s10, -1
	s_mov_b64 s[48:49], -1
	s_cbranch_scc0 .LBB0_1639

; #define PG8_STAGE(bufoff, gbase, voff) do { _Pragma("unroll") for (int _i = 0; _i < 2; ++_i) \
;         __builtin_amdgcn_global_load_lds((const unsigned*)((const char*)(gbase) + (voff)[_i]), (PG8_LAS unsigned*)(lds + (bufoff) + ldsw + _i * 8192), 16, 0, 0); } while (0)
; #define PG8_LDA(dst, b, h) do { _Pragma("unroll") for (int m = 0; m < 4; ++m) _Pragma("unroll") for (int k = 0; k < 2; ++k) dst[m][k] = *(const PG8_LAS bf16x8*)(lds + PG8_SA(b, h) + aoff + m * 2048 + k * 1024); } while (0)
; #define PG8_LDB(dst, b, h) do { _Pragma("unroll") for (int n = 0; n < 2; ++n) _Pragma("unroll") for (int k = 0; k < 2; ++k) dst[n][k] = *(const PG8_LAS bf16x8*)(lds + PG8_SB(b, h) + boff + n * 2048 + k * 1024); } while (0)
; #define PG8_MMA(ai, bj, At, Bt) do { __builtin_amdgcn_s_setprio(1); _Pragma("unroll") for (int m = 0; m < 4; ++m) _Pragma("unroll") for (int n = 0; n < 2; ++n) _Pragma("unroll") for (int k = 0; k < 2; ++k) \
;         acc[ai][bj][m][n] = __builtin_amdgcn_mfma_f32_16x16x32_bf16(Bt[n][k], At[m][k], acc[ai][bj][m][n], 0, 0, 0); __builtin_amdgcn_s_setprio(0); } while (0)
; #define PG8_WAIT_L(n) asm volatile("s_waitcnt lgkmcnt(" #n ")" ::: "memory")
; #define PG8_BAR __builtin_amdgcn_s_barrier()
; #define PG8_SCHED __builtin_amdgcn_sched_barrier(0)
; template <class Epi, class Sched>
; __device__ __forceinline__ void gemm_phase(PG8_LAS unsigned char* lds, const Gemm g, const Sched& S, const Epi& E) {
;     ...
;             const bool last = (t == cnk - 2);
;             const char* a1 = cA + (size_t)(t + 1) * kstep;
;             const char* a2 = last ? nA : cA + (size_t)(t + 2) * kstep; const char* b2 = last ? nB : cB + (size_t)(t + 2) * kstep;
;             const char* a3 = a2 + kstep; const char* b3 = b2 + kstep;
;             if (last && has_next) S.a_ready(nxt);
;             if (last) E.prefetch(pre, cur, wr, fr);
;             PG8_LDB(B0, 0, 0); PG8_SCHED; PG8_LDA(At, 0, 0); PG8_STAGE(PG8_SA(1, 1), a1 + hstep, voffA);
;             PG8_WAIT_L(8); PG8_BAR; PG8_WAIT_L(0); PG8_MMA(0, 0, At, B0); PG8_BAR; PG8_SCHED;
;             PG8_LDB(B1, 0, 1); PG8_STAGE(PG8_SB(0, 0), b2, voffB);
;             PG8_BAR; PG8_WAIT_L(0); PG8_MMA(0, 1, At, B1); PG8_BAR;
;             PG8_LDA(At, 0, 1); PG8_STAGE(PG8_SA(0, 0), a2, voffA);
;             PG8_BAR; PG8_WAIT_L(0); PG8_MMA(1, 0, At, B0); PG8_BAR; PG8_SCHED;
.LBB0_1847:
	v_add_u32_e32 v138, s73, v159
	ds_read_b128 v[130:133], v138
	ds_read_b128 v[134:137], v138 offset:1024
	ds_read_b128 v[182:185], v138 offset:2048
	ds_read_b128 v[186:189], v138 offset:3072
	s_add_u32 s14, s0, 0xfffc0080
	s_addc_u32 s15, s1, -1
	s_and_b64 s[12:13], s[12:13], exec
	s_cselect_b32 s15, s11, s15
	s_cselect_b32 s14, s47, s14
	s_cselect_b32 s13, s45, s55
	s_cselect_b32 s12, vcc_lo, vcc_hi
	v_lshl_add_u64 v[138:139], s[0:1], 0, v[166:167]
	s_add_i32 m0, s25, 0xc000
	ds_read_b128 v[190:193], v213
	ds_read_b128 v[194:197], v213 offset:1024
	ds_read_b128 v[198:201], v213 offset:2048
	ds_read_b128 v[202:205], v213 offset:3072
	ds_read_b128 v[218:221], v213 offset:4096
	ds_read_b128 v[222:225], v213 offset:5120
	ds_read_b128 v[226:229], v213 offset:6144
	ds_read_b128 v[230:233], v213 offset:7168
	global_load_lds_dwordx4 v[138:139], off
	s_add_i32 m0, s25, 0xe000
	v_lshl_add_u64 v[138:139], s[0:1], 0, v[168:169]
	global_load_lds_dwordx4 v[138:139], off
	s_waitcnt lgkmcnt(8)
	s_barrier
	s_waitcnt lgkmcnt(0)
	s_setprio 1
	v_mfma_f32_16x16x32_bf16 v[124:127], v[130:133], v[190:193], v[124:127]
	v_mfma_f32_16x16x32_bf16 v[120:123], v[182:185], v[190:193], v[120:123]
	v_mfma_f32_16x16x32_bf16 v[108:111], v[130:133], v[198:201], v[108:111]
	v_mfma_f32_16x16x32_bf16 v[104:107], v[182:185], v[198:201], v[104:107]
	v_mfma_f32_16x16x32_bf16 v[92:95], v[130:133], v[218:221], v[92:95]
	v_mfma_f32_16x16x32_bf16 v[88:91], v[182:185], v[218:221], v[88:91]
	v_mfma_f32_16x16x32_bf16 v[76:79], v[130:133], v[226:229], v[76:79]
	v_mfma_f32_16x16x32_bf16 v[72:75], v[182:185], v[226:229], v[72:75]
	v_mfma_f32_16x16x32_bf16 v[124:127], v[134:137], v[194:197], v[124:127]
	v_mfma_f32_16x16x32_bf16 v[120:123], v[186:189], v[194:197], v[120:123]
	v_mfma_f32_16x16x32_bf16 v[108:111], v[134:137], v[202:205], v[108:111]
	v_mfma_f32_16x16x32_bf16 v[104:107], v[186:189], v[202:205], v[104:107]
	v_mfma_f32_16x16x32_bf16 v[92:95], v[134:137], v[222:225], v[92:95]
	v_mfma_f32_16x16x32_bf16 v[88:91], v[186:189], v[222:225], v[88:91]
	v_mfma_f32_16x16x32_bf16 v[76:79], v[134:137], v[230:233], v[76:79]
	v_mfma_f32_16x16x32_bf16 v[72:75], v[186:189], v[230:233], v[72:75]
	s_setprio 0
	s_barrier
	v_add_u32_e32 v138, s74, v159
	s_add_i32 s30, s73, s24
	ds_read_b128 v[234:237], v138
	ds_read_b128 v[238:241], v138 offset:1024
	ds_read_b128 v[242:245], v138 offset:2048
	ds_read_b128 v[246:249], v138 offset:3072
	v_lshl_add_u64 v[138:139], s[12:13], 0, v[142:143]
	s_mov_b32 m0, s30
	v_lshl_add_u64 v[206:207], s[12:13], 0, v[146:147]
	global_load_lds_dwordx4 v[138:139], off
	s_add_i32 m0, s30, 0x2000
	s_nop 0
	global_load_lds_dwordx4 v[206:207], off
	s_barrier
	s_waitcnt lgkmcnt(0)
	s_setprio 1
	v_mfma_f32_16x16x32_bf16 v[116:119], v[234:237], v[190:193], v[116:119]
	v_mfma_f32_16x16x32_bf16 v[112:115], v[242:245], v[190:193], v[112:115]
	v_mfma_f32_16x16x32_bf16 v[100:103], v[234:237], v[198:201], v[100:103]
	v_mfma_f32_16x16x32_bf16 v[96:99], v[242:245], v[198:201], v[96:99]
	v_mfma_f32_16x16x32_bf16 v[84:87], v[234:237], v[218:221], v[84:87]
	v_mfma_f32_16x16x32_bf16 v[80:83], v[242:245], v[218:221], v[80:83]
	v_mfma_f32_16x16x32_bf16 v[68:71], v[234:237], v[226:229], v[68:71]
	v_mfma_f32_16x16x32_bf16 v[64:67], v[242:245], v[226:229], v[64:67]
	v_mfma_f32_16x16x32_bf16 v[116:119], v[238:241], v[194:197], v[116:119]
	v_mfma_f32_16x16x32_bf16 v[112:115], v[246:249], v[194:197], v[112:115]
	v_mfma_f32_16x16x32_bf16 v[100:103], v[238:241], v[202:205], v[100:103]
	v_mfma_f32_16x16x32_bf16 v[96:99], v[246:249], v[202:205], v[96:99]
	v_mfma_f32_16x16x32_bf16 v[84:87], v[238:241], v[222:225], v[84:87]
	v_mfma_f32_16x16x32_bf16 v[80:83], v[246:249], v[222:225], v[80:83]
	v_mfma_f32_16x16x32_bf16 v[68:71], v[238:241], v[230:233], v[68:71]
	v_mfma_f32_16x16x32_bf16 v[64:67], v[246:249], v[230:233], v[64:67]
	s_setprio 0
	s_mov_b32 m0, s25
	v_lshl_add_u64 v[250:251], s[14:15], 0, v[140:141]
	s_barrier
	ds_read_b128 v[190:193], v213 offset:16384
	ds_read_b128 v[194:197], v213 offset:17408
	ds_read_b128 v[198:201], v213 offset:18432
	ds_read_b128 v[202:205], v213 offset:19456
	ds_read_b128 v[218:221], v213 offset:20480
	ds_read_b128 v[222:225], v213 offset:21504
	ds_read_b128 v[226:229], v213 offset:22528
	ds_read_b128 v[230:233], v213 offset:23552
	global_load_lds_dwordx4 v[250:251], off
	s_mov_b32 m0, s27
	v_lshl_add_u64 v[252:253], s[14:15], 0, v[144:145]
	global_load_lds_dwordx4 v[252:253], off
	s_barrier
	s_waitcnt lgkmcnt(0)
	s_setprio 1
	v_mfma_f32_16x16x32_bf16 v[60:63], v[130:133], v[190:193], v[60:63]
	v_mfma_f32_16x16x32_bf16 v[56:59], v[182:185], v[190:193], v[56:59]
	v_mfma_f32_16x16x32_bf16 v[44:47], v[130:133], v[198:201], v[44:47]
	v_mfma_f32_16x16x32_bf16 v[40:43], v[182:185], v[198:201], v[40:43]
	v_mfma_f32_16x16x32_bf16 v[28:31], v[130:133], v[218:221], v[28:31]
	v_mfma_f32_16x16x32_bf16 v[24:27], v[182:185], v[218:221], v[24:27]
	v_mfma_f32_16x16x32_bf16 v[12:15], v[130:133], v[226:229], v[12:15]
	v_mfma_f32_16x16x32_bf16 v[8:11], v[182:185], v[226:229], v[8:11]
	v_mfma_f32_16x16x32_bf16 v[60:63], v[134:137], v[194:197], v[60:63]
	v_mfma_f32_16x16x32_bf16 v[56:59], v[186:189], v[194:197], v[56:59]
	v_mfma_f32_16x16x32_bf16 v[44:47], v[134:137], v[202:205], v[44:47]
	v_mfma_f32_16x16x32_bf16 v[40:43], v[186:189], v[202:205], v[40:43]
	v_mfma_f32_16x16x32_bf16 v[28:31], v[134:137], v[222:225], v[28:31]
	v_mfma_f32_16x16x32_bf16 v[24:27], v[186:189], v[222:225], v[24:27]
	v_mfma_f32_16x16x32_bf16 v[12:15], v[134:137], v[230:233], v[12:15]
	v_mfma_f32_16x16x32_bf16 v[8:11], v[186:189], v[230:233], v[8:11]
	s_setprio 0
	s_barrier
; #define PG8_STAGE(bufoff, gbase, voff) do { _Pragma("unroll") for (int _i = 0; _i < 2; ++_i) \
;         __builtin_amdgcn_global_load_lds((const unsigned*)((const char*)(gbase) + (voff)[_i]), (PG8_LAS unsigned*)(lds + (bufoff) + ldsw + _i * 8192), 16, 0, 0); } while (0)
; #define PG8_LDA(dst, b, h) do { _Pragma("unroll") for (int m = 0; m < 4; ++m) _Pragma("unroll") for (int k = 0; k < 2; ++k) dst[m][k] = *(const PG8_LAS bf16x8*)(lds + PG8_SA(b, h) + aoff + m * 2048 + k * 1024); } while (0)
; #define PG8_LDB(dst, b, h) do { _Pragma("unroll") for (int n = 0; n < 2; ++n) _Pragma("unroll") for (int k = 0; k < 2; ++k) dst[n][k] = *(const PG8_LAS bf16x8*)(lds + PG8_SB(b, h) + boff + n * 2048 + k * 1024); } while (0)
; #define PG8_MMA(ai, bj, At, Bt) do { __builtin_amdgcn_s_setprio(1); _Pragma("unroll") for (int m = 0; m < 4; ++m) _Pragma("unroll") for (int n = 0; n < 2; ++n) _Pragma("unroll") for (int k = 0; k < 2; ++k) \
;         acc[ai][bj][m][n] = __builtin_amdgcn_mfma_f32_16x16x32_bf16(Bt[n][k], At[m][k], acc[ai][bj][m][n], 0, 0, 0); __builtin_amdgcn_s_setprio(0); } while (0)
; #define PG8_WAIT_V(n) asm volatile("s_waitcnt vmcnt(" #n ")" ::: "memory")
; #define PG8_WAIT_L(n) asm volatile("s_waitcnt lgkmcnt(" #n ")" ::: "memory")
; #define PG8_BAR __builtin_amdgcn_s_barrier()
; #define PG8_SCHED __builtin_amdgcn_sched_barrier(0)
; template <class Epi, class Sched>
; __device__ __forceinline__ void gemm_phase(PG8_LAS unsigned char* lds, const Gemm g, const Sched& S, const Epi& E) {
;     ...
;             PG8_STAGE(PG8_SB(0, 1), b2 + hstep, voffB);
;             PG8_WAIT_V(6); PG8_BAR; PG8_MMA(1, 1, At, B1); PG8_BAR;
;             PG8_LDB(B0, 1, 0); PG8_SCHED; PG8_LDA(At, 1, 0); PG8_STAGE(PG8_SA(0, 1), a2 + hstep, voffA);
;             PG8_WAIT_L(8); PG8_BAR; PG8_WAIT_L(0); PG8_MMA(0, 0, At, B0); PG8_BAR; PG8_SCHED;
;             PG8_LDB(B1, 1, 1); PG8_STAGE(PG8_SB(1, 0), b3, voffB);
	s_add_u32 s96, s12, 0x40000
	s_addc_u32 s97, s13, 0
	s_add_i32 s30, s74, s24
	s_mov_b32 m0, s30
	v_lshl_add_u64 v[130:131], s[96:97], 0, v[142:143]
	global_load_lds_dwordx4 v[130:131], off
	s_add_i32 m0, s30, 0x2000
	v_lshl_add_u64 v[130:131], s[96:97], 0, v[146:147]
	global_load_lds_dwordx4 v[130:131], off
	s_waitcnt vmcnt(6)
	s_barrier
	s_setprio 1
	v_mfma_f32_16x16x32_bf16 v[52:55], v[234:237], v[190:193], v[52:55]
	v_mfma_f32_16x16x32_bf16 v[48:51], v[242:245], v[190:193], v[48:51]
	v_mfma_f32_16x16x32_bf16 v[36:39], v[234:237], v[198:201], v[36:39]
	v_mfma_f32_16x16x32_bf16 v[32:35], v[242:245], v[198:201], v[32:35]
	v_mfma_f32_16x16x32_bf16 v[20:23], v[234:237], v[218:221], v[20:23]
	v_mfma_f32_16x16x32_bf16 v[16:19], v[242:245], v[218:221], v[16:19]
	v_mfma_f32_16x16x32_bf16 v[4:7], v[234:237], v[226:229], v[4:7]
	v_mfma_f32_16x16x32_bf16 v[0:3], v[242:245], v[226:229], v[0:3]
	v_mfma_f32_16x16x32_bf16 v[52:55], v[238:241], v[194:197], v[52:55]
	v_mfma_f32_16x16x32_bf16 v[48:51], v[246:249], v[194:197], v[48:51]
	v_mfma_f32_16x16x32_bf16 v[36:39], v[238:241], v[202:205], v[36:39]
	v_mfma_f32_16x16x32_bf16 v[32:35], v[246:249], v[202:205], v[32:35]
	v_mfma_f32_16x16x32_bf16 v[20:23], v[238:241], v[222:225], v[20:23]
	v_mfma_f32_16x16x32_bf16 v[16:19], v[246:249], v[222:225], v[16:19]
	v_mfma_f32_16x16x32_bf16 v[4:7], v[238:241], v[230:233], v[4:7]
	v_mfma_f32_16x16x32_bf16 v[0:3], v[246:249], v[230:233], v[0:3]
	s_setprio 0
	s_add_i32 s30, 0, 0x18000
	v_add_u32_e32 v148, s30, v159
	s_barrier
	ds_read_b128 v[130:133], v148
	ds_read_b128 v[134:137], v148 offset:1024
	ds_read_b128 v[182:185], v148 offset:2048
	ds_read_b128 v[186:189], v148 offset:3072
	s_add_u32 s14, s14, 0x40000
	s_addc_u32 s15, s15, 0
	s_mov_b32 m0, s29
	v_lshl_add_u64 v[234:235], s[14:15], 0, v[140:141]
	ds_read_b128 v[190:193], v213 offset:32768
	ds_read_b128 v[194:197], v213 offset:33792
	ds_read_b128 v[198:201], v213 offset:34816
	ds_read_b128 v[202:205], v213 offset:35840
	ds_read_b128 v[218:221], v213 offset:36864
	ds_read_b128 v[222:225], v213 offset:37888
	ds_read_b128 v[226:229], v213 offset:38912
	ds_read_b128 v[230:233], v213 offset:39936
	global_load_lds_dwordx4 v[234:235], off
	s_mov_b32 m0, s33
	v_lshl_add_u64 v[234:235], s[14:15], 0, v[144:145]
	global_load_lds_dwordx4 v[234:235], off
	s_waitcnt lgkmcnt(8)
	s_barrier
	s_waitcnt lgkmcnt(0)
	s_setprio 1
	v_mfma_f32_16x16x32_bf16 v[124:127], v[130:133], v[190:193], v[124:127]
	v_mfma_f32_16x16x32_bf16 v[120:123], v[182:185], v[190:193], v[120:123]
	v_mfma_f32_16x16x32_bf16 v[108:111], v[130:133], v[198:201], v[108:111]
	v_mfma_f32_16x16x32_bf16 v[104:107], v[182:185], v[198:201], v[104:107]
	v_mfma_f32_16x16x32_bf16 v[92:95], v[130:133], v[218:221], v[92:95]
	v_mfma_f32_16x16x32_bf16 v[88:91], v[182:185], v[218:221], v[88:91]
	v_mfma_f32_16x16x32_bf16 v[76:79], v[130:133], v[226:229], v[76:79]
	v_mfma_f32_16x16x32_bf16 v[72:75], v[182:185], v[226:229], v[72:75]
	v_mfma_f32_16x16x32_bf16 v[124:127], v[134:137], v[194:197], v[124:127]
	v_mfma_f32_16x16x32_bf16 v[120:123], v[186:189], v[194:197], v[120:123]
	v_mfma_f32_16x16x32_bf16 v[108:111], v[134:137], v[202:205], v[108:111]
	v_mfma_f32_16x16x32_bf16 v[104:107], v[186:189], v[202:205], v[104:107]
	v_mfma_f32_16x16x32_bf16 v[92:95], v[134:137], v[222:225], v[92:95]
	v_mfma_f32_16x16x32_bf16 v[88:91], v[186:189], v[222:225], v[88:91]
	v_mfma_f32_16x16x32_bf16 v[76:79], v[134:137], v[230:233], v[76:79]
	v_mfma_f32_16x16x32_bf16 v[72:75], v[186:189], v[230:233], v[72:75]
	s_setprio 0
	s_barrier
	s_add_i32 s14, 0, 0x1c000
	s_add_i32 s15, s30, s24
	v_add_u32_e32 v148, s14, v159
	v_lshl_add_u64 v[138:139], v[138:139], 0, s[20:21]
	s_mov_b32 m0, s15
	ds_read_b128 v[234:237], v148
	ds_read_b128 v[238:241], v148 offset:1024
	ds_read_b128 v[242:245], v148 offset:2048
	ds_read_b128 v[246:249], v148 offset:3072
	global_load_lds_dwordx4 v[138:139], off
	s_add_i32 m0, s15, 0x2000
	v_lshl_add_u64 v[138:139], v[206:207], 0, s[20:21]
	global_load_lds_dwordx4 v[138:139], off
	s_barrier
; #define PG8_STAGE(bufoff, gbase, voff) do { _Pragma("unroll") for (int _i = 0; _i < 2; ++_i) \
;         __builtin_amdgcn_global_load_lds((const unsigned*)((const char*)(gbase) + (voff)[_i]), (PG8_LAS unsigned*)(lds + (bufoff) + ldsw + _i * 8192), 16, 0, 0); } while (0)
; #define PG8_LDA(dst, b, h) do { _Pragma("unroll") for (int m = 0; m < 4; ++m) _Pragma("unroll") for (int k = 0; k < 2; ++k) dst[m][k] = *(const PG8_LAS bf16x8*)(lds + PG8_SA(b, h) + aoff + m * 2048 + k * 1024); } while (0)
; #define PG8_MMA(ai, bj, At, Bt) do { __builtin_amdgcn_s_setprio(1); _Pragma("unroll") for (int m = 0; m < 4; ++m) _Pragma("unroll") for (int n = 0; n < 2; ++n) _Pragma("unroll") for (int k = 0; k < 2; ++k) \
;         acc[ai][bj][m][n] = __builtin_amdgcn_mfma_f32_16x16x32_bf16(Bt[n][k], At[m][k], acc[ai][bj][m][n], 0, 0, 0); __builtin_amdgcn_s_setprio(0); } while (0)
; #define PG8_WAIT_V(n) asm volatile("s_waitcnt vmcnt(" #n ")" ::: "memory")
; #define PG8_WAIT_L(n) asm volatile("s_waitcnt lgkmcnt(" #n ")" ::: "memory")
; #define PG8_BAR __builtin_amdgcn_s_barrier()
; #define PG8_SCHED __builtin_amdgcn_sched_barrier(0)
; template <class Epi, class Sched>
; __device__ __forceinline__ void gemm_phase(PG8_LAS unsigned char* lds, const Gemm g, const Sched& S, const Epi& E) {
;     ...
;         for (int t = 0; t < cnk; t += 2) {
;     ...
;             PG8_BAR; PG8_WAIT_L(0); PG8_MMA(0, 1, At, B1); PG8_BAR;
;             PG8_LDA(At, 1, 1); PG8_STAGE(PG8_SA(1, 0), a3, voffA);
;             PG8_BAR; PG8_WAIT_L(0); PG8_MMA(1, 0, At, B0); PG8_BAR; PG8_SCHED;
;             PG8_STAGE(PG8_SB(1, 1), b3 + hstep, voffB);
;             PG8_WAIT_V(6); PG8_BAR; PG8_MMA(1, 1, At, B1); PG8_BAR;
;         }
	s_waitcnt lgkmcnt(0)
	s_setprio 1
	v_mfma_f32_16x16x32_bf16 v[116:119], v[234:237], v[190:193], v[116:119]
	v_mfma_f32_16x16x32_bf16 v[112:115], v[242:245], v[190:193], v[112:115]
	v_mfma_f32_16x16x32_bf16 v[100:103], v[234:237], v[198:201], v[100:103]
	v_mfma_f32_16x16x32_bf16 v[96:99], v[242:245], v[198:201], v[96:99]
	v_mfma_f32_16x16x32_bf16 v[84:87], v[234:237], v[218:221], v[84:87]
	v_mfma_f32_16x16x32_bf16 v[80:83], v[242:245], v[218:221], v[80:83]
	v_mfma_f32_16x16x32_bf16 v[68:71], v[234:237], v[226:229], v[68:71]
	v_mfma_f32_16x16x32_bf16 v[64:67], v[242:245], v[226:229], v[64:67]
	v_mfma_f32_16x16x32_bf16 v[116:119], v[238:241], v[194:197], v[116:119]
	v_mfma_f32_16x16x32_bf16 v[112:115], v[246:249], v[194:197], v[112:115]
	v_mfma_f32_16x16x32_bf16 v[100:103], v[238:241], v[202:205], v[100:103]
	v_mfma_f32_16x16x32_bf16 v[96:99], v[246:249], v[202:205], v[96:99]
	v_mfma_f32_16x16x32_bf16 v[84:87], v[238:241], v[222:225], v[84:87]
	v_mfma_f32_16x16x32_bf16 v[80:83], v[246:249], v[222:225], v[80:83]
	v_mfma_f32_16x16x32_bf16 v[68:71], v[238:241], v[230:233], v[68:71]
	v_mfma_f32_16x16x32_bf16 v[64:67], v[246:249], v[230:233], v[64:67]
	s_setprio 0
	s_mov_b32 m0, s16
	v_lshl_add_u64 v[138:139], v[250:251], 0, s[20:21]
	s_barrier
	ds_read_b128 v[190:193], v213 offset:49152
	ds_read_b128 v[194:197], v213 offset:50176
	ds_read_b128 v[198:201], v213 offset:51200
	ds_read_b128 v[202:205], v213 offset:52224
	ds_read_b128 v[218:221], v213 offset:53248
	ds_read_b128 v[222:225], v213 offset:54272
	ds_read_b128 v[226:229], v213 offset:55296
	ds_read_b128 v[230:233], v213 offset:56320
	global_load_lds_dwordx4 v[138:139], off
	s_mov_b32 m0, s17
	v_lshl_add_u64 v[138:139], v[252:253], 0, s[20:21]
	global_load_lds_dwordx4 v[138:139], off
	s_barrier
	s_waitcnt lgkmcnt(0)
	s_setprio 1
	v_mfma_f32_16x16x32_bf16 v[60:63], v[130:133], v[190:193], v[60:63]
	v_mfma_f32_16x16x32_bf16 v[56:59], v[182:185], v[190:193], v[56:59]
	v_mfma_f32_16x16x32_bf16 v[44:47], v[130:133], v[198:201], v[44:47]
	v_mfma_f32_16x16x32_bf16 v[40:43], v[182:185], v[198:201], v[40:43]
	v_mfma_f32_16x16x32_bf16 v[28:31], v[130:133], v[218:221], v[28:31]
	v_mfma_f32_16x16x32_bf16 v[24:27], v[182:185], v[218:221], v[24:27]
	v_mfma_f32_16x16x32_bf16 v[12:15], v[130:133], v[226:229], v[12:15]
	v_mfma_f32_16x16x32_bf16 v[8:11], v[182:185], v[226:229], v[8:11]
	v_mfma_f32_16x16x32_bf16 v[60:63], v[134:137], v[194:197], v[60:63]
	v_mfma_f32_16x16x32_bf16 v[56:59], v[186:189], v[194:197], v[56:59]
	v_mfma_f32_16x16x32_bf16 v[44:47], v[134:137], v[202:205], v[44:47]
	v_mfma_f32_16x16x32_bf16 v[40:43], v[186:189], v[202:205], v[40:43]
	v_mfma_f32_16x16x32_bf16 v[28:31], v[134:137], v[222:225], v[28:31]
	v_mfma_f32_16x16x32_bf16 v[24:27], v[186:189], v[222:225], v[24:27]
	v_mfma_f32_16x16x32_bf16 v[12:15], v[134:137], v[230:233], v[12:15]
	v_mfma_f32_16x16x32_bf16 v[8:11], v[186:189], v[230:233], v[8:11]
	s_setprio 0
	s_barrier
	s_add_u32 s12, s12, 0x40080
	s_addc_u32 s13, s13, 0
	s_add_i32 s14, s14, s24
	s_mov_b32 m0, s14
	v_lshl_add_u64 v[130:131], s[12:13], 0, v[142:143]
	global_load_lds_dwordx4 v[130:131], off
	s_add_i32 m0, s14, 0x2000
	v_lshl_add_u64 v[130:131], s[12:13], 0, v[146:147]
	global_load_lds_dwordx4 v[130:131], off
	s_waitcnt vmcnt(6)
	s_barrier
	s_setprio 1
	v_mfma_f32_16x16x32_bf16 v[52:55], v[234:237], v[190:193], v[52:55]
	v_mfma_f32_16x16x32_bf16 v[48:51], v[242:245], v[190:193], v[48:51]
	v_mfma_f32_16x16x32_bf16 v[36:39], v[234:237], v[198:201], v[36:39]
	v_mfma_f32_16x16x32_bf16 v[32:35], v[242:245], v[198:201], v[32:35]
	v_mfma_f32_16x16x32_bf16 v[20:23], v[234:237], v[218:221], v[20:23]
	v_mfma_f32_16x16x32_bf16 v[16:19], v[242:245], v[218:221], v[16:19]
	v_mfma_f32_16x16x32_bf16 v[4:7], v[234:237], v[226:229], v[4:7]
	v_mfma_f32_16x16x32_bf16 v[0:3], v[242:245], v[226:229], v[0:3]
	v_mfma_f32_16x16x32_bf16 v[52:55], v[238:241], v[194:197], v[52:55]
	v_mfma_f32_16x16x32_bf16 v[48:51], v[246:249], v[194:197], v[48:51]
	v_mfma_f32_16x16x32_bf16 v[36:39], v[238:241], v[202:205], v[36:39]
	v_mfma_f32_16x16x32_bf16 v[32:35], v[246:249], v[202:205], v[32:35]
	v_mfma_f32_16x16x32_bf16 v[20:23], v[238:241], v[222:225], v[20:23]
	v_mfma_f32_16x16x32_bf16 v[16:19], v[246:249], v[222:225], v[16:19]
	v_mfma_f32_16x16x32_bf16 v[4:7], v[238:241], v[230:233], v[4:7]
	v_mfma_f32_16x16x32_bf16 v[0:3], v[246:249], v[230:233], v[0:3]
	s_setprio 0
	s_add_i32 s5, s5, 2
	s_add_u32 s0, s0, 0x100
	s_addc_u32 s1, s1, 0
	s_add_u32 vcc_hi, vcc_hi, 0x100
	s_addc_u32 s55, s55, 0
	s_cmp_lt_u32 s5, 14
	s_barrier
	s_cbranch_scc0 .LBB0_1850

; #define PG8_STAGE(bufoff, gbase, voff) do { _Pragma("unroll") for (int _i = 0; _i < 2; ++_i) \
;         __builtin_amdgcn_global_load_lds((const unsigned*)((const char*)(gbase) + (voff)[_i]), (PG8_LAS unsigned*)(lds + (bufoff) + ldsw + _i * 8192), 16, 0, 0); } while (0)
; #define PG8_LDA(dst, b, h) do { _Pragma("unroll") for (int m = 0; m < 4; ++m) _Pragma("unroll") for (int k = 0; k < 2; ++k) dst[m][k] = *(const PG8_LAS bf16x8*)(lds + PG8_SA(b, h) + aoff + m * 2048 + k * 1024); } while (0)
; #define PG8_LDB(dst, b, h) do { _Pragma("unroll") for (int n = 0; n < 2; ++n) _Pragma("unroll") for (int k = 0; k < 2; ++k) dst[n][k] = *(const PG8_LAS bf16x8*)(lds + PG8_SB(b, h) + boff + n * 2048 + k * 1024); } while (0)
; #define PG8_MMA(ai, bj, At, Bt) do { __builtin_amdgcn_s_setprio(1); _Pragma("unroll") for (int m = 0; m < 4; ++m) _Pragma("unroll") for (int n = 0; n < 2; ++n) _Pragma("unroll") for (int k = 0; k < 2; ++k) \
;         acc[ai][bj][m][n] = __builtin_amdgcn_mfma_f32_16x16x32_bf16(Bt[n][k], At[m][k], acc[ai][bj][m][n], 0, 0, 0); __builtin_amdgcn_s_setprio(0); } while (0)
; #define PG8_WAIT_L(n) asm volatile("s_waitcnt lgkmcnt(" #n ")" ::: "memory")
; #define PG8_BAR __builtin_amdgcn_s_barrier()
; #define PG8_SCHED __builtin_amdgcn_sched_barrier(0)
; template <class Epi, class Sched>
; __device__ __forceinline__ void gemm_phase(PG8_LAS unsigned char* lds, const Gemm g, const Sched& S, const Epi& E) {
;     ...
;             const bool last = (t == cnk - 2);
;             const char* a1 = cA + (size_t)(t + 1) * kstep;
;             const char* a2 = last ? nA : cA + (size_t)(t + 2) * kstep; const char* b2 = last ? nB : cB + (size_t)(t + 2) * kstep;
;             const char* a3 = a2 + kstep; const char* b3 = b2 + kstep;
;             if (last && has_next) S.a_ready(nxt);
;             if (last) E.prefetch(pre, cur, wr, fr);
;             PG8_LDB(B0, 0, 0); PG8_SCHED; PG8_LDA(At, 0, 0); PG8_STAGE(PG8_SA(1, 1), a1 + hstep, voffA);
;             PG8_WAIT_L(8); PG8_BAR; PG8_WAIT_L(0); PG8_MMA(0, 0, At, B0); PG8_BAR; PG8_SCHED;
;             PG8_LDB(B1, 0, 1); PG8_STAGE(PG8_SB(0, 0), b2, voffB);
;             PG8_BAR; PG8_WAIT_L(0); PG8_MMA(0, 1, At, B1); PG8_BAR;
;             PG8_LDA(At, 0, 1); PG8_STAGE(PG8_SA(0, 0), a2, voffA);
;             PG8_BAR; PG8_WAIT_L(0); PG8_MMA(1, 0, At, B0); PG8_BAR; PG8_SCHED;
.LBB0_2251:
	ds_read_b128 v[128:131], v192
	ds_read_b128 v[132:135], v192 offset:1024
	ds_read_b128 v[136:139], v192 offset:2048
	ds_read_b128 v[140:143], v192 offset:3072
	s_add_i32 s70, s43, 2
	s_add_u32 s30, s46, 0xfffc0080
	s_addc_u32 s48, s47, -1
	s_cmp_eq_u32 s25, s43
	s_cselect_b32 s51, s41, s48
	s_cselect_b32 s50, s40, s30
	s_cselect_b32 s49, s45, s37
	s_cselect_b32 s48, s44, s27
	v_lshl_add_u64 v[190:191], s[46:47], 0, v[168:169]
	s_add_i32 m0, s5, 0xc000
	ds_read_b128 v[144:147], v193
	ds_read_b128 v[148:151], v193 offset:1024
	ds_read_b128 v[174:177], v193 offset:2048
	ds_read_b128 v[178:181], v193 offset:3072
	ds_read_b128 v[182:185], v193 offset:4096
	ds_read_b128 v[186:189], v193 offset:5120
	ds_read_b128 v[196:199], v193 offset:6144
	ds_read_b128 v[200:203], v193 offset:7168
	global_load_lds_dwordx4 v[190:191], off
	s_add_i32 m0, s5, 0xe000
	v_lshl_add_u64 v[190:191], s[46:47], 0, v[170:171]
	global_load_lds_dwordx4 v[190:191], off
	s_waitcnt lgkmcnt(8)
	s_barrier
	s_waitcnt lgkmcnt(0)
	s_setprio 1
	v_mfma_f32_16x16x32_bf16 v[124:127], v[128:131], v[144:147], v[124:127]
	v_mfma_f32_16x16x32_bf16 v[120:123], v[136:139], v[144:147], v[120:123]
	v_mfma_f32_16x16x32_bf16 v[108:111], v[128:131], v[174:177], v[108:111]
	v_mfma_f32_16x16x32_bf16 v[104:107], v[136:139], v[174:177], v[104:107]
	v_mfma_f32_16x16x32_bf16 v[92:95], v[128:131], v[182:185], v[92:95]
	v_mfma_f32_16x16x32_bf16 v[88:91], v[136:139], v[182:185], v[88:91]
	v_mfma_f32_16x16x32_bf16 v[76:79], v[128:131], v[196:199], v[76:79]
	v_mfma_f32_16x16x32_bf16 v[72:75], v[136:139], v[196:199], v[72:75]
	v_mfma_f32_16x16x32_bf16 v[124:127], v[132:135], v[148:151], v[124:127]
	v_mfma_f32_16x16x32_bf16 v[120:123], v[140:143], v[148:151], v[120:123]
	v_mfma_f32_16x16x32_bf16 v[108:111], v[132:135], v[178:181], v[108:111]
	v_mfma_f32_16x16x32_bf16 v[104:107], v[140:143], v[178:181], v[104:107]
	v_mfma_f32_16x16x32_bf16 v[92:95], v[132:135], v[186:189], v[92:95]
	v_mfma_f32_16x16x32_bf16 v[88:91], v[140:143], v[186:189], v[88:91]
	v_mfma_f32_16x16x32_bf16 v[76:79], v[132:135], v[200:203], v[76:79]
	v_mfma_f32_16x16x32_bf16 v[72:75], v[140:143], v[200:203], v[72:75]
	s_setprio 0
	s_barrier
	s_add_i32 s30, s53, s4
	v_lshl_add_u64 v[190:191], s[48:49], 0, v[160:161]
	s_mov_b32 m0, s30
	ds_read_b128 v[204:207], v194
	ds_read_b128 v[208:211], v194 offset:1024
	ds_read_b128 v[212:215], v194 offset:2048
	ds_read_b128 v[216:219], v194 offset:3072
	global_load_lds_dwordx4 v[190:191], off
	s_add_i32 m0, s30, 0x2000
	v_lshl_add_u64 v[220:221], s[48:49], 0, v[164:165]
	global_load_lds_dwordx4 v[220:221], off
	s_barrier
	s_waitcnt lgkmcnt(0)
	s_setprio 1
	v_mfma_f32_16x16x32_bf16 v[116:119], v[204:207], v[144:147], v[116:119]
	v_mfma_f32_16x16x32_bf16 v[112:115], v[212:215], v[144:147], v[112:115]
	v_mfma_f32_16x16x32_bf16 v[100:103], v[204:207], v[174:177], v[100:103]
	v_mfma_f32_16x16x32_bf16 v[96:99], v[212:215], v[174:177], v[96:99]
	v_mfma_f32_16x16x32_bf16 v[84:87], v[204:207], v[182:185], v[84:87]
	v_mfma_f32_16x16x32_bf16 v[80:83], v[212:215], v[182:185], v[80:83]
	v_mfma_f32_16x16x32_bf16 v[68:71], v[204:207], v[196:199], v[68:71]
	v_mfma_f32_16x16x32_bf16 v[64:67], v[212:215], v[196:199], v[64:67]
	v_mfma_f32_16x16x32_bf16 v[116:119], v[208:211], v[148:151], v[116:119]
	v_mfma_f32_16x16x32_bf16 v[112:115], v[216:219], v[148:151], v[112:115]
	v_mfma_f32_16x16x32_bf16 v[100:103], v[208:211], v[178:181], v[100:103]
	v_mfma_f32_16x16x32_bf16 v[96:99], v[216:219], v[178:181], v[96:99]
	v_mfma_f32_16x16x32_bf16 v[84:87], v[208:211], v[186:189], v[84:87]
	v_mfma_f32_16x16x32_bf16 v[80:83], v[216:219], v[186:189], v[80:83]
	v_mfma_f32_16x16x32_bf16 v[68:71], v[208:211], v[200:203], v[68:71]
	v_mfma_f32_16x16x32_bf16 v[64:67], v[216:219], v[200:203], v[64:67]
	s_setprio 0
	s_mov_b32 m0, s5
	v_lshl_add_u64 v[222:223], s[50:51], 0, v[158:159]
	s_barrier
	ds_read_b128 v[144:147], v193 offset:16384
	ds_read_b128 v[148:151], v193 offset:17408
	ds_read_b128 v[174:177], v193 offset:18432
	ds_read_b128 v[178:181], v193 offset:19456
	ds_read_b128 v[182:185], v193 offset:20480
	ds_read_b128 v[186:189], v193 offset:21504
	ds_read_b128 v[196:199], v193 offset:22528
	ds_read_b128 v[200:203], v193 offset:23552
	global_load_lds_dwordx4 v[222:223], off
	s_mov_b32 m0, s6
	v_lshl_add_u64 v[224:225], s[50:51], 0, v[162:163]
	global_load_lds_dwordx4 v[224:225], off
	s_barrier
	s_waitcnt lgkmcnt(0)
	s_setprio 1
	v_mfma_f32_16x16x32_bf16 v[60:63], v[128:131], v[144:147], v[60:63]
	v_mfma_f32_16x16x32_bf16 v[56:59], v[136:139], v[144:147], v[56:59]
	v_mfma_f32_16x16x32_bf16 v[44:47], v[128:131], v[174:177], v[44:47]
	v_mfma_f32_16x16x32_bf16 v[40:43], v[136:139], v[174:177], v[40:43]
	v_mfma_f32_16x16x32_bf16 v[28:31], v[128:131], v[182:185], v[28:31]
	v_mfma_f32_16x16x32_bf16 v[24:27], v[136:139], v[182:185], v[24:27]
	v_mfma_f32_16x16x32_bf16 v[12:15], v[128:131], v[196:199], v[12:15]
	v_mfma_f32_16x16x32_bf16 v[8:11], v[136:139], v[196:199], v[8:11]
	v_mfma_f32_16x16x32_bf16 v[60:63], v[132:135], v[148:151], v[60:63]
	v_mfma_f32_16x16x32_bf16 v[56:59], v[140:143], v[148:151], v[56:59]
	v_mfma_f32_16x16x32_bf16 v[44:47], v[132:135], v[178:181], v[44:47]
	v_mfma_f32_16x16x32_bf16 v[40:43], v[140:143], v[178:181], v[40:43]
	v_mfma_f32_16x16x32_bf16 v[28:31], v[132:135], v[186:189], v[28:31]
	v_mfma_f32_16x16x32_bf16 v[24:27], v[140:143], v[186:189], v[24:27]
	v_mfma_f32_16x16x32_bf16 v[12:15], v[132:135], v[200:203], v[12:15]
	v_mfma_f32_16x16x32_bf16 v[8:11], v[140:143], v[200:203], v[8:11]
	s_setprio 0
	s_barrier
; #define PG8_STAGE(bufoff, gbase, voff) do { _Pragma("unroll") for (int _i = 0; _i < 2; ++_i) \
;         __builtin_amdgcn_global_load_lds((const unsigned*)((const char*)(gbase) + (voff)[_i]), (PG8_LAS unsigned*)(lds + (bufoff) + ldsw + _i * 8192), 16, 0, 0); } while (0)
; #define PG8_LDA(dst, b, h) do { _Pragma("unroll") for (int m = 0; m < 4; ++m) _Pragma("unroll") for (int k = 0; k < 2; ++k) dst[m][k] = *(const PG8_LAS bf16x8*)(lds + PG8_SA(b, h) + aoff + m * 2048 + k * 1024); } while (0)
; #define PG8_LDB(dst, b, h) do { _Pragma("unroll") for (int n = 0; n < 2; ++n) _Pragma("unroll") for (int k = 0; k < 2; ++k) dst[n][k] = *(const PG8_LAS bf16x8*)(lds + PG8_SB(b, h) + boff + n * 2048 + k * 1024); } while (0)
; #define PG8_MMA(ai, bj, At, Bt) do { __builtin_amdgcn_s_setprio(1); _Pragma("unroll") for (int m = 0; m < 4; ++m) _Pragma("unroll") for (int n = 0; n < 2; ++n) _Pragma("unroll") for (int k = 0; k < 2; ++k) \
;         acc[ai][bj][m][n] = __builtin_amdgcn_mfma_f32_16x16x32_bf16(Bt[n][k], At[m][k], acc[ai][bj][m][n], 0, 0, 0); __builtin_amdgcn_s_setprio(0); } while (0)
; #define PG8_WAIT_V(n) asm volatile("s_waitcnt vmcnt(" #n ")" ::: "memory")
; #define PG8_WAIT_L(n) asm volatile("s_waitcnt lgkmcnt(" #n ")" ::: "memory")
; #define PG8_BAR __builtin_amdgcn_s_barrier()
; #define PG8_SCHED __builtin_amdgcn_sched_barrier(0)
; template <class Epi, class Sched>
; __device__ __forceinline__ void gemm_phase(PG8_LAS unsigned char* lds, const Gemm g, const Sched& S, const Epi& E) {
;     ...
;             PG8_STAGE(PG8_SB(0, 1), b2 + hstep, voffB);
;             PG8_WAIT_V(6); PG8_BAR; PG8_MMA(1, 1, At, B1); PG8_BAR;
;             PG8_LDB(B0, 1, 0); PG8_SCHED; PG8_LDA(At, 1, 0); PG8_STAGE(PG8_SA(0, 1), a2 + hstep, voffA);
;             PG8_WAIT_L(8); PG8_BAR; PG8_WAIT_L(0); PG8_MMA(0, 0, At, B0); PG8_BAR; PG8_SCHED;
;             PG8_LDB(B1, 1, 1); PG8_STAGE(PG8_SB(1, 0), b3, voffB);
	s_add_u32 s72, s48, 0x40000
	s_addc_u32 s73, s49, 0
	s_add_i32 s30, s54, s4
	s_mov_b32 m0, s30
	v_lshl_add_u64 v[128:129], s[72:73], 0, v[160:161]
	global_load_lds_dwordx4 v[128:129], off
	s_add_i32 m0, s30, 0x2000
	v_lshl_add_u64 v[128:129], s[72:73], 0, v[164:165]
	global_load_lds_dwordx4 v[128:129], off
	s_waitcnt vmcnt(6)
	s_barrier
	s_setprio 1
	v_mfma_f32_16x16x32_bf16 v[52:55], v[204:207], v[144:147], v[52:55]
	v_mfma_f32_16x16x32_bf16 v[48:51], v[212:215], v[144:147], v[48:51]
	v_mfma_f32_16x16x32_bf16 v[36:39], v[204:207], v[174:177], v[36:39]
	v_mfma_f32_16x16x32_bf16 v[32:35], v[212:215], v[174:177], v[32:35]
	v_mfma_f32_16x16x32_bf16 v[20:23], v[204:207], v[182:185], v[20:23]
	v_mfma_f32_16x16x32_bf16 v[16:19], v[212:215], v[182:185], v[16:19]
	v_mfma_f32_16x16x32_bf16 v[4:7], v[204:207], v[196:199], v[4:7]
	v_mfma_f32_16x16x32_bf16 v[0:3], v[212:215], v[196:199], v[0:3]
	v_mfma_f32_16x16x32_bf16 v[52:55], v[208:211], v[148:151], v[52:55]
	v_mfma_f32_16x16x32_bf16 v[48:51], v[216:219], v[148:151], v[48:51]
	v_mfma_f32_16x16x32_bf16 v[36:39], v[208:211], v[178:181], v[36:39]
	v_mfma_f32_16x16x32_bf16 v[32:35], v[216:219], v[178:181], v[32:35]
	v_mfma_f32_16x16x32_bf16 v[20:23], v[208:211], v[186:189], v[20:23]
	v_mfma_f32_16x16x32_bf16 v[16:19], v[216:219], v[186:189], v[16:19]
	v_mfma_f32_16x16x32_bf16 v[4:7], v[208:211], v[200:203], v[4:7]
	v_mfma_f32_16x16x32_bf16 v[0:3], v[216:219], v[200:203], v[0:3]
	s_setprio 0
	s_add_i32 s30, 0, 0x18000
	v_add_u32_e32 v140, s30, v155
	s_barrier
	ds_read_b128 v[128:131], v140
	ds_read_b128 v[132:135], v140 offset:1024
	ds_read_b128 v[136:139], v140 offset:2048
	ds_read_b128 v[140:143], v140 offset:3072
	s_add_u32 s50, s50, 0x40000
	s_addc_u32 s51, s51, 0
	s_mov_b32 m0, s7
	v_lshl_add_u64 v[204:205], s[50:51], 0, v[158:159]
	ds_read_b128 v[144:147], v193 offset:32768
	ds_read_b128 v[148:151], v193 offset:33792
	ds_read_b128 v[174:177], v193 offset:34816
	ds_read_b128 v[178:181], v193 offset:35840
	ds_read_b128 v[182:185], v193 offset:36864
	ds_read_b128 v[186:189], v193 offset:37888
	ds_read_b128 v[196:199], v193 offset:38912
	ds_read_b128 v[200:203], v193 offset:39936
	global_load_lds_dwordx4 v[204:205], off
	s_mov_b32 m0, s16
	v_lshl_add_u64 v[204:205], s[50:51], 0, v[162:163]
	global_load_lds_dwordx4 v[204:205], off
	s_waitcnt lgkmcnt(8)
	s_barrier
	s_waitcnt lgkmcnt(0)
	s_setprio 1
	v_mfma_f32_16x16x32_bf16 v[124:127], v[128:131], v[144:147], v[124:127]
	v_mfma_f32_16x16x32_bf16 v[120:123], v[136:139], v[144:147], v[120:123]
	v_mfma_f32_16x16x32_bf16 v[108:111], v[128:131], v[174:177], v[108:111]
	v_mfma_f32_16x16x32_bf16 v[104:107], v[136:139], v[174:177], v[104:107]
	v_mfma_f32_16x16x32_bf16 v[92:95], v[128:131], v[182:185], v[92:95]
	v_mfma_f32_16x16x32_bf16 v[88:91], v[136:139], v[182:185], v[88:91]
	v_mfma_f32_16x16x32_bf16 v[76:79], v[128:131], v[196:199], v[76:79]
	v_mfma_f32_16x16x32_bf16 v[72:75], v[136:139], v[196:199], v[72:75]
	v_mfma_f32_16x16x32_bf16 v[124:127], v[132:135], v[148:151], v[124:127]
	v_mfma_f32_16x16x32_bf16 v[120:123], v[140:143], v[148:151], v[120:123]
	v_mfma_f32_16x16x32_bf16 v[108:111], v[132:135], v[178:181], v[108:111]
	v_mfma_f32_16x16x32_bf16 v[104:107], v[140:143], v[178:181], v[104:107]
	v_mfma_f32_16x16x32_bf16 v[92:95], v[132:135], v[186:189], v[92:95]
	v_mfma_f32_16x16x32_bf16 v[88:91], v[140:143], v[186:189], v[88:91]
	v_mfma_f32_16x16x32_bf16 v[76:79], v[132:135], v[200:203], v[76:79]
	v_mfma_f32_16x16x32_bf16 v[72:75], v[140:143], v[200:203], v[72:75]
	s_setprio 0
	s_barrier
	s_add_i32 s43, 0, 0x1c000
	s_add_i32 s30, s30, s4
	v_add_u32_e32 v216, s43, v155
	v_lshl_add_u64 v[190:191], v[190:191], 0, s[14:15]
	s_mov_b32 m0, s30
	ds_read_b128 v[204:207], v216
	ds_read_b128 v[208:211], v216 offset:1024
	ds_read_b128 v[212:215], v216 offset:2048
	ds_read_b128 v[216:219], v216 offset:3072
	global_load_lds_dwordx4 v[190:191], off
	s_add_i32 m0, s30, 0x2000
	v_lshl_add_u64 v[190:191], v[220:221], 0, s[14:15]
	global_load_lds_dwordx4 v[190:191], off
	s_barrier
; #define PG8_STAGE(bufoff, gbase, voff) do { _Pragma("unroll") for (int _i = 0; _i < 2; ++_i) \
;         __builtin_amdgcn_global_load_lds((const unsigned*)((const char*)(gbase) + (voff)[_i]), (PG8_LAS unsigned*)(lds + (bufoff) + ldsw + _i * 8192), 16, 0, 0); } while (0)
; #define PG8_LDA(dst, b, h) do { _Pragma("unroll") for (int m = 0; m < 4; ++m) _Pragma("unroll") for (int k = 0; k < 2; ++k) dst[m][k] = *(const PG8_LAS bf16x8*)(lds + PG8_SA(b, h) + aoff + m * 2048 + k * 1024); } while (0)
; #define PG8_MMA(ai, bj, At, Bt) do { __builtin_amdgcn_s_setprio(1); _Pragma("unroll") for (int m = 0; m < 4; ++m) _Pragma("unroll") for (int n = 0; n < 2; ++n) _Pragma("unroll") for (int k = 0; k < 2; ++k) \
;         acc[ai][bj][m][n] = __builtin_amdgcn_mfma_f32_16x16x32_bf16(Bt[n][k], At[m][k], acc[ai][bj][m][n], 0, 0, 0); __builtin_amdgcn_s_setprio(0); } while (0)
; #define PG8_WAIT_V(n) asm volatile("s_waitcnt vmcnt(" #n ")" ::: "memory")
; #define PG8_WAIT_L(n) asm volatile("s_waitcnt lgkmcnt(" #n ")" ::: "memory")
; #define PG8_BAR __builtin_amdgcn_s_barrier()
; #define PG8_SCHED __builtin_amdgcn_sched_barrier(0)
; template <class Epi, class Sched>
; __device__ __forceinline__ void gemm_phase(PG8_LAS unsigned char* lds, const Gemm g, const Sched& S, const Epi& E) {
;     ...
;         for (int t = 0; t < cnk; t += 2) {
;     ...
;             PG8_BAR; PG8_WAIT_L(0); PG8_MMA(0, 1, At, B1); PG8_BAR;
;             PG8_LDA(At, 1, 1); PG8_STAGE(PG8_SA(1, 0), a3, voffA);
;             PG8_BAR; PG8_WAIT_L(0); PG8_MMA(1, 0, At, B0); PG8_BAR; PG8_SCHED;
;             PG8_STAGE(PG8_SB(1, 1), b3 + hstep, voffB);
;             PG8_WAIT_V(6); PG8_BAR; PG8_MMA(1, 1, At, B1); PG8_BAR;
;         }
	s_waitcnt lgkmcnt(0)
	s_setprio 1
	v_mfma_f32_16x16x32_bf16 v[116:119], v[204:207], v[144:147], v[116:119]
	v_mfma_f32_16x16x32_bf16 v[112:115], v[212:215], v[144:147], v[112:115]
	v_mfma_f32_16x16x32_bf16 v[100:103], v[204:207], v[174:177], v[100:103]
	v_mfma_f32_16x16x32_bf16 v[96:99], v[212:215], v[174:177], v[96:99]
	v_mfma_f32_16x16x32_bf16 v[84:87], v[204:207], v[182:185], v[84:87]
	v_mfma_f32_16x16x32_bf16 v[80:83], v[212:215], v[182:185], v[80:83]
	v_mfma_f32_16x16x32_bf16 v[68:71], v[204:207], v[196:199], v[68:71]
	v_mfma_f32_16x16x32_bf16 v[64:67], v[212:215], v[196:199], v[64:67]
	v_mfma_f32_16x16x32_bf16 v[116:119], v[208:211], v[148:151], v[116:119]
	v_mfma_f32_16x16x32_bf16 v[112:115], v[216:219], v[148:151], v[112:115]
	v_mfma_f32_16x16x32_bf16 v[100:103], v[208:211], v[178:181], v[100:103]
	v_mfma_f32_16x16x32_bf16 v[96:99], v[216:219], v[178:181], v[96:99]
	v_mfma_f32_16x16x32_bf16 v[84:87], v[208:211], v[186:189], v[84:87]
	v_mfma_f32_16x16x32_bf16 v[80:83], v[216:219], v[186:189], v[80:83]
	v_mfma_f32_16x16x32_bf16 v[68:71], v[208:211], v[200:203], v[68:71]
	v_mfma_f32_16x16x32_bf16 v[64:67], v[216:219], v[200:203], v[64:67]
	s_setprio 0
	s_mov_b32 m0, s18
	v_lshl_add_u64 v[190:191], v[222:223], 0, s[14:15]
	s_barrier
	ds_read_b128 v[144:147], v193 offset:49152
	ds_read_b128 v[148:151], v193 offset:50176
	ds_read_b128 v[174:177], v193 offset:51200
	ds_read_b128 v[178:181], v193 offset:52224
	ds_read_b128 v[182:185], v193 offset:53248
	ds_read_b128 v[186:189], v193 offset:54272
	ds_read_b128 v[196:199], v193 offset:55296
	ds_read_b128 v[200:203], v193 offset:56320
	global_load_lds_dwordx4 v[190:191], off
	s_mov_b32 m0, s19
	v_lshl_add_u64 v[190:191], v[224:225], 0, s[14:15]
	global_load_lds_dwordx4 v[190:191], off
	s_barrier
	s_waitcnt lgkmcnt(0)
	s_setprio 1
	v_mfma_f32_16x16x32_bf16 v[60:63], v[128:131], v[144:147], v[60:63]
	v_mfma_f32_16x16x32_bf16 v[56:59], v[136:139], v[144:147], v[56:59]
	v_mfma_f32_16x16x32_bf16 v[44:47], v[128:131], v[174:177], v[44:47]
	v_mfma_f32_16x16x32_bf16 v[40:43], v[136:139], v[174:177], v[40:43]
	v_mfma_f32_16x16x32_bf16 v[28:31], v[128:131], v[182:185], v[28:31]
	v_mfma_f32_16x16x32_bf16 v[24:27], v[136:139], v[182:185], v[24:27]
	v_mfma_f32_16x16x32_bf16 v[12:15], v[128:131], v[196:199], v[12:15]
	v_mfma_f32_16x16x32_bf16 v[8:11], v[136:139], v[196:199], v[8:11]
	v_mfma_f32_16x16x32_bf16 v[60:63], v[132:135], v[148:151], v[60:63]
	v_mfma_f32_16x16x32_bf16 v[56:59], v[140:143], v[148:151], v[56:59]
	v_mfma_f32_16x16x32_bf16 v[44:47], v[132:135], v[178:181], v[44:47]
	v_mfma_f32_16x16x32_bf16 v[40:43], v[140:143], v[178:181], v[40:43]
	v_mfma_f32_16x16x32_bf16 v[28:31], v[132:135], v[186:189], v[28:31]
	v_mfma_f32_16x16x32_bf16 v[24:27], v[140:143], v[186:189], v[24:27]
	v_mfma_f32_16x16x32_bf16 v[12:15], v[132:135], v[200:203], v[12:15]
	v_mfma_f32_16x16x32_bf16 v[8:11], v[140:143], v[200:203], v[8:11]
	s_setprio 0
	s_barrier
	s_add_u32 s48, s48, 0x40080
	s_addc_u32 s49, s49, 0
	s_add_i32 s30, s43, s4
	s_mov_b32 m0, s30
	v_lshl_add_u64 v[128:129], s[48:49], 0, v[160:161]
	global_load_lds_dwordx4 v[128:129], off
	s_add_i32 m0, s30, 0x2000
	v_lshl_add_u64 v[128:129], s[48:49], 0, v[164:165]
	global_load_lds_dwordx4 v[128:129], off
	s_waitcnt vmcnt(6)
	s_barrier
	s_setprio 1
	v_mfma_f32_16x16x32_bf16 v[52:55], v[204:207], v[144:147], v[52:55]
	v_mfma_f32_16x16x32_bf16 v[48:51], v[212:215], v[144:147], v[48:51]
	v_mfma_f32_16x16x32_bf16 v[36:39], v[204:207], v[174:177], v[36:39]
	v_mfma_f32_16x16x32_bf16 v[32:35], v[212:215], v[174:177], v[32:35]
	v_mfma_f32_16x16x32_bf16 v[20:23], v[204:207], v[182:185], v[20:23]
	v_mfma_f32_16x16x32_bf16 v[16:19], v[212:215], v[182:185], v[16:19]
	v_mfma_f32_16x16x32_bf16 v[4:7], v[204:207], v[196:199], v[4:7]
	v_mfma_f32_16x16x32_bf16 v[0:3], v[212:215], v[196:199], v[0:3]
	v_mfma_f32_16x16x32_bf16 v[52:55], v[208:211], v[148:151], v[52:55]
	v_mfma_f32_16x16x32_bf16 v[48:51], v[216:219], v[148:151], v[48:51]
	v_mfma_f32_16x16x32_bf16 v[36:39], v[208:211], v[178:181], v[36:39]
	v_mfma_f32_16x16x32_bf16 v[32:35], v[216:219], v[178:181], v[32:35]
	v_mfma_f32_16x16x32_bf16 v[20:23], v[208:211], v[186:189], v[20:23]
	v_mfma_f32_16x16x32_bf16 v[16:19], v[216:219], v[186:189], v[16:19]
	v_mfma_f32_16x16x32_bf16 v[4:7], v[208:211], v[200:203], v[4:7]
	v_mfma_f32_16x16x32_bf16 v[0:3], v[216:219], v[200:203], v[0:3]
	s_setprio 0
	s_add_u32 s46, s46, 0x100
	s_addc_u32 s47, s47, 0
	s_add_u32 s27, s27, 0x100
	s_addc_u32 s37, s37, 0
	s_cmp_ge_i32 s70, s23
	s_mov_b32 s43, s70
	s_barrier
	s_cbranch_scc0 .LBB0_2251
	s_cmp_gt_i32 s12, -1
	s_mov_b64 s[46:47], -1
	s_cbranch_scc0 .LBB0_2254

; #define PG8_STAGE(bufoff, gbase, voff) do { _Pragma("unroll") for (int _i = 0; _i < 2; ++_i) \
;         __builtin_amdgcn_global_load_lds((const unsigned*)((const char*)(gbase) + (voff)[_i]), (PG8_LAS unsigned*)(lds + (bufoff) + ldsw + _i * 8192), 16, 0, 0); } while (0)
; #define PG8_LDA(dst, b, h) do { _Pragma("unroll") for (int m = 0; m < 4; ++m) _Pragma("unroll") for (int k = 0; k < 2; ++k) dst[m][k] = *(const PG8_LAS bf16x8*)(lds + PG8_SA(b, h) + aoff + m * 2048 + k * 1024); } while (0)
; #define PG8_LDB(dst, b, h) do { _Pragma("unroll") for (int n = 0; n < 2; ++n) _Pragma("unroll") for (int k = 0; k < 2; ++k) dst[n][k] = *(const PG8_LAS bf16x8*)(lds + PG8_SB(b, h) + boff + n * 2048 + k * 1024); } while (0)
; #define PG8_MMA(ai, bj, At, Bt) do { __builtin_amdgcn_s_setprio(1); _Pragma("unroll") for (int m = 0; m < 4; ++m) _Pragma("unroll") for (int n = 0; n < 2; ++n) _Pragma("unroll") for (int k = 0; k < 2; ++k) \
;         acc[ai][bj][m][n] = __builtin_amdgcn_mfma_f32_16x16x32_bf16(Bt[n][k], At[m][k], acc[ai][bj][m][n], 0, 0, 0); __builtin_amdgcn_s_setprio(0); } while (0)
; #define PG8_WAIT_L(n) asm volatile("s_waitcnt lgkmcnt(" #n ")" ::: "memory")
; #define PG8_BAR __builtin_amdgcn_s_barrier()
; #define PG8_SCHED __builtin_amdgcn_sched_barrier(0)
; template <class Epi, class Sched>
; __device__ __forceinline__ void gemm_phase(PG8_LAS unsigned char* lds, const Gemm g, const Sched& S, const Epi& E) {
;     ...
;             const bool last = (t == cnk - 2);
;             const char* a1 = cA + (size_t)(t + 1) * kstep;
;             const char* a2 = last ? nA : cA + (size_t)(t + 2) * kstep; const char* b2 = last ? nB : cB + (size_t)(t + 2) * kstep;
;             const char* a3 = a2 + kstep; const char* b3 = b2 + kstep;
;             if (last && has_next) S.a_ready(nxt);
;             if (last) E.prefetch(pre, cur, wr, fr);
;             PG8_LDB(B0, 0, 0); PG8_SCHED; PG8_LDA(At, 0, 0); PG8_STAGE(PG8_SA(1, 1), a1 + hstep, voffA);
;             PG8_WAIT_L(8); PG8_BAR; PG8_WAIT_L(0); PG8_MMA(0, 0, At, B0); PG8_BAR; PG8_SCHED;
;             PG8_LDB(B1, 0, 1); PG8_STAGE(PG8_SB(0, 0), b2, voffB);
;             PG8_BAR; PG8_WAIT_L(0); PG8_MMA(0, 1, At, B1); PG8_BAR;
;             PG8_LDA(At, 0, 1); PG8_STAGE(PG8_SA(0, 0), a2, voffA);
;             PG8_BAR; PG8_WAIT_L(0); PG8_MMA(1, 0, At, B0); PG8_BAR; PG8_SCHED;
.LBB0_2447:
	v_add_u32_e32 v176, s28, v155
	ds_read_b128 v[164:167], v176
	ds_read_b128 v[168:171], v176 offset:1024
	ds_read_b128 v[172:175], v176 offset:2048
	ds_read_b128 v[180:183], v176 offset:3072
	s_add_u32 s12, s6, 0xfffc0080
	s_addc_u32 s13, s7, -1
	s_and_b64 s[8:9], s[8:9], exec
	s_cselect_b32 s13, s37, s13
	s_cselect_b32 s12, s42, s12
	s_cselect_b32 s9, s27, s53
	s_cselect_b32 s8, s43, s52
	v_lshl_add_u64 v[176:177], s[6:7], 0, v[138:139]
	s_add_i32 m0, s17, 0xc000
	ds_read_b128 v[184:187], v178
	ds_read_b128 v[188:191], v178 offset:1024
	ds_read_b128 v[192:195], v178 offset:2048
	ds_read_b128 v[196:199], v178 offset:3072
	ds_read_b128 v[200:203], v178 offset:4096
	ds_read_b128 v[204:207], v178 offset:5120
	ds_read_b128 v[208:211], v178 offset:6144
	ds_read_b128 v[212:215], v178 offset:7168
	global_load_lds_dwordx4 v[176:177], off
	s_add_i32 m0, s17, 0xe000
	v_lshl_add_u64 v[176:177], s[6:7], 0, v[140:141]
	global_load_lds_dwordx4 v[176:177], off
	s_waitcnt lgkmcnt(8)
	s_barrier
	s_waitcnt lgkmcnt(0)
	s_setprio 1
	v_mfma_f32_16x16x32_bf16 v[124:127], v[164:167], v[184:187], v[124:127]
	v_mfma_f32_16x16x32_bf16 v[120:123], v[172:175], v[184:187], v[120:123]
	v_mfma_f32_16x16x32_bf16 v[108:111], v[164:167], v[192:195], v[108:111]
	v_mfma_f32_16x16x32_bf16 v[104:107], v[172:175], v[192:195], v[104:107]
	v_mfma_f32_16x16x32_bf16 v[92:95], v[164:167], v[200:203], v[92:95]
	v_mfma_f32_16x16x32_bf16 v[88:91], v[172:175], v[200:203], v[88:91]
	v_mfma_f32_16x16x32_bf16 v[76:79], v[164:167], v[208:211], v[76:79]
	v_mfma_f32_16x16x32_bf16 v[72:75], v[172:175], v[208:211], v[72:75]
	v_mfma_f32_16x16x32_bf16 v[124:127], v[168:171], v[188:191], v[124:127]
	v_mfma_f32_16x16x32_bf16 v[120:123], v[180:183], v[188:191], v[120:123]
	v_mfma_f32_16x16x32_bf16 v[108:111], v[168:171], v[196:199], v[108:111]
	v_mfma_f32_16x16x32_bf16 v[104:107], v[180:183], v[196:199], v[104:107]
	v_mfma_f32_16x16x32_bf16 v[92:95], v[168:171], v[204:207], v[92:95]
	v_mfma_f32_16x16x32_bf16 v[88:91], v[180:183], v[204:207], v[88:91]
	v_mfma_f32_16x16x32_bf16 v[76:79], v[168:171], v[212:215], v[76:79]
	v_mfma_f32_16x16x32_bf16 v[72:75], v[180:183], v[212:215], v[72:75]
	s_setprio 0
	s_barrier
	v_add_u32_e32 v176, s70, v155
	s_add_i32 s30, s28, s3
	ds_read_b128 v[216:219], v176
	ds_read_b128 v[220:223], v176 offset:1024
	ds_read_b128 v[224:227], v176 offset:2048
	ds_read_b128 v[228:231], v176 offset:3072
	v_lshl_add_u64 v[176:177], s[8:9], 0, v[132:133]
	s_mov_b32 m0, s30
	v_lshl_add_u64 v[232:233], s[8:9], 0, v[128:129]
	global_load_lds_dwordx4 v[176:177], off
	s_add_i32 m0, s30, 0x2000
	s_nop 0
	global_load_lds_dwordx4 v[232:233], off
	s_barrier
	s_waitcnt lgkmcnt(0)
	s_setprio 1
	v_mfma_f32_16x16x32_bf16 v[116:119], v[216:219], v[184:187], v[116:119]
	v_mfma_f32_16x16x32_bf16 v[112:115], v[224:227], v[184:187], v[112:115]
	v_mfma_f32_16x16x32_bf16 v[100:103], v[216:219], v[192:195], v[100:103]
	v_mfma_f32_16x16x32_bf16 v[96:99], v[224:227], v[192:195], v[96:99]
	v_mfma_f32_16x16x32_bf16 v[84:87], v[216:219], v[200:203], v[84:87]
	v_mfma_f32_16x16x32_bf16 v[80:83], v[224:227], v[200:203], v[80:83]
	v_mfma_f32_16x16x32_bf16 v[68:71], v[216:219], v[208:211], v[68:71]
	v_mfma_f32_16x16x32_bf16 v[64:67], v[224:227], v[208:211], v[64:67]
	v_mfma_f32_16x16x32_bf16 v[116:119], v[220:223], v[188:191], v[116:119]
	v_mfma_f32_16x16x32_bf16 v[112:115], v[228:231], v[188:191], v[112:115]
	v_mfma_f32_16x16x32_bf16 v[100:103], v[220:223], v[196:199], v[100:103]
	v_mfma_f32_16x16x32_bf16 v[96:99], v[228:231], v[196:199], v[96:99]
	v_mfma_f32_16x16x32_bf16 v[84:87], v[220:223], v[204:207], v[84:87]
	v_mfma_f32_16x16x32_bf16 v[80:83], v[228:231], v[204:207], v[80:83]
	v_mfma_f32_16x16x32_bf16 v[68:71], v[220:223], v[212:215], v[68:71]
	v_mfma_f32_16x16x32_bf16 v[64:67], v[228:231], v[212:215], v[64:67]
	s_setprio 0
	s_mov_b32 m0, s17
	v_lshl_add_u64 v[234:235], s[12:13], 0, v[134:135]
	s_barrier
	ds_read_b128 v[184:187], v178 offset:16384
	ds_read_b128 v[188:191], v178 offset:17408
	ds_read_b128 v[192:195], v178 offset:18432
	ds_read_b128 v[196:199], v178 offset:19456
	ds_read_b128 v[200:203], v178 offset:20480
	ds_read_b128 v[204:207], v178 offset:21504
	ds_read_b128 v[208:211], v178 offset:22528
	ds_read_b128 v[212:215], v178 offset:23552
	global_load_lds_dwordx4 v[234:235], off
	s_mov_b32 m0, s19
	v_lshl_add_u64 v[236:237], s[12:13], 0, v[130:131]
	global_load_lds_dwordx4 v[236:237], off
	s_barrier
	s_waitcnt lgkmcnt(0)
	s_setprio 1
	v_mfma_f32_16x16x32_bf16 v[60:63], v[164:167], v[184:187], v[60:63]
	v_mfma_f32_16x16x32_bf16 v[56:59], v[172:175], v[184:187], v[56:59]
	v_mfma_f32_16x16x32_bf16 v[44:47], v[164:167], v[192:195], v[44:47]
	v_mfma_f32_16x16x32_bf16 v[40:43], v[172:175], v[192:195], v[40:43]
	v_mfma_f32_16x16x32_bf16 v[28:31], v[164:167], v[200:203], v[28:31]
	v_mfma_f32_16x16x32_bf16 v[24:27], v[172:175], v[200:203], v[24:27]
	v_mfma_f32_16x16x32_bf16 v[12:15], v[164:167], v[208:211], v[12:15]
	v_mfma_f32_16x16x32_bf16 v[8:11], v[172:175], v[208:211], v[8:11]
	v_mfma_f32_16x16x32_bf16 v[60:63], v[168:171], v[188:191], v[60:63]
	v_mfma_f32_16x16x32_bf16 v[56:59], v[180:183], v[188:191], v[56:59]
	v_mfma_f32_16x16x32_bf16 v[44:47], v[168:171], v[196:199], v[44:47]
	v_mfma_f32_16x16x32_bf16 v[40:43], v[180:183], v[196:199], v[40:43]
	v_mfma_f32_16x16x32_bf16 v[28:31], v[168:171], v[204:207], v[28:31]
	v_mfma_f32_16x16x32_bf16 v[24:27], v[180:183], v[204:207], v[24:27]
	v_mfma_f32_16x16x32_bf16 v[12:15], v[168:171], v[212:215], v[12:15]
	v_mfma_f32_16x16x32_bf16 v[8:11], v[180:183], v[212:215], v[8:11]
	s_setprio 0
	s_barrier
; #define PG8_STAGE(bufoff, gbase, voff) do { _Pragma("unroll") for (int _i = 0; _i < 2; ++_i) \
;         __builtin_amdgcn_global_load_lds((const unsigned*)((const char*)(gbase) + (voff)[_i]), (PG8_LAS unsigned*)(lds + (bufoff) + ldsw + _i * 8192), 16, 0, 0); } while (0)
; #define PG8_LDA(dst, b, h) do { _Pragma("unroll") for (int m = 0; m < 4; ++m) _Pragma("unroll") for (int k = 0; k < 2; ++k) dst[m][k] = *(const PG8_LAS bf16x8*)(lds + PG8_SA(b, h) + aoff + m * 2048 + k * 1024); } while (0)
; #define PG8_LDB(dst, b, h) do { _Pragma("unroll") for (int n = 0; n < 2; ++n) _Pragma("unroll") for (int k = 0; k < 2; ++k) dst[n][k] = *(const PG8_LAS bf16x8*)(lds + PG8_SB(b, h) + boff + n * 2048 + k * 1024); } while (0)
; #define PG8_MMA(ai, bj, At, Bt) do { __builtin_amdgcn_s_setprio(1); _Pragma("unroll") for (int m = 0; m < 4; ++m) _Pragma("unroll") for (int n = 0; n < 2; ++n) _Pragma("unroll") for (int k = 0; k < 2; ++k) \
;         acc[ai][bj][m][n] = __builtin_amdgcn_mfma_f32_16x16x32_bf16(Bt[n][k], At[m][k], acc[ai][bj][m][n], 0, 0, 0); __builtin_amdgcn_s_setprio(0); } while (0)
; #define PG8_WAIT_V(n) asm volatile("s_waitcnt vmcnt(" #n ")" ::: "memory")
; #define PG8_WAIT_L(n) asm volatile("s_waitcnt lgkmcnt(" #n ")" ::: "memory")
; #define PG8_BAR __builtin_amdgcn_s_barrier()
; #define PG8_SCHED __builtin_amdgcn_sched_barrier(0)
; template <class Epi, class Sched>
; __device__ __forceinline__ void gemm_phase(PG8_LAS unsigned char* lds, const Gemm g, const Sched& S, const Epi& E) {
;     ...
;             PG8_STAGE(PG8_SB(0, 1), b2 + hstep, voffB);
;             PG8_WAIT_V(6); PG8_BAR; PG8_MMA(1, 1, At, B1); PG8_BAR;
;             PG8_LDB(B0, 1, 0); PG8_SCHED; PG8_LDA(At, 1, 0); PG8_STAGE(PG8_SA(0, 1), a2 + hstep, voffA);
;             PG8_WAIT_L(8); PG8_BAR; PG8_WAIT_L(0); PG8_MMA(0, 0, At, B0); PG8_BAR; PG8_SCHED;
;             PG8_LDB(B1, 1, 1); PG8_STAGE(PG8_SB(1, 0), b3, voffB);
	s_add_u32 s56, s8, 0x40000
	s_addc_u32 s57, s9, 0
	s_add_i32 s30, s70, s3
	s_mov_b32 m0, s30
	v_lshl_add_u64 v[164:165], s[56:57], 0, v[132:133]
	global_load_lds_dwordx4 v[164:165], off
	s_add_i32 m0, s30, 0x2000
	v_lshl_add_u64 v[164:165], s[56:57], 0, v[128:129]
	global_load_lds_dwordx4 v[164:165], off
	s_waitcnt vmcnt(6)
	s_barrier
	s_setprio 1
	v_mfma_f32_16x16x32_bf16 v[52:55], v[216:219], v[184:187], v[52:55]
	v_mfma_f32_16x16x32_bf16 v[48:51], v[224:227], v[184:187], v[48:51]
	v_mfma_f32_16x16x32_bf16 v[36:39], v[216:219], v[192:195], v[36:39]
	v_mfma_f32_16x16x32_bf16 v[32:35], v[224:227], v[192:195], v[32:35]
	v_mfma_f32_16x16x32_bf16 v[20:23], v[216:219], v[200:203], v[20:23]
	v_mfma_f32_16x16x32_bf16 v[16:19], v[224:227], v[200:203], v[16:19]
	v_mfma_f32_16x16x32_bf16 v[4:7], v[216:219], v[208:211], v[4:7]
	v_mfma_f32_16x16x32_bf16 v[0:3], v[224:227], v[208:211], v[0:3]
	v_mfma_f32_16x16x32_bf16 v[52:55], v[220:223], v[188:191], v[52:55]
	v_mfma_f32_16x16x32_bf16 v[48:51], v[228:231], v[188:191], v[48:51]
	v_mfma_f32_16x16x32_bf16 v[36:39], v[220:223], v[196:199], v[36:39]
	v_mfma_f32_16x16x32_bf16 v[32:35], v[228:231], v[196:199], v[32:35]
	v_mfma_f32_16x16x32_bf16 v[20:23], v[220:223], v[204:207], v[20:23]
	v_mfma_f32_16x16x32_bf16 v[16:19], v[228:231], v[204:207], v[16:19]
	v_mfma_f32_16x16x32_bf16 v[4:7], v[220:223], v[212:215], v[4:7]
	v_mfma_f32_16x16x32_bf16 v[0:3], v[228:231], v[212:215], v[0:3]
	s_setprio 0
	s_add_i32 s30, 0, 0x18000
	v_add_u32_e32 v180, s30, v155
	s_barrier
	ds_read_b128 v[164:167], v180
	ds_read_b128 v[168:171], v180 offset:1024
	ds_read_b128 v[172:175], v180 offset:2048
	ds_read_b128 v[180:183], v180 offset:3072
	s_add_u32 s12, s12, 0x40000
	s_addc_u32 s13, s13, 0
	s_mov_b32 m0, s21
	v_lshl_add_u64 v[216:217], s[12:13], 0, v[134:135]
	ds_read_b128 v[184:187], v178 offset:32768
	ds_read_b128 v[188:191], v178 offset:33792
	ds_read_b128 v[192:195], v178 offset:34816
	ds_read_b128 v[196:199], v178 offset:35840
	ds_read_b128 v[200:203], v178 offset:36864
	ds_read_b128 v[204:207], v178 offset:37888
	ds_read_b128 v[208:211], v178 offset:38912
	ds_read_b128 v[212:215], v178 offset:39936
	global_load_lds_dwordx4 v[216:217], off
	s_mov_b32 m0, s29
	v_lshl_add_u64 v[216:217], s[12:13], 0, v[130:131]
	global_load_lds_dwordx4 v[216:217], off
	s_waitcnt lgkmcnt(8)
	s_barrier
	s_waitcnt lgkmcnt(0)
	s_setprio 1
	v_mfma_f32_16x16x32_bf16 v[124:127], v[164:167], v[184:187], v[124:127]
	v_mfma_f32_16x16x32_bf16 v[120:123], v[172:175], v[184:187], v[120:123]
	v_mfma_f32_16x16x32_bf16 v[108:111], v[164:167], v[192:195], v[108:111]
	v_mfma_f32_16x16x32_bf16 v[104:107], v[172:175], v[192:195], v[104:107]
	v_mfma_f32_16x16x32_bf16 v[92:95], v[164:167], v[200:203], v[92:95]
	v_mfma_f32_16x16x32_bf16 v[88:91], v[172:175], v[200:203], v[88:91]
	v_mfma_f32_16x16x32_bf16 v[76:79], v[164:167], v[208:211], v[76:79]
	v_mfma_f32_16x16x32_bf16 v[72:75], v[172:175], v[208:211], v[72:75]
	v_mfma_f32_16x16x32_bf16 v[124:127], v[168:171], v[188:191], v[124:127]
	v_mfma_f32_16x16x32_bf16 v[120:123], v[180:183], v[188:191], v[120:123]
	v_mfma_f32_16x16x32_bf16 v[108:111], v[168:171], v[196:199], v[108:111]
	v_mfma_f32_16x16x32_bf16 v[104:107], v[180:183], v[196:199], v[104:107]
	v_mfma_f32_16x16x32_bf16 v[92:95], v[168:171], v[204:207], v[92:95]
	v_mfma_f32_16x16x32_bf16 v[88:91], v[180:183], v[204:207], v[88:91]
	v_mfma_f32_16x16x32_bf16 v[76:79], v[168:171], v[212:215], v[76:79]
	v_mfma_f32_16x16x32_bf16 v[72:75], v[180:183], v[212:215], v[72:75]
	s_setprio 0
	s_barrier
	s_add_i32 s12, 0, 0x1c000
	s_add_i32 s13, s30, s3
	v_add_u32_e32 v228, s12, v155
	v_lshl_add_u64 v[176:177], v[176:177], 0, s[14:15]
	s_mov_b32 m0, s13
	ds_read_b128 v[216:219], v228
	ds_read_b128 v[220:223], v228 offset:1024
	ds_read_b128 v[224:227], v228 offset:2048
	ds_read_b128 v[228:231], v228 offset:3072
	global_load_lds_dwordx4 v[176:177], off
	s_add_i32 m0, s13, 0x2000
	v_lshl_add_u64 v[176:177], v[232:233], 0, s[14:15]
	global_load_lds_dwordx4 v[176:177], off
	s_barrier
; #define PG8_STAGE(bufoff, gbase, voff) do { _Pragma("unroll") for (int _i = 0; _i < 2; ++_i) \
;         __builtin_amdgcn_global_load_lds((const unsigned*)((const char*)(gbase) + (voff)[_i]), (PG8_LAS unsigned*)(lds + (bufoff) + ldsw + _i * 8192), 16, 0, 0); } while (0)
; #define PG8_LDA(dst, b, h) do { _Pragma("unroll") for (int m = 0; m < 4; ++m) _Pragma("unroll") for (int k = 0; k < 2; ++k) dst[m][k] = *(const PG8_LAS bf16x8*)(lds + PG8_SA(b, h) + aoff + m * 2048 + k * 1024); } while (0)
; #define PG8_MMA(ai, bj, At, Bt) do { __builtin_amdgcn_s_setprio(1); _Pragma("unroll") for (int m = 0; m < 4; ++m) _Pragma("unroll") for (int n = 0; n < 2; ++n) _Pragma("unroll") for (int k = 0; k < 2; ++k) \
;         acc[ai][bj][m][n] = __builtin_amdgcn_mfma_f32_16x16x32_bf16(Bt[n][k], At[m][k], acc[ai][bj][m][n], 0, 0, 0); __builtin_amdgcn_s_setprio(0); } while (0)
; #define PG8_WAIT_V(n) asm volatile("s_waitcnt vmcnt(" #n ")" ::: "memory")
; #define PG8_WAIT_L(n) asm volatile("s_waitcnt lgkmcnt(" #n ")" ::: "memory")
; #define PG8_BAR __builtin_amdgcn_s_barrier()
; #define PG8_SCHED __builtin_amdgcn_sched_barrier(0)
; template <class Epi, class Sched>
; __device__ __forceinline__ void gemm_phase(PG8_LAS unsigned char* lds, const Gemm g, const Sched& S, const Epi& E) {
;     ...
;         for (int t = 0; t < cnk; t += 2) {
;     ...
;             PG8_BAR; PG8_WAIT_L(0); PG8_MMA(0, 1, At, B1); PG8_BAR;
;             PG8_LDA(At, 1, 1); PG8_STAGE(PG8_SA(1, 0), a3, voffA);
;             PG8_BAR; PG8_WAIT_L(0); PG8_MMA(1, 0, At, B0); PG8_BAR; PG8_SCHED;
;             PG8_STAGE(PG8_SB(1, 1), b3 + hstep, voffB);
;             PG8_WAIT_V(6); PG8_BAR; PG8_MMA(1, 1, At, B1); PG8_BAR;
;         }
	s_waitcnt lgkmcnt(0)
	s_setprio 1
	v_mfma_f32_16x16x32_bf16 v[116:119], v[216:219], v[184:187], v[116:119]
	v_mfma_f32_16x16x32_bf16 v[112:115], v[224:227], v[184:187], v[112:115]
	v_mfma_f32_16x16x32_bf16 v[100:103], v[216:219], v[192:195], v[100:103]
	v_mfma_f32_16x16x32_bf16 v[96:99], v[224:227], v[192:195], v[96:99]
	v_mfma_f32_16x16x32_bf16 v[84:87], v[216:219], v[200:203], v[84:87]
	v_mfma_f32_16x16x32_bf16 v[80:83], v[224:227], v[200:203], v[80:83]
	v_mfma_f32_16x16x32_bf16 v[68:71], v[216:219], v[208:211], v[68:71]
	v_mfma_f32_16x16x32_bf16 v[64:67], v[224:227], v[208:211], v[64:67]
	v_mfma_f32_16x16x32_bf16 v[116:119], v[220:223], v[188:191], v[116:119]
	v_mfma_f32_16x16x32_bf16 v[112:115], v[228:231], v[188:191], v[112:115]
	v_mfma_f32_16x16x32_bf16 v[100:103], v[220:223], v[196:199], v[100:103]
	v_mfma_f32_16x16x32_bf16 v[96:99], v[228:231], v[196:199], v[96:99]
	v_mfma_f32_16x16x32_bf16 v[84:87], v[220:223], v[204:207], v[84:87]
	v_mfma_f32_16x16x32_bf16 v[80:83], v[228:231], v[204:207], v[80:83]
	v_mfma_f32_16x16x32_bf16 v[68:71], v[220:223], v[212:215], v[68:71]
	v_mfma_f32_16x16x32_bf16 v[64:67], v[228:231], v[212:215], v[64:67]
	s_setprio 0
	s_mov_b32 m0, s34
	v_lshl_add_u64 v[176:177], v[234:235], 0, s[14:15]
	s_barrier
	ds_read_b128 v[184:187], v178 offset:49152
	ds_read_b128 v[188:191], v178 offset:50176
	ds_read_b128 v[192:195], v178 offset:51200
	ds_read_b128 v[196:199], v178 offset:52224
	ds_read_b128 v[200:203], v178 offset:53248
	ds_read_b128 v[204:207], v178 offset:54272
	ds_read_b128 v[208:211], v178 offset:55296
	ds_read_b128 v[212:215], v178 offset:56320
	global_load_lds_dwordx4 v[176:177], off
	s_mov_b32 m0, s35
	v_lshl_add_u64 v[176:177], v[236:237], 0, s[14:15]
	global_load_lds_dwordx4 v[176:177], off
	s_barrier
	s_waitcnt lgkmcnt(0)
	s_setprio 1
	v_mfma_f32_16x16x32_bf16 v[60:63], v[164:167], v[184:187], v[60:63]
	v_mfma_f32_16x16x32_bf16 v[56:59], v[172:175], v[184:187], v[56:59]
	v_mfma_f32_16x16x32_bf16 v[44:47], v[164:167], v[192:195], v[44:47]
	v_mfma_f32_16x16x32_bf16 v[40:43], v[172:175], v[192:195], v[40:43]
	v_mfma_f32_16x16x32_bf16 v[28:31], v[164:167], v[200:203], v[28:31]
	v_mfma_f32_16x16x32_bf16 v[24:27], v[172:175], v[200:203], v[24:27]
	v_mfma_f32_16x16x32_bf16 v[12:15], v[164:167], v[208:211], v[12:15]
	v_mfma_f32_16x16x32_bf16 v[8:11], v[172:175], v[208:211], v[8:11]
	v_mfma_f32_16x16x32_bf16 v[60:63], v[168:171], v[188:191], v[60:63]
	v_mfma_f32_16x16x32_bf16 v[56:59], v[180:183], v[188:191], v[56:59]
	v_mfma_f32_16x16x32_bf16 v[44:47], v[168:171], v[196:199], v[44:47]
	v_mfma_f32_16x16x32_bf16 v[40:43], v[180:183], v[196:199], v[40:43]
	v_mfma_f32_16x16x32_bf16 v[28:31], v[168:171], v[204:207], v[28:31]
	v_mfma_f32_16x16x32_bf16 v[24:27], v[180:183], v[204:207], v[24:27]
	v_mfma_f32_16x16x32_bf16 v[12:15], v[168:171], v[212:215], v[12:15]
	v_mfma_f32_16x16x32_bf16 v[8:11], v[180:183], v[212:215], v[8:11]
	s_setprio 0
	s_barrier
	s_add_u32 s8, s8, 0x40080
	s_addc_u32 s9, s9, 0
	s_add_i32 s12, s12, s3
	s_mov_b32 m0, s12
	v_lshl_add_u64 v[164:165], s[8:9], 0, v[132:133]
	global_load_lds_dwordx4 v[164:165], off
	s_add_i32 m0, s12, 0x2000
	v_lshl_add_u64 v[164:165], s[8:9], 0, v[128:129]
	global_load_lds_dwordx4 v[164:165], off
	s_waitcnt vmcnt(6)
	s_barrier
	s_setprio 1
	v_mfma_f32_16x16x32_bf16 v[52:55], v[216:219], v[184:187], v[52:55]
	v_mfma_f32_16x16x32_bf16 v[48:51], v[224:227], v[184:187], v[48:51]
	v_mfma_f32_16x16x32_bf16 v[36:39], v[216:219], v[192:195], v[36:39]
	v_mfma_f32_16x16x32_bf16 v[32:35], v[224:227], v[192:195], v[32:35]
	v_mfma_f32_16x16x32_bf16 v[20:23], v[216:219], v[200:203], v[20:23]
	v_mfma_f32_16x16x32_bf16 v[16:19], v[224:227], v[200:203], v[16:19]
	v_mfma_f32_16x16x32_bf16 v[4:7], v[216:219], v[208:211], v[4:7]
	v_mfma_f32_16x16x32_bf16 v[0:3], v[224:227], v[208:211], v[0:3]
	v_mfma_f32_16x16x32_bf16 v[52:55], v[220:223], v[188:191], v[52:55]
	v_mfma_f32_16x16x32_bf16 v[48:51], v[228:231], v[188:191], v[48:51]
	v_mfma_f32_16x16x32_bf16 v[36:39], v[220:223], v[196:199], v[36:39]
	v_mfma_f32_16x16x32_bf16 v[32:35], v[228:231], v[196:199], v[32:35]
	v_mfma_f32_16x16x32_bf16 v[20:23], v[220:223], v[204:207], v[20:23]
	v_mfma_f32_16x16x32_bf16 v[16:19], v[228:231], v[204:207], v[16:19]
	v_mfma_f32_16x16x32_bf16 v[4:7], v[220:223], v[212:215], v[4:7]
	v_mfma_f32_16x16x32_bf16 v[0:3], v[228:231], v[212:215], v[0:3]
	s_setprio 0
	s_add_i32 s54, s54, 2
	s_add_u32 s6, s6, 0x100
	s_addc_u32 s7, s7, 0
	s_add_u32 s52, s52, 0x100
	s_addc_u32 s53, s53, 0
	s_cmp_lt_u32 s54, 14
	s_barrier
	s_cbranch_scc0 .LBB0_2450

; #define PG8_STAGE(bufoff, gbase, voff) do { _Pragma("unroll") for (int _i = 0; _i < 2; ++_i) \
;         __builtin_amdgcn_global_load_lds((const unsigned*)((const char*)(gbase) + (voff)[_i]), (PG8_LAS unsigned*)(lds + (bufoff) + ldsw + _i * 8192), 16, 0, 0); } while (0)
; #define PG8_LDA(dst, b, h) do { _Pragma("unroll") for (int m = 0; m < 4; ++m) _Pragma("unroll") for (int k = 0; k < 2; ++k) dst[m][k] = *(const PG8_LAS bf16x8*)(lds + PG8_SA(b, h) + aoff + m * 2048 + k * 1024); } while (0)
; #define PG8_LDB(dst, b, h) do { _Pragma("unroll") for (int n = 0; n < 2; ++n) _Pragma("unroll") for (int k = 0; k < 2; ++k) dst[n][k] = *(const PG8_LAS bf16x8*)(lds + PG8_SB(b, h) + boff + n * 2048 + k * 1024); } while (0)
; #define PG8_MMA(ai, bj, At, Bt) do { __builtin_amdgcn_s_setprio(1); _Pragma("unroll") for (int m = 0; m < 4; ++m) _Pragma("unroll") for (int n = 0; n < 2; ++n) _Pragma("unroll") for (int k = 0; k < 2; ++k) \
;         acc[ai][bj][m][n] = __builtin_amdgcn_mfma_f32_16x16x32_bf16(Bt[n][k], At[m][k], acc[ai][bj][m][n], 0, 0, 0); __builtin_amdgcn_s_setprio(0); } while (0)
; #define PG8_WAIT_L(n) asm volatile("s_waitcnt lgkmcnt(" #n ")" ::: "memory")
; #define PG8_BAR __builtin_amdgcn_s_barrier()
; #define PG8_SCHED __builtin_amdgcn_sched_barrier(0)
; template <class Epi, class Sched>
; __device__ __forceinline__ void gemm_phase(PG8_LAS unsigned char* lds, const Gemm g, const Sched& S, const Epi& E) {
;     ...
;             const bool last = (t == cnk - 2);
;             const char* a1 = cA + (size_t)(t + 1) * kstep;
;             const char* a2 = last ? nA : cA + (size_t)(t + 2) * kstep; const char* b2 = last ? nB : cB + (size_t)(t + 2) * kstep;
;             const char* a3 = a2 + kstep; const char* b3 = b2 + kstep;
;             if (last && has_next) S.a_ready(nxt);
;             if (last) E.prefetch(pre, cur, wr, fr);
;             PG8_LDB(B0, 0, 0); PG8_SCHED; PG8_LDA(At, 0, 0); PG8_STAGE(PG8_SA(1, 1), a1 + hstep, voffA);
;             PG8_WAIT_L(8); PG8_BAR; PG8_WAIT_L(0); PG8_MMA(0, 0, At, B0); PG8_BAR; PG8_SCHED;
;             PG8_LDB(B1, 0, 1); PG8_STAGE(PG8_SB(0, 0), b2, voffB);
;             PG8_BAR; PG8_WAIT_L(0); PG8_MMA(0, 1, At, B1); PG8_BAR;
;             PG8_LDA(At, 0, 1); PG8_STAGE(PG8_SA(0, 0), a2, voffA);
;             PG8_BAR; PG8_WAIT_L(0); PG8_MMA(1, 0, At, B0); PG8_BAR; PG8_SCHED;
.LBB0_2574:
	ds_read_b128 v[128:131], v192
	ds_read_b128 v[132:135], v192 offset:1024
	ds_read_b128 v[136:139], v192 offset:2048
	ds_read_b128 v[140:143], v192 offset:3072
	s_add_i32 s83, s27, 2
	s_add_u32 s30, s38, 0xfff00080
	s_addc_u32 s40, s39, -1
	s_cmp_eq_u32 s17, s27
	s_cselect_b32 s43, s25, s40
	s_cselect_b32 s42, s24, s30
	s_cselect_b32 s41, s37, s21
	s_cselect_b32 s40, s36, s19
	v_lshl_add_u64 v[190:191], s[38:39], 0, v[168:169]
	s_add_i32 m0, s31, 0xc000
	ds_read_b128 v[144:147], v193
	ds_read_b128 v[148:151], v193 offset:1024
	ds_read_b128 v[174:177], v193 offset:2048
	ds_read_b128 v[178:181], v193 offset:3072
	ds_read_b128 v[182:185], v193 offset:4096
	ds_read_b128 v[186:189], v193 offset:5120
	ds_read_b128 v[196:199], v193 offset:6144
	ds_read_b128 v[200:203], v193 offset:7168
	global_load_lds_dwordx4 v[190:191], off
	s_add_i32 m0, s31, 0xe000
	v_lshl_add_u64 v[190:191], s[38:39], 0, v[170:171]
	global_load_lds_dwordx4 v[190:191], off
	s_waitcnt lgkmcnt(8)
	s_barrier
	s_waitcnt lgkmcnt(0)
	s_setprio 1
	v_mfma_f32_16x16x32_bf16 v[124:127], v[128:131], v[144:147], v[124:127]
	v_mfma_f32_16x16x32_bf16 v[120:123], v[136:139], v[144:147], v[120:123]
	v_mfma_f32_16x16x32_bf16 v[108:111], v[128:131], v[174:177], v[108:111]
	v_mfma_f32_16x16x32_bf16 v[104:107], v[136:139], v[174:177], v[104:107]
	v_mfma_f32_16x16x32_bf16 v[92:95], v[128:131], v[182:185], v[92:95]
	v_mfma_f32_16x16x32_bf16 v[88:91], v[136:139], v[182:185], v[88:91]
	v_mfma_f32_16x16x32_bf16 v[76:79], v[128:131], v[196:199], v[76:79]
	v_mfma_f32_16x16x32_bf16 v[72:75], v[136:139], v[196:199], v[72:75]
	v_mfma_f32_16x16x32_bf16 v[124:127], v[132:135], v[148:151], v[124:127]
	v_mfma_f32_16x16x32_bf16 v[120:123], v[140:143], v[148:151], v[120:123]
	v_mfma_f32_16x16x32_bf16 v[108:111], v[132:135], v[178:181], v[108:111]
	v_mfma_f32_16x16x32_bf16 v[104:107], v[140:143], v[178:181], v[104:107]
	v_mfma_f32_16x16x32_bf16 v[92:95], v[132:135], v[186:189], v[92:95]
	v_mfma_f32_16x16x32_bf16 v[88:91], v[140:143], v[186:189], v[88:91]
	v_mfma_f32_16x16x32_bf16 v[76:79], v[132:135], v[200:203], v[76:79]
	v_mfma_f32_16x16x32_bf16 v[72:75], v[140:143], v[200:203], v[72:75]
	s_setprio 0
	s_barrier
	s_add_i32 s27, s53, s29
	v_lshl_add_u64 v[190:191], s[40:41], 0, v[160:161]
	s_mov_b32 m0, s27
	ds_read_b128 v[204:207], v194
	ds_read_b128 v[208:211], v194 offset:1024
	ds_read_b128 v[212:215], v194 offset:2048
	ds_read_b128 v[216:219], v194 offset:3072
	global_load_lds_dwordx4 v[190:191], off
	s_add_i32 m0, s27, 0x2000
	v_lshl_add_u64 v[220:221], s[40:41], 0, v[164:165]
	global_load_lds_dwordx4 v[220:221], off
	s_barrier
	s_waitcnt lgkmcnt(0)
	s_setprio 1
	v_mfma_f32_16x16x32_bf16 v[116:119], v[204:207], v[144:147], v[116:119]
	v_mfma_f32_16x16x32_bf16 v[112:115], v[212:215], v[144:147], v[112:115]
	v_mfma_f32_16x16x32_bf16 v[100:103], v[204:207], v[174:177], v[100:103]
	v_mfma_f32_16x16x32_bf16 v[96:99], v[212:215], v[174:177], v[96:99]
	v_mfma_f32_16x16x32_bf16 v[84:87], v[204:207], v[182:185], v[84:87]
	v_mfma_f32_16x16x32_bf16 v[80:83], v[212:215], v[182:185], v[80:83]
	v_mfma_f32_16x16x32_bf16 v[68:71], v[204:207], v[196:199], v[68:71]
	v_mfma_f32_16x16x32_bf16 v[64:67], v[212:215], v[196:199], v[64:67]
	v_mfma_f32_16x16x32_bf16 v[116:119], v[208:211], v[148:151], v[116:119]
	v_mfma_f32_16x16x32_bf16 v[112:115], v[216:219], v[148:151], v[112:115]
	v_mfma_f32_16x16x32_bf16 v[100:103], v[208:211], v[178:181], v[100:103]
	v_mfma_f32_16x16x32_bf16 v[96:99], v[216:219], v[178:181], v[96:99]
	v_mfma_f32_16x16x32_bf16 v[84:87], v[208:211], v[186:189], v[84:87]
	v_mfma_f32_16x16x32_bf16 v[80:83], v[216:219], v[186:189], v[80:83]
	v_mfma_f32_16x16x32_bf16 v[68:71], v[208:211], v[200:203], v[68:71]
	v_mfma_f32_16x16x32_bf16 v[64:67], v[216:219], v[200:203], v[64:67]
	s_setprio 0
	s_mov_b32 m0, s31
	v_lshl_add_u64 v[222:223], s[42:43], 0, v[158:159]
	s_barrier
	ds_read_b128 v[144:147], v193 offset:16384
	ds_read_b128 v[148:151], v193 offset:17408
	ds_read_b128 v[174:177], v193 offset:18432
	ds_read_b128 v[178:181], v193 offset:19456
	ds_read_b128 v[182:185], v193 offset:20480
	ds_read_b128 v[186:189], v193 offset:21504
	ds_read_b128 v[196:199], v193 offset:22528
	ds_read_b128 v[200:203], v193 offset:23552
	global_load_lds_dwordx4 v[222:223], off
	s_mov_b32 m0, s33
	v_lshl_add_u64 v[224:225], s[42:43], 0, v[162:163]
	global_load_lds_dwordx4 v[224:225], off
	s_barrier
	s_waitcnt lgkmcnt(0)
	s_setprio 1
	v_mfma_f32_16x16x32_bf16 v[60:63], v[128:131], v[144:147], v[60:63]
	v_mfma_f32_16x16x32_bf16 v[56:59], v[136:139], v[144:147], v[56:59]
	v_mfma_f32_16x16x32_bf16 v[44:47], v[128:131], v[174:177], v[44:47]
	v_mfma_f32_16x16x32_bf16 v[40:43], v[136:139], v[174:177], v[40:43]
	v_mfma_f32_16x16x32_bf16 v[28:31], v[128:131], v[182:185], v[28:31]
	v_mfma_f32_16x16x32_bf16 v[24:27], v[136:139], v[182:185], v[24:27]
	v_mfma_f32_16x16x32_bf16 v[12:15], v[128:131], v[196:199], v[12:15]
	v_mfma_f32_16x16x32_bf16 v[8:11], v[136:139], v[196:199], v[8:11]
	v_mfma_f32_16x16x32_bf16 v[60:63], v[132:135], v[148:151], v[60:63]
	v_mfma_f32_16x16x32_bf16 v[56:59], v[140:143], v[148:151], v[56:59]
	v_mfma_f32_16x16x32_bf16 v[44:47], v[132:135], v[178:181], v[44:47]
	v_mfma_f32_16x16x32_bf16 v[40:43], v[140:143], v[178:181], v[40:43]
	v_mfma_f32_16x16x32_bf16 v[28:31], v[132:135], v[186:189], v[28:31]
	v_mfma_f32_16x16x32_bf16 v[24:27], v[140:143], v[186:189], v[24:27]
	v_mfma_f32_16x16x32_bf16 v[12:15], v[132:135], v[200:203], v[12:15]
	v_mfma_f32_16x16x32_bf16 v[8:11], v[140:143], v[200:203], v[8:11]
	s_setprio 0
	s_barrier
; #define PG8_STAGE(bufoff, gbase, voff) do { _Pragma("unroll") for (int _i = 0; _i < 2; ++_i) \
;         __builtin_amdgcn_global_load_lds((const unsigned*)((const char*)(gbase) + (voff)[_i]), (PG8_LAS unsigned*)(lds + (bufoff) + ldsw + _i * 8192), 16, 0, 0); } while (0)
; #define PG8_LDA(dst, b, h) do { _Pragma("unroll") for (int m = 0; m < 4; ++m) _Pragma("unroll") for (int k = 0; k < 2; ++k) dst[m][k] = *(const PG8_LAS bf16x8*)(lds + PG8_SA(b, h) + aoff + m * 2048 + k * 1024); } while (0)
; #define PG8_LDB(dst, b, h) do { _Pragma("unroll") for (int n = 0; n < 2; ++n) _Pragma("unroll") for (int k = 0; k < 2; ++k) dst[n][k] = *(const PG8_LAS bf16x8*)(lds + PG8_SB(b, h) + boff + n * 2048 + k * 1024); } while (0)
; #define PG8_MMA(ai, bj, At, Bt) do { __builtin_amdgcn_s_setprio(1); _Pragma("unroll") for (int m = 0; m < 4; ++m) _Pragma("unroll") for (int n = 0; n < 2; ++n) _Pragma("unroll") for (int k = 0; k < 2; ++k) \
;         acc[ai][bj][m][n] = __builtin_amdgcn_mfma_f32_16x16x32_bf16(Bt[n][k], At[m][k], acc[ai][bj][m][n], 0, 0, 0); __builtin_amdgcn_s_setprio(0); } while (0)
; #define PG8_WAIT_V(n) asm volatile("s_waitcnt vmcnt(" #n ")" ::: "memory")
; #define PG8_WAIT_L(n) asm volatile("s_waitcnt lgkmcnt(" #n ")" ::: "memory")
; #define PG8_BAR __builtin_amdgcn_s_barrier()
; #define PG8_SCHED __builtin_amdgcn_sched_barrier(0)
; template <class Epi, class Sched>
; __device__ __forceinline__ void gemm_phase(PG8_LAS unsigned char* lds, const Gemm g, const Sched& S, const Epi& E) {
;     ...
;             PG8_STAGE(PG8_SB(0, 1), b2 + hstep, voffB);
;             PG8_WAIT_V(6); PG8_BAR; PG8_MMA(1, 1, At, B1); PG8_BAR;
;             PG8_LDB(B0, 1, 0); PG8_SCHED; PG8_LDA(At, 1, 0); PG8_STAGE(PG8_SA(0, 1), a2 + hstep, voffA);
;             PG8_WAIT_L(8); PG8_BAR; PG8_WAIT_L(0); PG8_MMA(0, 0, At, B0); PG8_BAR; PG8_SCHED;
;             PG8_LDB(B1, 1, 1); PG8_STAGE(PG8_SB(1, 0), b3, voffB);
	s_add_u32 s84, s40, 0x100000
	s_addc_u32 s85, s41, 0
	s_add_i32 s27, s54, s29
	s_mov_b32 m0, s27
	v_lshl_add_u64 v[128:129], s[84:85], 0, v[160:161]
	global_load_lds_dwordx4 v[128:129], off
	s_add_i32 m0, s27, 0x2000
	v_lshl_add_u64 v[128:129], s[84:85], 0, v[164:165]
	global_load_lds_dwordx4 v[128:129], off
	s_waitcnt vmcnt(6)
	s_barrier
	s_setprio 1
	v_mfma_f32_16x16x32_bf16 v[52:55], v[204:207], v[144:147], v[52:55]
	v_mfma_f32_16x16x32_bf16 v[48:51], v[212:215], v[144:147], v[48:51]
	v_mfma_f32_16x16x32_bf16 v[36:39], v[204:207], v[174:177], v[36:39]
	v_mfma_f32_16x16x32_bf16 v[32:35], v[212:215], v[174:177], v[32:35]
	v_mfma_f32_16x16x32_bf16 v[20:23], v[204:207], v[182:185], v[20:23]
	v_mfma_f32_16x16x32_bf16 v[16:19], v[212:215], v[182:185], v[16:19]
	v_mfma_f32_16x16x32_bf16 v[4:7], v[204:207], v[196:199], v[4:7]
	v_mfma_f32_16x16x32_bf16 v[0:3], v[212:215], v[196:199], v[0:3]
	v_mfma_f32_16x16x32_bf16 v[52:55], v[208:211], v[148:151], v[52:55]
	v_mfma_f32_16x16x32_bf16 v[48:51], v[216:219], v[148:151], v[48:51]
	v_mfma_f32_16x16x32_bf16 v[36:39], v[208:211], v[178:181], v[36:39]
	v_mfma_f32_16x16x32_bf16 v[32:35], v[216:219], v[178:181], v[32:35]
	v_mfma_f32_16x16x32_bf16 v[20:23], v[208:211], v[186:189], v[20:23]
	v_mfma_f32_16x16x32_bf16 v[16:19], v[216:219], v[186:189], v[16:19]
	v_mfma_f32_16x16x32_bf16 v[4:7], v[208:211], v[200:203], v[4:7]
	v_mfma_f32_16x16x32_bf16 v[0:3], v[216:219], v[200:203], v[0:3]
	s_setprio 0
	s_add_i32 s27, 0, 0x18000
	v_add_u32_e32 v140, s27, v155
	s_barrier
	ds_read_b128 v[128:131], v140
	ds_read_b128 v[132:135], v140 offset:1024
	ds_read_b128 v[136:139], v140 offset:2048
	ds_read_b128 v[140:143], v140 offset:3072
	s_add_u32 s42, s42, 0x100000
	s_addc_u32 s43, s43, 0
	s_mov_b32 m0, s34
	v_lshl_add_u64 v[204:205], s[42:43], 0, v[158:159]
	ds_read_b128 v[144:147], v193 offset:32768
	ds_read_b128 v[148:151], v193 offset:33792
	ds_read_b128 v[174:177], v193 offset:34816
	ds_read_b128 v[178:181], v193 offset:35840
	ds_read_b128 v[182:185], v193 offset:36864
	ds_read_b128 v[186:189], v193 offset:37888
	ds_read_b128 v[196:199], v193 offset:38912
	ds_read_b128 v[200:203], v193 offset:39936
	global_load_lds_dwordx4 v[204:205], off
	s_mov_b32 m0, s35
	v_lshl_add_u64 v[204:205], s[42:43], 0, v[162:163]
	global_load_lds_dwordx4 v[204:205], off
	s_waitcnt lgkmcnt(8)
	s_barrier
	s_waitcnt lgkmcnt(0)
	s_setprio 1
	v_mfma_f32_16x16x32_bf16 v[124:127], v[128:131], v[144:147], v[124:127]
	v_mfma_f32_16x16x32_bf16 v[120:123], v[136:139], v[144:147], v[120:123]
	v_mfma_f32_16x16x32_bf16 v[108:111], v[128:131], v[174:177], v[108:111]
	v_mfma_f32_16x16x32_bf16 v[104:107], v[136:139], v[174:177], v[104:107]
	v_mfma_f32_16x16x32_bf16 v[92:95], v[128:131], v[182:185], v[92:95]
	v_mfma_f32_16x16x32_bf16 v[88:91], v[136:139], v[182:185], v[88:91]
	v_mfma_f32_16x16x32_bf16 v[76:79], v[128:131], v[196:199], v[76:79]
	v_mfma_f32_16x16x32_bf16 v[72:75], v[136:139], v[196:199], v[72:75]
	v_mfma_f32_16x16x32_bf16 v[124:127], v[132:135], v[148:151], v[124:127]
	v_mfma_f32_16x16x32_bf16 v[120:123], v[140:143], v[148:151], v[120:123]
	v_mfma_f32_16x16x32_bf16 v[108:111], v[132:135], v[178:181], v[108:111]
	v_mfma_f32_16x16x32_bf16 v[104:107], v[140:143], v[178:181], v[104:107]
	v_mfma_f32_16x16x32_bf16 v[92:95], v[132:135], v[186:189], v[92:95]
	v_mfma_f32_16x16x32_bf16 v[88:91], v[140:143], v[186:189], v[88:91]
	v_mfma_f32_16x16x32_bf16 v[76:79], v[132:135], v[200:203], v[76:79]
	v_mfma_f32_16x16x32_bf16 v[72:75], v[140:143], v[200:203], v[72:75]
	s_setprio 0
	s_barrier
	s_add_i32 s30, 0, 0x1c000
	s_add_i32 s27, s27, s29
	v_add_u32_e32 v216, s30, v155
	v_lshl_add_u64 v[190:191], v[190:191], 0, s[10:11]
	s_mov_b32 m0, s27
	ds_read_b128 v[204:207], v216
	ds_read_b128 v[208:211], v216 offset:1024
	ds_read_b128 v[212:215], v216 offset:2048
	ds_read_b128 v[216:219], v216 offset:3072
	global_load_lds_dwordx4 v[190:191], off
	s_add_i32 m0, s27, 0x2000
	v_lshl_add_u64 v[190:191], v[220:221], 0, s[10:11]
	global_load_lds_dwordx4 v[190:191], off
	s_barrier
; #define PG8_STAGE(bufoff, gbase, voff) do { _Pragma("unroll") for (int _i = 0; _i < 2; ++_i) \
;         __builtin_amdgcn_global_load_lds((const unsigned*)((const char*)(gbase) + (voff)[_i]), (PG8_LAS unsigned*)(lds + (bufoff) + ldsw + _i * 8192), 16, 0, 0); } while (0)
; #define PG8_LDA(dst, b, h) do { _Pragma("unroll") for (int m = 0; m < 4; ++m) _Pragma("unroll") for (int k = 0; k < 2; ++k) dst[m][k] = *(const PG8_LAS bf16x8*)(lds + PG8_SA(b, h) + aoff + m * 2048 + k * 1024); } while (0)
; #define PG8_MMA(ai, bj, At, Bt) do { __builtin_amdgcn_s_setprio(1); _Pragma("unroll") for (int m = 0; m < 4; ++m) _Pragma("unroll") for (int n = 0; n < 2; ++n) _Pragma("unroll") for (int k = 0; k < 2; ++k) \
;         acc[ai][bj][m][n] = __builtin_amdgcn_mfma_f32_16x16x32_bf16(Bt[n][k], At[m][k], acc[ai][bj][m][n], 0, 0, 0); __builtin_amdgcn_s_setprio(0); } while (0)
; #define PG8_WAIT_V(n) asm volatile("s_waitcnt vmcnt(" #n ")" ::: "memory")
; #define PG8_WAIT_L(n) asm volatile("s_waitcnt lgkmcnt(" #n ")" ::: "memory")
; #define PG8_BAR __builtin_amdgcn_s_barrier()
; #define PG8_SCHED __builtin_amdgcn_sched_barrier(0)
; template <class Epi, class Sched>
; __device__ __forceinline__ void gemm_phase(PG8_LAS unsigned char* lds, const Gemm g, const Sched& S, const Epi& E) {
;     ...
;         for (int t = 0; t < cnk; t += 2) {
;     ...
;             PG8_BAR; PG8_WAIT_L(0); PG8_MMA(0, 1, At, B1); PG8_BAR;
;             PG8_LDA(At, 1, 1); PG8_STAGE(PG8_SA(1, 0), a3, voffA);
;             PG8_BAR; PG8_WAIT_L(0); PG8_MMA(1, 0, At, B0); PG8_BAR; PG8_SCHED;
;             PG8_STAGE(PG8_SB(1, 1), b3 + hstep, voffB);
;             PG8_WAIT_V(6); PG8_BAR; PG8_MMA(1, 1, At, B1); PG8_BAR;
;         }
	s_waitcnt lgkmcnt(0)
	s_setprio 1
	v_mfma_f32_16x16x32_bf16 v[116:119], v[204:207], v[144:147], v[116:119]
	v_mfma_f32_16x16x32_bf16 v[112:115], v[212:215], v[144:147], v[112:115]
	v_mfma_f32_16x16x32_bf16 v[100:103], v[204:207], v[174:177], v[100:103]
	v_mfma_f32_16x16x32_bf16 v[96:99], v[212:215], v[174:177], v[96:99]
	v_mfma_f32_16x16x32_bf16 v[84:87], v[204:207], v[182:185], v[84:87]
	v_mfma_f32_16x16x32_bf16 v[80:83], v[212:215], v[182:185], v[80:83]
	v_mfma_f32_16x16x32_bf16 v[68:71], v[204:207], v[196:199], v[68:71]
	v_mfma_f32_16x16x32_bf16 v[64:67], v[212:215], v[196:199], v[64:67]
	v_mfma_f32_16x16x32_bf16 v[116:119], v[208:211], v[148:151], v[116:119]
	v_mfma_f32_16x16x32_bf16 v[112:115], v[216:219], v[148:151], v[112:115]
	v_mfma_f32_16x16x32_bf16 v[100:103], v[208:211], v[178:181], v[100:103]
	v_mfma_f32_16x16x32_bf16 v[96:99], v[216:219], v[178:181], v[96:99]
	v_mfma_f32_16x16x32_bf16 v[84:87], v[208:211], v[186:189], v[84:87]
	v_mfma_f32_16x16x32_bf16 v[80:83], v[216:219], v[186:189], v[80:83]
	v_mfma_f32_16x16x32_bf16 v[68:71], v[208:211], v[200:203], v[68:71]
	v_mfma_f32_16x16x32_bf16 v[64:67], v[216:219], v[200:203], v[64:67]
	s_setprio 0
	s_mov_b32 m0, s45
	v_lshl_add_u64 v[190:191], v[222:223], 0, s[10:11]
	s_barrier
	ds_read_b128 v[144:147], v193 offset:49152
	ds_read_b128 v[148:151], v193 offset:50176
	ds_read_b128 v[174:177], v193 offset:51200
	ds_read_b128 v[178:181], v193 offset:52224
	ds_read_b128 v[182:185], v193 offset:53248
	ds_read_b128 v[186:189], v193 offset:54272
	ds_read_b128 v[196:199], v193 offset:55296
	ds_read_b128 v[200:203], v193 offset:56320
	global_load_lds_dwordx4 v[190:191], off
	s_mov_b32 m0, s46
	v_lshl_add_u64 v[190:191], v[224:225], 0, s[10:11]
	global_load_lds_dwordx4 v[190:191], off
	s_barrier
	s_waitcnt lgkmcnt(0)
	s_setprio 1
	v_mfma_f32_16x16x32_bf16 v[60:63], v[128:131], v[144:147], v[60:63]
	v_mfma_f32_16x16x32_bf16 v[56:59], v[136:139], v[144:147], v[56:59]
	v_mfma_f32_16x16x32_bf16 v[44:47], v[128:131], v[174:177], v[44:47]
	v_mfma_f32_16x16x32_bf16 v[40:43], v[136:139], v[174:177], v[40:43]
	v_mfma_f32_16x16x32_bf16 v[28:31], v[128:131], v[182:185], v[28:31]
	v_mfma_f32_16x16x32_bf16 v[24:27], v[136:139], v[182:185], v[24:27]
	v_mfma_f32_16x16x32_bf16 v[12:15], v[128:131], v[196:199], v[12:15]
	v_mfma_f32_16x16x32_bf16 v[8:11], v[136:139], v[196:199], v[8:11]
	v_mfma_f32_16x16x32_bf16 v[60:63], v[132:135], v[148:151], v[60:63]
	v_mfma_f32_16x16x32_bf16 v[56:59], v[140:143], v[148:151], v[56:59]
	v_mfma_f32_16x16x32_bf16 v[44:47], v[132:135], v[178:181], v[44:47]
	v_mfma_f32_16x16x32_bf16 v[40:43], v[140:143], v[178:181], v[40:43]
	v_mfma_f32_16x16x32_bf16 v[28:31], v[132:135], v[186:189], v[28:31]
	v_mfma_f32_16x16x32_bf16 v[24:27], v[140:143], v[186:189], v[24:27]
	v_mfma_f32_16x16x32_bf16 v[12:15], v[132:135], v[200:203], v[12:15]
	v_mfma_f32_16x16x32_bf16 v[8:11], v[140:143], v[200:203], v[8:11]
	s_setprio 0
	s_barrier
	s_add_u32 s40, s40, 0x100080
	s_addc_u32 s41, s41, 0
	s_add_i32 s27, s30, s29
	s_mov_b32 m0, s27
	v_lshl_add_u64 v[128:129], s[40:41], 0, v[160:161]
	global_load_lds_dwordx4 v[128:129], off
	s_add_i32 m0, s27, 0x2000
	v_lshl_add_u64 v[128:129], s[40:41], 0, v[164:165]
	global_load_lds_dwordx4 v[128:129], off
	s_waitcnt vmcnt(6)
	s_barrier
	s_setprio 1
	v_mfma_f32_16x16x32_bf16 v[52:55], v[204:207], v[144:147], v[52:55]
	v_mfma_f32_16x16x32_bf16 v[48:51], v[212:215], v[144:147], v[48:51]
	v_mfma_f32_16x16x32_bf16 v[36:39], v[204:207], v[174:177], v[36:39]
	v_mfma_f32_16x16x32_bf16 v[32:35], v[212:215], v[174:177], v[32:35]
	v_mfma_f32_16x16x32_bf16 v[20:23], v[204:207], v[182:185], v[20:23]
	v_mfma_f32_16x16x32_bf16 v[16:19], v[212:215], v[182:185], v[16:19]
	v_mfma_f32_16x16x32_bf16 v[4:7], v[204:207], v[196:199], v[4:7]
	v_mfma_f32_16x16x32_bf16 v[0:3], v[212:215], v[196:199], v[0:3]
	v_mfma_f32_16x16x32_bf16 v[52:55], v[208:211], v[148:151], v[52:55]
	v_mfma_f32_16x16x32_bf16 v[48:51], v[216:219], v[148:151], v[48:51]
	v_mfma_f32_16x16x32_bf16 v[36:39], v[208:211], v[178:181], v[36:39]
	v_mfma_f32_16x16x32_bf16 v[32:35], v[216:219], v[178:181], v[32:35]
	v_mfma_f32_16x16x32_bf16 v[20:23], v[208:211], v[186:189], v[20:23]
	v_mfma_f32_16x16x32_bf16 v[16:19], v[216:219], v[186:189], v[16:19]
	v_mfma_f32_16x16x32_bf16 v[4:7], v[208:211], v[200:203], v[4:7]
	v_mfma_f32_16x16x32_bf16 v[0:3], v[216:219], v[200:203], v[0:3]
	s_setprio 0
	s_add_u32 s38, s38, 0x100
	s_addc_u32 s39, s39, 0
	s_add_u32 s19, s19, 0x100
	s_addc_u32 s21, s21, 0
	s_cmp_ge_i32 s83, s15
	s_mov_b32 s27, s83
	s_barrier
	s_cbranch_scc0 .LBB0_2574
	s_mov_b32 s84, s68
	s_cmp_gt_i32 s8, -1
	s_mov_b64 s[38:39], -1
	s_cbranch_scc0 .LBB0_2577
